# A/B: deleted the per-phase s_setprio 1/0 flips around MFMA groups in the 8-phase GEMM loops (timing-only)
# speedup vs baseline: 1.0036x; 1.0036x over previous
; #define G8_STA(b, h, kt) G8_STAGE(G8_SA(b, h), Ag, lda, h, kt)
; #define G8_STB(b, h, kt) G8_STAGE(G8_SB(b, h), Bg, ldb, h, kt)
; #define G8_LDA(b, h) do { _Pragma("unroll") for (int m_ = 0; m_ < 2; ++m_) _Pragma("unroll") for (int k_ = 0; k_ < 4; ++k_) \
;     At[m_][k_] = *reinterpret_cast<const LAS bf16x8*>(la + ((b) * 2 + (h)) * 16384 + m_ * 4096 + (((k_ * 2 + hi) ^ swz) << 4)); } while (0)
; #define G8_LDB(dst, b, h) do { _Pragma("unroll") for (int k_ = 0; k_ < 4; ++k_) \
;     dst[k_] = *reinterpret_cast<const LAS bf16x8*>(lb + ((b) * 2 + (h)) * 16384 + (((k_ * 2 + hi) ^ swz) << 4)); } while (0)
; #define G8_MMA(ai, bj, Bx) do { __builtin_amdgcn_s_setprio(1); _Pragma("unroll") for (int k_ = 0; k_ < 4; ++k_) _Pragma("unroll") for (int m_ = 0; m_ < 2; ++m_) \
;     acc[ai][bj][m_] = __builtin_amdgcn_mfma_f32_32x32x16_bf16(At[m_][k_], Bx[k_], acc[ai][bj][m_], 0, 0, 0); __builtin_amdgcn_s_setprio(0); } while (0)
; #define G8_WV(n) asm volatile("s_waitcnt vmcnt(" #n ")" ::: "memory")
; #define G8_WL(n) asm volatile("s_waitcnt lgkmcnt(" #n ")" ::: "memory")
; #define G8_BAR __builtin_amdgcn_s_barrier()
; #define G8_SCHED __builtin_amdgcn_sched_barrier(0)
; template <class Epi>
; __device__ __forceinline__ void gemm8p(const bf16_t* __restrict__ A, int lda, const bf16_t* __restrict__ Bt, int ldb, int K,
;                                        LP lds, const Epi& epi, bool pre = false, const bf16_t* An = nullptr, const bf16_t* Bn = nullptr) {
;     ...
;   for (int t = 0; t < nt - 2; t += 2) {
;     G8_LDB(B0, 0, 0); G8_SCHED; G8_LDA(0, 0); G8_STA(1, 1, t + 1);
;     G8_WL(8); G8_BAR; G8_WL(0); G8_MMA(0, 0, B0); G8_BAR; G8_SCHED;
;     G8_LDB(B1, 0, 1); G8_STB(0, 0, t + 2);
;     G8_BAR; G8_WL(0); G8_MMA(0, 1, B1); G8_BAR; G8_SCHED;
;     G8_LDA(0, 1); G8_STA(0, 0, t + 2);
;     G8_BAR; G8_WL(0); G8_MMA(1, 0, B0); G8_BAR; G8_SCHED;
;     G8_STB(0, 1, t + 2);
;     G8_WV(6); G8_BAR; G8_MMA(1, 1, B1); G8_BAR; G8_SCHED;
.LBB0_220:
	ds_read_b128 v[168:171], v155
	ds_read_b128 v[172:175], v156
	ds_read_b128 v[176:179], v157
	ds_read_b128 v[180:183], v158
	v_lshl_add_u64 v[188:189], v[138:139], 0, v[128:129]
	v_readfirstlane_b32 s2, v166
	v_lshl_add_u64 v[220:221], v[188:189], 0, s[28:29]
	s_mov_b32 m0, s2
	v_readfirstlane_b32 s2, v165
	ds_read_b128 v[184:187], v154
	ds_read_b128 v[192:195], v154 offset:4096
	ds_read_b128 v[196:199], v153
	ds_read_b128 v[200:203], v153 offset:4096
	ds_read_b128 v[204:207], v152
	ds_read_b128 v[208:211], v152 offset:4096
	ds_read_b128 v[212:215], v131
	ds_read_b128 v[216:219], v131 offset:4096
	global_load_lds_dwordx4 v[220:221], off
	v_lshl_add_u64 v[220:221], v[188:189], 0, s[30:31]
	s_mov_b32 m0, s2
	s_nop 0
	global_load_lds_dwordx4 v[220:221], off
	s_waitcnt lgkmcnt(8)
	s_barrier
	s_waitcnt lgkmcnt(0)
	s_waitcnt lgkmcnt(0)
	v_mfma_f32_32x32x16_bf16 v[112:127], v[184:187], v[168:171], v[112:127]
	v_mfma_f32_32x32x16_bf16 v[96:111], v[192:195], v[168:171], v[96:111]
	v_mfma_f32_32x32x16_bf16 v[112:127], v[196:199], v[172:175], v[112:127]
	v_mfma_f32_32x32x16_bf16 v[96:111], v[200:203], v[172:175], v[96:111]
	v_mfma_f32_32x32x16_bf16 v[112:127], v[204:207], v[176:179], v[112:127]
	v_mfma_f32_32x32x16_bf16 v[96:111], v[208:211], v[176:179], v[96:111]
	v_mfma_f32_32x32x16_bf16 v[112:127], v[212:215], v[180:183], v[112:127]
	v_mfma_f32_32x32x16_bf16 v[96:111], v[216:219], v[180:183], v[96:111]
	s_barrier
	v_lshl_add_u64 v[236:237], v[136:137], 0, v[128:129]
	v_readfirstlane_b32 s2, v147
	v_lshl_add_u64 v[238:239], v[236:237], 0, s[36:37]
	s_mov_b32 m0, s2
	v_readfirstlane_b32 s2, v146
	ds_read_b128 v[220:223], v155 offset:16384
	ds_read_b128 v[224:227], v156 offset:16384
	ds_read_b128 v[228:231], v157 offset:16384
	ds_read_b128 v[232:235], v158 offset:16384
	global_load_lds_dwordx4 v[238:239], off
	v_lshl_add_u64 v[238:239], v[236:237], 0, s[38:39]
	s_mov_b32 m0, s2
	s_nop 0
	global_load_lds_dwordx4 v[238:239], off
	s_barrier
	s_waitcnt lgkmcnt(0)
	s_waitcnt lgkmcnt(0)
	v_mfma_f32_32x32x16_bf16 v[80:95], v[184:187], v[220:223], v[80:95]
	v_mfma_f32_32x32x16_bf16 v[64:79], v[192:195], v[220:223], v[64:79]
	v_mfma_f32_32x32x16_bf16 v[80:95], v[196:199], v[224:227], v[80:95]
	v_mfma_f32_32x32x16_bf16 v[64:79], v[200:203], v[224:227], v[64:79]
	v_mfma_f32_32x32x16_bf16 v[80:95], v[204:207], v[228:231], v[80:95]
	v_mfma_f32_32x32x16_bf16 v[64:79], v[208:211], v[228:231], v[64:79]
	v_mfma_f32_32x32x16_bf16 v[80:95], v[212:215], v[232:235], v[80:95]
	v_mfma_f32_32x32x16_bf16 v[64:79], v[216:219], v[232:235], v[64:79]
	s_barrier
	v_readfirstlane_b32 s2, v143
	v_lshl_add_u64 v[238:239], v[188:189], 0, s[40:41]
	s_mov_b32 m0, s2
	v_readfirstlane_b32 s2, v145
	ds_read_b128 v[184:187], v154 offset:16384
	ds_read_b128 v[192:195], v154 offset:20480
	ds_read_b128 v[196:199], v153 offset:16384
	ds_read_b128 v[200:203], v153 offset:20480
	ds_read_b128 v[204:207], v152 offset:16384
	ds_read_b128 v[208:211], v152 offset:20480
	ds_read_b128 v[212:215], v131 offset:16384
	ds_read_b128 v[216:219], v131 offset:20480
	global_load_lds_dwordx4 v[238:239], off
	v_lshl_add_u64 v[238:239], v[188:189], 0, s[42:43]
	s_mov_b32 m0, s2
	s_nop 0
	global_load_lds_dwordx4 v[238:239], off
	s_barrier
	s_waitcnt lgkmcnt(0)
	s_waitcnt lgkmcnt(0)
	v_mfma_f32_32x32x16_bf16 v[48:63], v[184:187], v[168:171], v[48:63]
	v_mfma_f32_32x32x16_bf16 v[32:47], v[192:195], v[168:171], v[32:47]
	v_mfma_f32_32x32x16_bf16 v[48:63], v[196:199], v[172:175], v[48:63]
	v_mfma_f32_32x32x16_bf16 v[32:47], v[200:203], v[172:175], v[32:47]
	v_mfma_f32_32x32x16_bf16 v[48:63], v[204:207], v[176:179], v[48:63]
	v_mfma_f32_32x32x16_bf16 v[32:47], v[208:211], v[176:179], v[32:47]
	v_mfma_f32_32x32x16_bf16 v[48:63], v[212:215], v[180:183], v[48:63]
	v_mfma_f32_32x32x16_bf16 v[32:47], v[216:219], v[180:183], v[32:47]
	s_barrier
	v_readfirstlane_b32 s2, v144
	v_lshl_add_u64 v[168:169], v[236:237], 0, s[44:45]
	s_mov_b32 m0, s2
	v_readfirstlane_b32 s2, v142
	global_load_lds_dwordx4 v[168:169], off
	v_lshl_add_u64 v[168:169], v[236:237], 0, s[46:47]
	s_mov_b32 m0, s2
	s_nop 0
	global_load_lds_dwordx4 v[168:169], off
	s_waitcnt vmcnt(6)
	s_barrier
	v_mfma_f32_32x32x16_bf16 v[16:31], v[184:187], v[220:223], v[16:31]
	v_mfma_f32_32x32x16_bf16 v[0:15], v[192:195], v[220:223], v[0:15]
	v_mfma_f32_32x32x16_bf16 v[16:31], v[196:199], v[224:227], v[16:31]
	v_mfma_f32_32x32x16_bf16 v[0:15], v[200:203], v[224:227], v[0:15]
	v_mfma_f32_32x32x16_bf16 v[16:31], v[204:207], v[228:231], v[16:31]
	v_mfma_f32_32x32x16_bf16 v[0:15], v[208:211], v[228:231], v[0:15]
	v_mfma_f32_32x32x16_bf16 v[16:31], v[212:215], v[232:235], v[16:31]
	v_mfma_f32_32x32x16_bf16 v[0:15], v[216:219], v[232:235], v[0:15]
	s_barrier
	ds_read_b128 v[168:171], v155 offset:32768
	ds_read_b128 v[172:175], v156 offset:32768
	ds_read_b128 v[176:179], v157 offset:32768
	ds_read_b128 v[180:183], v158 offset:32768
	v_readfirstlane_b32 s2, v141
	v_lshl_add_u64 v[220:221], v[188:189], 0, s[48:49]
	s_mov_b32 m0, s2
	v_readfirstlane_b32 s2, v140
	ds_read_b128 v[184:187], v154 offset:32768
	ds_read_b128 v[192:195], v154 offset:36864
	ds_read_b128 v[196:199], v153 offset:32768
	ds_read_b128 v[200:203], v153 offset:36864
	ds_read_b128 v[204:207], v152 offset:32768
	ds_read_b128 v[208:211], v152 offset:36864
	ds_read_b128 v[212:215], v131 offset:32768
	ds_read_b128 v[216:219], v131 offset:36864
	global_load_lds_dwordx4 v[220:221], off
	v_lshl_add_u64 v[220:221], v[188:189], 0, s[50:51]
	s_mov_b32 m0, s2
	s_nop 0
	global_load_lds_dwordx4 v[220:221], off
	s_waitcnt lgkmcnt(8)
	s_barrier
; #define G8_STA(b, h, kt) G8_STAGE(G8_SA(b, h), Ag, lda, h, kt)
; #define G8_STB(b, h, kt) G8_STAGE(G8_SB(b, h), Bg, ldb, h, kt)
; #define G8_LDA(b, h) do { _Pragma("unroll") for (int m_ = 0; m_ < 2; ++m_) _Pragma("unroll") for (int k_ = 0; k_ < 4; ++k_) \
;     At[m_][k_] = *reinterpret_cast<const LAS bf16x8*>(la + ((b) * 2 + (h)) * 16384 + m_ * 4096 + (((k_ * 2 + hi) ^ swz) << 4)); } while (0)
; #define G8_LDB(dst, b, h) do { _Pragma("unroll") for (int k_ = 0; k_ < 4; ++k_) \
;     dst[k_] = *reinterpret_cast<const LAS bf16x8*>(lb + ((b) * 2 + (h)) * 16384 + (((k_ * 2 + hi) ^ swz) << 4)); } while (0)
; #define G8_MMA(ai, bj, Bx) do { __builtin_amdgcn_s_setprio(1); _Pragma("unroll") for (int k_ = 0; k_ < 4; ++k_) _Pragma("unroll") for (int m_ = 0; m_ < 2; ++m_) \
;     acc[ai][bj][m_] = __builtin_amdgcn_mfma_f32_32x32x16_bf16(At[m_][k_], Bx[k_], acc[ai][bj][m_], 0, 0, 0); __builtin_amdgcn_s_setprio(0); } while (0)
; #define G8_WV(n) asm volatile("s_waitcnt vmcnt(" #n ")" ::: "memory")
; #define G8_WL(n) asm volatile("s_waitcnt lgkmcnt(" #n ")" ::: "memory")
; #define G8_BAR __builtin_amdgcn_s_barrier()
; #define G8_SCHED __builtin_amdgcn_sched_barrier(0)
; template <class Epi>
; __device__ __forceinline__ void gemm8p(const bf16_t* __restrict__ A, int lda, const bf16_t* __restrict__ Bt, int ldb, int K,
;                                        LP lds, const Epi& epi, bool pre = false, const bf16_t* An = nullptr, const bf16_t* Bn = nullptr) {
;     ...
;     G8_LDB(B0, 1, 0); G8_SCHED; G8_LDA(1, 0); G8_STA(0, 1, t + 2);
;     G8_WL(8); G8_BAR; G8_WL(0); G8_MMA(0, 0, B0); G8_BAR; G8_SCHED;
;     G8_LDB(B1, 1, 1); G8_STB(1, 0, t + 3);
;     G8_BAR; G8_WL(0); G8_MMA(0, 1, B1); G8_BAR; G8_SCHED;
;     G8_LDA(1, 1); G8_STA(1, 0, t + 3);
;     G8_BAR; G8_WL(0); G8_MMA(1, 0, B0); G8_BAR; G8_SCHED;
;     G8_STB(1, 1, t + 3);
;     G8_WV(6); G8_BAR; G8_MMA(1, 1, B1); G8_BAR; G8_SCHED;
;   }
;   { G8_LDB(B0, 0, 0); G8_LDA(0, 0); G8_STA(1, 1, nt - 1);
;     G8_BAR; G8_WL(0); G8_MMA(0, 0, B0); G8_BAR; G8_SCHED;
	s_waitcnt lgkmcnt(0)
	s_waitcnt lgkmcnt(0)
	v_mfma_f32_32x32x16_bf16 v[112:127], v[184:187], v[168:171], v[112:127]
	v_mfma_f32_32x32x16_bf16 v[96:111], v[192:195], v[168:171], v[96:111]
	v_mfma_f32_32x32x16_bf16 v[112:127], v[196:199], v[172:175], v[112:127]
	v_mfma_f32_32x32x16_bf16 v[96:111], v[200:203], v[172:175], v[96:111]
	v_mfma_f32_32x32x16_bf16 v[112:127], v[204:207], v[176:179], v[112:127]
	v_mfma_f32_32x32x16_bf16 v[96:111], v[208:211], v[176:179], v[96:111]
	v_mfma_f32_32x32x16_bf16 v[112:127], v[212:215], v[180:183], v[112:127]
	v_mfma_f32_32x32x16_bf16 v[96:111], v[216:219], v[180:183], v[96:111]
	s_barrier
	v_readfirstlane_b32 s2, v159
	v_lshl_add_u64 v[238:239], v[236:237], 0, s[52:53]
	s_mov_b32 m0, s2
	v_readfirstlane_b32 s2, v160
	ds_read_b128 v[220:223], v155 offset:49152
	ds_read_b128 v[224:227], v156 offset:49152
	ds_read_b128 v[228:231], v157 offset:49152
	ds_read_b128 v[232:235], v158 offset:49152
	global_load_lds_dwordx4 v[238:239], off
	v_lshl_add_u64 v[238:239], v[236:237], 0, s[54:55]
	s_mov_b32 m0, s2
	s_nop 0
	global_load_lds_dwordx4 v[238:239], off
	s_barrier
	s_waitcnt lgkmcnt(0)
	s_waitcnt lgkmcnt(0)
	v_mfma_f32_32x32x16_bf16 v[80:95], v[184:187], v[220:223], v[80:95]
	v_mfma_f32_32x32x16_bf16 v[64:79], v[192:195], v[220:223], v[64:79]
	v_mfma_f32_32x32x16_bf16 v[80:95], v[196:199], v[224:227], v[80:95]
	v_mfma_f32_32x32x16_bf16 v[64:79], v[200:203], v[224:227], v[64:79]
	v_mfma_f32_32x32x16_bf16 v[80:95], v[204:207], v[228:231], v[80:95]
	v_mfma_f32_32x32x16_bf16 v[64:79], v[208:211], v[228:231], v[64:79]
	v_mfma_f32_32x32x16_bf16 v[80:95], v[212:215], v[232:235], v[80:95]
	v_mfma_f32_32x32x16_bf16 v[64:79], v[216:219], v[232:235], v[64:79]
	s_barrier
	v_readfirstlane_b32 s2, v161
	v_lshl_add_u64 v[238:239], v[188:189], 0, s[56:57]
	s_mov_b32 m0, s2
	v_readfirstlane_b32 s2, v162
	ds_read_b128 v[184:187], v154 offset:49152
	ds_read_b128 v[192:195], v154 offset:53248
	ds_read_b128 v[196:199], v153 offset:49152
	ds_read_b128 v[200:203], v153 offset:53248
	ds_read_b128 v[204:207], v152 offset:49152
	ds_read_b128 v[208:211], v152 offset:53248
	ds_read_b128 v[212:215], v131 offset:49152
	ds_read_b128 v[216:219], v131 offset:53248
	global_load_lds_dwordx4 v[238:239], off
	v_lshl_add_u64 v[188:189], v[188:189], 0, s[58:59]
	s_mov_b32 m0, s2
	s_nop 0
	global_load_lds_dwordx4 v[188:189], off
	s_barrier
	s_waitcnt lgkmcnt(0)
	s_waitcnt lgkmcnt(0)
	v_mfma_f32_32x32x16_bf16 v[48:63], v[184:187], v[168:171], v[48:63]
	v_mfma_f32_32x32x16_bf16 v[32:47], v[192:195], v[168:171], v[32:47]
	v_mfma_f32_32x32x16_bf16 v[48:63], v[196:199], v[172:175], v[48:63]
	v_mfma_f32_32x32x16_bf16 v[32:47], v[200:203], v[172:175], v[32:47]
	v_mfma_f32_32x32x16_bf16 v[48:63], v[204:207], v[176:179], v[48:63]
	v_mfma_f32_32x32x16_bf16 v[32:47], v[208:211], v[176:179], v[32:47]
	v_mfma_f32_32x32x16_bf16 v[48:63], v[212:215], v[180:183], v[48:63]
	v_mfma_f32_32x32x16_bf16 v[32:47], v[216:219], v[180:183], v[32:47]
	s_barrier
	v_readfirstlane_b32 s2, v163
	v_lshl_add_u64 v[168:169], v[236:237], 0, s[60:61]
	s_mov_b32 m0, s2
	v_readfirstlane_b32 s2, v164
	global_load_lds_dwordx4 v[168:169], off
	v_lshl_add_u64 v[168:169], v[236:237], 0, s[62:63]
	s_mov_b32 m0, s2
	s_nop 0
	global_load_lds_dwordx4 v[168:169], off
	s_waitcnt vmcnt(6)
	s_barrier
	v_mfma_f32_32x32x16_bf16 v[16:31], v[184:187], v[220:223], v[16:31]
	v_mfma_f32_32x32x16_bf16 v[0:15], v[192:195], v[220:223], v[0:15]
	v_mfma_f32_32x32x16_bf16 v[16:31], v[196:199], v[224:227], v[16:31]
	v_mfma_f32_32x32x16_bf16 v[0:15], v[200:203], v[224:227], v[0:15]
	v_mfma_f32_32x32x16_bf16 v[16:31], v[204:207], v[228:231], v[16:31]
	v_mfma_f32_32x32x16_bf16 v[0:15], v[208:211], v[228:231], v[0:15]
	v_mfma_f32_32x32x16_bf16 v[16:31], v[212:215], v[232:235], v[16:31]
	v_mfma_f32_32x32x16_bf16 v[0:15], v[216:219], v[232:235], v[0:15]
	s_barrier
	s_add_i32 s1, s1, 2
	v_lshl_add_u64 v[138:139], v[138:139], 0, s[36:37]
	s_cmp_lt_u32 s1, 12
	v_lshl_add_u64 v[136:137], v[136:137], 0, s[36:37]
	s_cbranch_scc1 .LBB0_220
	v_readfirstlane_b32 s1, v166
	v_lshl_add_u64 v[188:189], v[134:135], 0, s[64:65]
	s_mov_b32 m0, s1
	v_readfirstlane_b32 s1, v165
	ds_read_b128 v[136:139], v155
	ds_read_b128 v[160:163], v156
	ds_read_b128 v[168:171], v157
	ds_read_b128 v[172:175], v158
	ds_read_b128 v[176:179], v154
	ds_read_b128 v[180:183], v154 offset:4096
	ds_read_b128 v[184:187], v153
	ds_read_b128 v[192:195], v153 offset:4096
	ds_read_b128 v[196:199], v152
	ds_read_b128 v[200:203], v152 offset:4096
	ds_read_b128 v[204:207], v131
	ds_read_b128 v[208:211], v131 offset:4096
	global_load_lds_dwordx4 v[188:189], off
	v_lshl_add_u64 v[134:135], v[134:135], 0, s[66:67]
	s_mov_b32 m0, s1
	s_nop 0
	global_load_lds_dwordx4 v[134:135], off
	s_barrier
	s_waitcnt lgkmcnt(0)
	s_waitcnt lgkmcnt(0)
	v_mfma_f32_32x32x16_bf16 v[112:127], v[176:179], v[136:139], v[112:127]
	v_mfma_f32_32x32x16_bf16 v[96:111], v[180:183], v[136:139], v[96:111]
	v_mfma_f32_32x32x16_bf16 v[112:127], v[184:187], v[160:163], v[112:127]
	v_mfma_f32_32x32x16_bf16 v[96:111], v[192:195], v[160:163], v[96:111]
	v_mfma_f32_32x32x16_bf16 v[112:127], v[196:199], v[168:171], v[112:127]
	v_mfma_f32_32x32x16_bf16 v[96:111], v[200:203], v[168:171], v[96:111]
	v_mfma_f32_32x32x16_bf16 v[112:127], v[204:207], v[172:175], v[112:127]
	v_mfma_f32_32x32x16_bf16 v[96:111], v[208:211], v[172:175], v[96:111]
	s_barrier
	ds_read_b128 v[164:167], v155 offset:16384
	ds_read_b128 v[212:215], v156 offset:16384
	ds_read_b128 v[216:219], v157 offset:16384
	ds_read_b128 v[220:223], v158 offset:16384
	s_barrier
; #define G8_LDA(b, h) do { _Pragma("unroll") for (int m_ = 0; m_ < 2; ++m_) _Pragma("unroll") for (int k_ = 0; k_ < 4; ++k_) \
;     At[m_][k_] = *reinterpret_cast<const LAS bf16x8*>(la + ((b) * 2 + (h)) * 16384 + m_ * 4096 + (((k_ * 2 + hi) ^ swz) << 4)); } while (0)
; #define G8_LDB(dst, b, h) do { _Pragma("unroll") for (int k_ = 0; k_ < 4; ++k_) \
;     dst[k_] = *reinterpret_cast<const LAS bf16x8*>(lb + ((b) * 2 + (h)) * 16384 + (((k_ * 2 + hi) ^ swz) << 4)); } while (0)
; #define G8_MMA(ai, bj, Bx) do { __builtin_amdgcn_s_setprio(1); _Pragma("unroll") for (int k_ = 0; k_ < 4; ++k_) _Pragma("unroll") for (int m_ = 0; m_ < 2; ++m_) \
;     acc[ai][bj][m_] = __builtin_amdgcn_mfma_f32_32x32x16_bf16(At[m_][k_], Bx[k_], acc[ai][bj][m_], 0, 0, 0); __builtin_amdgcn_s_setprio(0); } while (0)
; #define G8_WV(n) asm volatile("s_waitcnt vmcnt(" #n ")" ::: "memory")
; #define G8_WL(n) asm volatile("s_waitcnt lgkmcnt(" #n ")" ::: "memory")
; #define G8_BAR __builtin_amdgcn_s_barrier()
; #define G8_SCHED __builtin_amdgcn_sched_barrier(0)
; template <class Epi>
; __device__ __forceinline__ void gemm8p(const bf16_t* __restrict__ A, int lda, const bf16_t* __restrict__ Bt, int ldb, int K,
;                                        LP lds, const Epi& epi, bool pre = false, const bf16_t* An = nullptr, const bf16_t* Bn = nullptr) {
;     ...
;     G8_BAR; G8_WL(0); G8_MMA(0, 0, B0); G8_BAR; G8_SCHED;
;     G8_LDB(B1, 0, 1); G8_BAR; G8_WL(0); G8_MMA(0, 1, B1); G8_BAR; G8_SCHED;
;     G8_LDA(0, 1); G8_WV(4); G8_BAR; G8_WL(0); G8_MMA(1, 0, B0); G8_MMA(1, 1, B1); G8_BAR; G8_SCHED; }
;   { G8_LDB(B0, 1, 0); G8_LDA(1, 0); G8_WV(2); G8_BAR; G8_WL(0); G8_MMA(0, 0, B0); G8_BAR; G8_SCHED;
;     G8_LDB(B1, 1, 1); G8_WV(0); G8_BAR; G8_WL(0); G8_MMA(0, 1, B1); G8_BAR; G8_SCHED;
;     G8_LDA(1, 1); G8_BAR; G8_WL(0); G8_MMA(1, 0, B0); G8_MMA(1, 1, B1); G8_BAR; G8_SCHED; }
;   if (wr == 0) G8_BAR;
	s_waitcnt lgkmcnt(0)
	s_waitcnt lgkmcnt(0)
	v_mfma_f32_32x32x16_bf16 v[80:95], v[176:179], v[164:167], v[80:95]
	v_mfma_f32_32x32x16_bf16 v[64:79], v[180:183], v[164:167], v[64:79]
	v_mfma_f32_32x32x16_bf16 v[80:95], v[184:187], v[212:215], v[80:95]
	v_mfma_f32_32x32x16_bf16 v[64:79], v[192:195], v[212:215], v[64:79]
	v_mfma_f32_32x32x16_bf16 v[80:95], v[196:199], v[216:219], v[80:95]
	v_mfma_f32_32x32x16_bf16 v[64:79], v[200:203], v[216:219], v[64:79]
	v_mfma_f32_32x32x16_bf16 v[80:95], v[204:207], v[220:223], v[80:95]
	v_mfma_f32_32x32x16_bf16 v[64:79], v[208:211], v[220:223], v[64:79]
	s_barrier
	ds_read_b128 v[176:179], v154 offset:16384
	ds_read_b128 v[180:183], v154 offset:20480
	ds_read_b128 v[184:187], v153 offset:16384
	ds_read_b128 v[192:195], v153 offset:20480
	ds_read_b128 v[196:199], v152 offset:16384
	ds_read_b128 v[200:203], v152 offset:20480
	ds_read_b128 v[204:207], v131 offset:16384
	ds_read_b128 v[208:211], v131 offset:20480
	s_waitcnt vmcnt(4)
	s_barrier
	s_waitcnt lgkmcnt(0)
	s_waitcnt lgkmcnt(0)
	v_mfma_f32_32x32x16_bf16 v[48:63], v[176:179], v[136:139], v[48:63]
	v_mfma_f32_32x32x16_bf16 v[32:47], v[180:183], v[136:139], v[32:47]
	v_mfma_f32_32x32x16_bf16 v[48:63], v[184:187], v[160:163], v[48:63]
	v_mfma_f32_32x32x16_bf16 v[32:47], v[192:195], v[160:163], v[32:47]
	v_mfma_f32_32x32x16_bf16 v[48:63], v[196:199], v[168:171], v[48:63]
	v_mfma_f32_32x32x16_bf16 v[32:47], v[200:203], v[168:171], v[32:47]
	v_mfma_f32_32x32x16_bf16 v[48:63], v[204:207], v[172:175], v[48:63]
	v_mfma_f32_32x32x16_bf16 v[32:47], v[208:211], v[172:175], v[32:47]
	v_mfma_f32_32x32x16_bf16 v[16:31], v[176:179], v[164:167], v[16:31]
	v_mfma_f32_32x32x16_bf16 v[0:15], v[180:183], v[164:167], v[0:15]
	v_mfma_f32_32x32x16_bf16 v[16:31], v[184:187], v[212:215], v[16:31]
	v_mfma_f32_32x32x16_bf16 v[0:15], v[192:195], v[212:215], v[0:15]
	v_mfma_f32_32x32x16_bf16 v[16:31], v[196:199], v[216:219], v[16:31]
	v_mfma_f32_32x32x16_bf16 v[0:15], v[200:203], v[216:219], v[0:15]
	v_mfma_f32_32x32x16_bf16 v[16:31], v[204:207], v[220:223], v[16:31]
	v_mfma_f32_32x32x16_bf16 v[0:15], v[208:211], v[220:223], v[0:15]
	s_barrier
	ds_read_b128 v[134:137], v155 offset:32768
	ds_read_b128 v[160:163], v156 offset:32768
	ds_read_b128 v[164:167], v157 offset:32768
	ds_read_b128 v[168:171], v158 offset:32768
	ds_read_b128 v[172:175], v154 offset:32768
	ds_read_b128 v[176:179], v154 offset:36864
	ds_read_b128 v[180:183], v153 offset:32768
	ds_read_b128 v[184:187], v153 offset:36864
	ds_read_b128 v[192:195], v152 offset:32768
	ds_read_b128 v[196:199], v152 offset:36864
	ds_read_b128 v[200:203], v131 offset:32768
	ds_read_b128 v[204:207], v131 offset:36864
	s_waitcnt vmcnt(2)
	s_barrier
	s_waitcnt lgkmcnt(0)
	s_waitcnt lgkmcnt(0)
	v_mfma_f32_32x32x16_bf16 v[112:127], v[172:175], v[134:137], v[112:127]
	v_mfma_f32_32x32x16_bf16 v[96:111], v[176:179], v[134:137], v[96:111]
	v_mfma_f32_32x32x16_bf16 v[112:127], v[180:183], v[160:163], v[112:127]
	v_mfma_f32_32x32x16_bf16 v[96:111], v[184:187], v[160:163], v[96:111]
	v_mfma_f32_32x32x16_bf16 v[112:127], v[192:195], v[164:167], v[112:127]
	v_mfma_f32_32x32x16_bf16 v[96:111], v[196:199], v[164:167], v[96:111]
	v_mfma_f32_32x32x16_bf16 v[112:127], v[200:203], v[168:171], v[112:127]
	v_mfma_f32_32x32x16_bf16 v[96:111], v[204:207], v[168:171], v[96:111]
	s_barrier
	ds_read_b128 v[208:211], v155 offset:49152
	ds_read_b128 v[212:215], v156 offset:49152
	ds_read_b128 v[216:219], v157 offset:49152
	ds_read_b128 v[156:159], v158 offset:49152
	s_waitcnt vmcnt(0)
	s_barrier
	s_waitcnt lgkmcnt(0)
	s_waitcnt lgkmcnt(0)
	v_mfma_f32_32x32x16_bf16 v[80:95], v[172:175], v[208:211], v[80:95]
	v_mfma_f32_32x32x16_bf16 v[64:79], v[176:179], v[208:211], v[64:79]
	v_mfma_f32_32x32x16_bf16 v[80:95], v[180:183], v[212:215], v[80:95]
	v_mfma_f32_32x32x16_bf16 v[64:79], v[184:187], v[212:215], v[64:79]
	v_mfma_f32_32x32x16_bf16 v[80:95], v[192:195], v[216:219], v[80:95]
	v_mfma_f32_32x32x16_bf16 v[64:79], v[196:199], v[216:219], v[64:79]
	v_mfma_f32_32x32x16_bf16 v[80:95], v[200:203], v[156:159], v[80:95]
	v_mfma_f32_32x32x16_bf16 v[64:79], v[204:207], v[156:159], v[64:79]
	s_barrier
	ds_read_b128 v[172:175], v154 offset:49152
	ds_read_b128 v[176:179], v154 offset:53248
	ds_read_b128 v[180:183], v153 offset:49152
	ds_read_b128 v[184:187], v153 offset:53248
	ds_read_b128 v[192:195], v152 offset:49152
	ds_read_b128 v[152:155], v152 offset:53248
	ds_read_b128 v[196:199], v131 offset:49152
	ds_read_b128 v[200:203], v131 offset:53248
	s_barrier
	s_waitcnt lgkmcnt(0)
	s_waitcnt lgkmcnt(0)
	v_mfma_f32_32x32x16_bf16 v[48:63], v[172:175], v[134:137], v[48:63]
	v_mfma_f32_32x32x16_bf16 v[32:47], v[176:179], v[134:137], v[32:47]
	v_mfma_f32_32x32x16_bf16 v[48:63], v[180:183], v[160:163], v[48:63]
	v_mfma_f32_32x32x16_bf16 v[32:47], v[184:187], v[160:163], v[32:47]
	v_mfma_f32_32x32x16_bf16 v[48:63], v[192:195], v[164:167], v[48:63]
	v_mfma_f32_32x32x16_bf16 v[32:47], v[152:155], v[164:167], v[32:47]
	v_mfma_f32_32x32x16_bf16 v[48:63], v[196:199], v[168:171], v[48:63]
	v_mfma_f32_32x32x16_bf16 v[32:47], v[200:203], v[168:171], v[32:47]
	v_mfma_f32_32x32x16_bf16 v[16:31], v[172:175], v[208:211], v[16:31]
	v_mfma_f32_32x32x16_bf16 v[0:15], v[176:179], v[208:211], v[0:15]
	v_mfma_f32_32x32x16_bf16 v[16:31], v[180:183], v[212:215], v[16:31]
	v_mfma_f32_32x32x16_bf16 v[0:15], v[184:187], v[212:215], v[0:15]
	v_mfma_f32_32x32x16_bf16 v[16:31], v[192:195], v[216:219], v[16:31]
	v_mfma_f32_32x32x16_bf16 v[0:15], v[152:155], v[216:219], v[0:15]
	v_mfma_f32_32x32x16_bf16 v[16:31], v[196:199], v[156:159], v[16:31]
	v_mfma_f32_32x32x16_bf16 v[0:15], v[200:203], v[156:159], v[0:15]
	s_barrier
	v_cmp_gt_u32_e32 vcc, s77, v148
	s_and_saveexec_b64 s[2:3], vcc
	s_cbranch_execz .LBB0_223
	s_barrier

; #define G8_STA(b, h, kt) G8_STAGE(G8_SA(b, h), Ag, lda, h, kt)
; #define G8_STB(b, h, kt) G8_STAGE(G8_SB(b, h), Bg, ldb, h, kt)
; #define G8_LDA(b, h) do { _Pragma("unroll") for (int m_ = 0; m_ < 2; ++m_) _Pragma("unroll") for (int k_ = 0; k_ < 4; ++k_) \
;     At[m_][k_] = *reinterpret_cast<const LAS bf16x8*>(la + ((b) * 2 + (h)) * 16384 + m_ * 4096 + (((k_ * 2 + hi) ^ swz) << 4)); } while (0)
; #define G8_LDB(dst, b, h) do { _Pragma("unroll") for (int k_ = 0; k_ < 4; ++k_) \
;     dst[k_] = *reinterpret_cast<const LAS bf16x8*>(lb + ((b) * 2 + (h)) * 16384 + (((k_ * 2 + hi) ^ swz) << 4)); } while (0)
; #define G8_MMA(ai, bj, Bx) do { __builtin_amdgcn_s_setprio(1); _Pragma("unroll") for (int k_ = 0; k_ < 4; ++k_) _Pragma("unroll") for (int m_ = 0; m_ < 2; ++m_) \
;     acc[ai][bj][m_] = __builtin_amdgcn_mfma_f32_32x32x16_bf16(At[m_][k_], Bx[k_], acc[ai][bj][m_], 0, 0, 0); __builtin_amdgcn_s_setprio(0); } while (0)
; #define G8_WV(n) asm volatile("s_waitcnt vmcnt(" #n ")" ::: "memory")
; #define G8_WL(n) asm volatile("s_waitcnt lgkmcnt(" #n ")" ::: "memory")
; #define G8_BAR __builtin_amdgcn_s_barrier()
; #define G8_SCHED __builtin_amdgcn_sched_barrier(0)
; template <class Epi>
; __device__ __forceinline__ void gemm8p(const bf16_t* __restrict__ A, int lda, const bf16_t* __restrict__ Bt, int ldb, int K,
;                                        LP lds, const Epi& epi, bool pre = false, const bf16_t* An = nullptr, const bf16_t* Bn = nullptr) {
;     ...
;   for (int t = 0; t < nt - 2; t += 2) {
;     G8_LDB(B0, 0, 0); G8_SCHED; G8_LDA(0, 0); G8_STA(1, 1, t + 1);
;     G8_WL(8); G8_BAR; G8_WL(0); G8_MMA(0, 0, B0); G8_BAR; G8_SCHED;
;     G8_LDB(B1, 0, 1); G8_STB(0, 0, t + 2);
;     G8_BAR; G8_WL(0); G8_MMA(0, 1, B1); G8_BAR; G8_SCHED;
;     G8_LDA(0, 1); G8_STA(0, 0, t + 2);
;     G8_BAR; G8_WL(0); G8_MMA(1, 0, B0); G8_BAR; G8_SCHED;
;     G8_STB(0, 1, t + 2);
;     G8_WV(6); G8_BAR; G8_MMA(1, 1, B1); G8_BAR; G8_SCHED;
.LBB0_1623:
	ds_read_b128 v[168:171], v155
	ds_read_b128 v[172:175], v156
	ds_read_b128 v[176:179], v157
	ds_read_b128 v[180:183], v158
	v_lshl_add_u64 v[188:189], v[138:139], 0, v[128:129]
	s_mov_b64 s[66:67], 0x3ab6080
	v_readfirstlane_b32 s63, v166
	v_lshl_add_u64 v[220:221], v[188:189], 0, s[66:67]
	s_mov_b32 m0, s63
	s_mov_b64 s[66:67], 0x3ad6080
	v_readfirstlane_b32 s63, v165
	ds_read_b128 v[184:187], v154
	ds_read_b128 v[192:195], v154 offset:4096
	ds_read_b128 v[196:199], v153
	ds_read_b128 v[200:203], v153 offset:4096
	ds_read_b128 v[204:207], v152
	ds_read_b128 v[208:211], v152 offset:4096
	ds_read_b128 v[212:215], v131
	ds_read_b128 v[216:219], v131 offset:4096
	global_load_lds_dwordx4 v[220:221], off
	v_lshl_add_u64 v[220:221], v[188:189], 0, s[66:67]
	s_mov_b32 m0, s63
	s_nop 0
	global_load_lds_dwordx4 v[220:221], off
	s_waitcnt lgkmcnt(8)
	s_barrier
	s_waitcnt lgkmcnt(0)
	s_waitcnt lgkmcnt(0)
	v_mfma_f32_32x32x16_bf16 v[112:127], v[184:187], v[168:171], v[112:127]
	v_mfma_f32_32x32x16_bf16 v[96:111], v[192:195], v[168:171], v[96:111]
	v_mfma_f32_32x32x16_bf16 v[112:127], v[196:199], v[172:175], v[112:127]
	v_mfma_f32_32x32x16_bf16 v[96:111], v[200:203], v[172:175], v[96:111]
	v_mfma_f32_32x32x16_bf16 v[112:127], v[204:207], v[176:179], v[112:127]
	v_mfma_f32_32x32x16_bf16 v[96:111], v[208:211], v[176:179], v[96:111]
	v_mfma_f32_32x32x16_bf16 v[112:127], v[212:215], v[180:183], v[112:127]
	v_mfma_f32_32x32x16_bf16 v[96:111], v[216:219], v[180:183], v[96:111]
	s_barrier
	v_lshl_add_u64 v[236:237], v[136:137], 0, v[128:129]
	s_mov_b64 s[66:67], 0x5a0100
	v_readfirstlane_b32 s63, v147
	v_lshl_add_u64 v[238:239], v[236:237], 0, s[66:67]
	s_mov_b32 m0, s63
	v_readfirstlane_b32 s63, v146
	ds_read_b128 v[220:223], v155 offset:16384
	ds_read_b128 v[224:227], v156 offset:16384
	ds_read_b128 v[228:231], v157 offset:16384
	ds_read_b128 v[232:235], v158 offset:16384
	global_load_lds_dwordx4 v[238:239], off
	v_lshl_add_u64 v[238:239], v[236:237], 0, s[20:21]
	s_mov_b32 m0, s63
	s_nop 0
	global_load_lds_dwordx4 v[238:239], off
	s_barrier
	s_waitcnt lgkmcnt(0)
	s_waitcnt lgkmcnt(0)
	v_mfma_f32_32x32x16_bf16 v[80:95], v[184:187], v[220:223], v[80:95]
	v_mfma_f32_32x32x16_bf16 v[64:79], v[192:195], v[220:223], v[64:79]
	v_mfma_f32_32x32x16_bf16 v[80:95], v[196:199], v[224:227], v[80:95]
	v_mfma_f32_32x32x16_bf16 v[64:79], v[200:203], v[224:227], v[64:79]
	v_mfma_f32_32x32x16_bf16 v[80:95], v[204:207], v[228:231], v[80:95]
	v_mfma_f32_32x32x16_bf16 v[64:79], v[208:211], v[228:231], v[64:79]
	v_mfma_f32_32x32x16_bf16 v[80:95], v[212:215], v[232:235], v[80:95]
	v_mfma_f32_32x32x16_bf16 v[64:79], v[216:219], v[232:235], v[64:79]
	s_barrier
	v_readfirstlane_b32 s63, v142
	v_lshl_add_u64 v[238:239], v[188:189], 0, s[22:23]
	s_mov_b32 m0, s63
	v_readfirstlane_b32 s63, v145
	ds_read_b128 v[184:187], v154 offset:16384
	ds_read_b128 v[192:195], v154 offset:20480
	ds_read_b128 v[196:199], v153 offset:16384
	ds_read_b128 v[200:203], v153 offset:20480
	ds_read_b128 v[204:207], v152 offset:16384
	ds_read_b128 v[208:211], v152 offset:20480
	ds_read_b128 v[212:215], v131 offset:16384
	ds_read_b128 v[216:219], v131 offset:20480
	global_load_lds_dwordx4 v[238:239], off
	v_lshl_add_u64 v[238:239], v[188:189], 0, s[24:25]
	s_mov_b32 m0, s63
	s_nop 0
	global_load_lds_dwordx4 v[238:239], off
	s_barrier
	s_waitcnt lgkmcnt(0)
	s_waitcnt lgkmcnt(0)
	v_mfma_f32_32x32x16_bf16 v[48:63], v[184:187], v[168:171], v[48:63]
	v_mfma_f32_32x32x16_bf16 v[32:47], v[192:195], v[168:171], v[32:47]
	v_mfma_f32_32x32x16_bf16 v[48:63], v[196:199], v[172:175], v[48:63]
	v_mfma_f32_32x32x16_bf16 v[32:47], v[200:203], v[172:175], v[32:47]
	v_mfma_f32_32x32x16_bf16 v[48:63], v[204:207], v[176:179], v[48:63]
	v_mfma_f32_32x32x16_bf16 v[32:47], v[208:211], v[176:179], v[32:47]
	v_mfma_f32_32x32x16_bf16 v[48:63], v[212:215], v[180:183], v[48:63]
	v_mfma_f32_32x32x16_bf16 v[32:47], v[216:219], v[180:183], v[32:47]
	s_barrier
	v_readfirstlane_b32 s63, v144
	v_lshl_add_u64 v[168:169], v[236:237], 0, s[26:27]
	s_mov_b32 m0, s63
	v_readfirstlane_b32 s63, v143
	global_load_lds_dwordx4 v[168:169], off
	v_lshl_add_u64 v[168:169], v[236:237], 0, s[28:29]
	s_mov_b32 m0, s63
	s_nop 0
	global_load_lds_dwordx4 v[168:169], off
	s_waitcnt vmcnt(6)
	s_barrier
	v_mfma_f32_32x32x16_bf16 v[16:31], v[184:187], v[220:223], v[16:31]
	v_mfma_f32_32x32x16_bf16 v[0:15], v[192:195], v[220:223], v[0:15]
	v_mfma_f32_32x32x16_bf16 v[16:31], v[196:199], v[224:227], v[16:31]
	v_mfma_f32_32x32x16_bf16 v[0:15], v[200:203], v[224:227], v[0:15]
	v_mfma_f32_32x32x16_bf16 v[16:31], v[204:207], v[228:231], v[16:31]
	v_mfma_f32_32x32x16_bf16 v[0:15], v[208:211], v[228:231], v[0:15]
	v_mfma_f32_32x32x16_bf16 v[16:31], v[212:215], v[232:235], v[16:31]
	v_mfma_f32_32x32x16_bf16 v[0:15], v[216:219], v[232:235], v[0:15]
	s_barrier
	ds_read_b128 v[168:171], v155 offset:32768
	ds_read_b128 v[172:175], v156 offset:32768
	ds_read_b128 v[176:179], v157 offset:32768
	ds_read_b128 v[180:183], v158 offset:32768
	v_readfirstlane_b32 s63, v141
	v_lshl_add_u64 v[220:221], v[188:189], 0, s[30:31]
	s_mov_b32 m0, s63
	v_readfirstlane_b32 s63, v140
	ds_read_b128 v[184:187], v154 offset:32768
	ds_read_b128 v[192:195], v154 offset:36864
	ds_read_b128 v[196:199], v153 offset:32768
	ds_read_b128 v[200:203], v153 offset:36864
	ds_read_b128 v[204:207], v152 offset:32768
	ds_read_b128 v[208:211], v152 offset:36864
	ds_read_b128 v[212:215], v131 offset:32768
	ds_read_b128 v[216:219], v131 offset:36864
	global_load_lds_dwordx4 v[220:221], off
	v_lshl_add_u64 v[220:221], v[188:189], 0, s[36:37]
	s_mov_b32 m0, s63
	s_nop 0
	global_load_lds_dwordx4 v[220:221], off
	s_waitcnt lgkmcnt(8)
	s_barrier
; #define G8_STA(b, h, kt) G8_STAGE(G8_SA(b, h), Ag, lda, h, kt)
; #define G8_STB(b, h, kt) G8_STAGE(G8_SB(b, h), Bg, ldb, h, kt)
; #define G8_LDA(b, h) do { _Pragma("unroll") for (int m_ = 0; m_ < 2; ++m_) _Pragma("unroll") for (int k_ = 0; k_ < 4; ++k_) \
;     At[m_][k_] = *reinterpret_cast<const LAS bf16x8*>(la + ((b) * 2 + (h)) * 16384 + m_ * 4096 + (((k_ * 2 + hi) ^ swz) << 4)); } while (0)
; #define G8_LDB(dst, b, h) do { _Pragma("unroll") for (int k_ = 0; k_ < 4; ++k_) \
;     dst[k_] = *reinterpret_cast<const LAS bf16x8*>(lb + ((b) * 2 + (h)) * 16384 + (((k_ * 2 + hi) ^ swz) << 4)); } while (0)
; #define G8_MMA(ai, bj, Bx) do { __builtin_amdgcn_s_setprio(1); _Pragma("unroll") for (int k_ = 0; k_ < 4; ++k_) _Pragma("unroll") for (int m_ = 0; m_ < 2; ++m_) \
;     acc[ai][bj][m_] = __builtin_amdgcn_mfma_f32_32x32x16_bf16(At[m_][k_], Bx[k_], acc[ai][bj][m_], 0, 0, 0); __builtin_amdgcn_s_setprio(0); } while (0)
; #define G8_WV(n) asm volatile("s_waitcnt vmcnt(" #n ")" ::: "memory")
; #define G8_WL(n) asm volatile("s_waitcnt lgkmcnt(" #n ")" ::: "memory")
; #define G8_BAR __builtin_amdgcn_s_barrier()
; #define G8_SCHED __builtin_amdgcn_sched_barrier(0)
; template <class Epi>
; __device__ __forceinline__ void gemm8p(const bf16_t* __restrict__ A, int lda, const bf16_t* __restrict__ Bt, int ldb, int K,
;                                        LP lds, const Epi& epi, bool pre = false, const bf16_t* An = nullptr, const bf16_t* Bn = nullptr) {
;     ...
;     G8_WL(8); G8_BAR; G8_WL(0); G8_MMA(0, 0, B0); G8_BAR; G8_SCHED;
;     G8_LDB(B1, 1, 1); G8_STB(1, 0, t + 3);
;     G8_BAR; G8_WL(0); G8_MMA(0, 1, B1); G8_BAR; G8_SCHED;
;     G8_LDA(1, 1); G8_STA(1, 0, t + 3);
;     G8_BAR; G8_WL(0); G8_MMA(1, 0, B0); G8_BAR; G8_SCHED;
;     G8_STB(1, 1, t + 3);
;     G8_WV(6); G8_BAR; G8_MMA(1, 1, B1); G8_BAR; G8_SCHED;
;   }
;   { G8_LDB(B0, 0, 0); G8_LDA(0, 0); G8_STA(1, 1, nt - 1);
;     G8_BAR; G8_WL(0); G8_MMA(0, 0, B0); G8_BAR; G8_SCHED;
;     G8_LDB(B1, 0, 1); G8_BAR; G8_WL(0); G8_MMA(0, 1, B1); G8_BAR; G8_SCHED;
	s_waitcnt lgkmcnt(0)
	s_waitcnt lgkmcnt(0)
	v_mfma_f32_32x32x16_bf16 v[112:127], v[184:187], v[168:171], v[112:127]
	v_mfma_f32_32x32x16_bf16 v[96:111], v[192:195], v[168:171], v[96:111]
	v_mfma_f32_32x32x16_bf16 v[112:127], v[196:199], v[172:175], v[112:127]
	v_mfma_f32_32x32x16_bf16 v[96:111], v[200:203], v[172:175], v[96:111]
	v_mfma_f32_32x32x16_bf16 v[112:127], v[204:207], v[176:179], v[112:127]
	v_mfma_f32_32x32x16_bf16 v[96:111], v[208:211], v[176:179], v[96:111]
	v_mfma_f32_32x32x16_bf16 v[112:127], v[212:215], v[180:183], v[112:127]
	v_mfma_f32_32x32x16_bf16 v[96:111], v[216:219], v[180:183], v[96:111]
	s_barrier
	v_readfirstlane_b32 s63, v159
	v_lshl_add_u64 v[238:239], v[236:237], 0, s[38:39]
	s_mov_b32 m0, s63
	v_readfirstlane_b32 s63, v160
	ds_read_b128 v[220:223], v155 offset:49152
	ds_read_b128 v[224:227], v156 offset:49152
	ds_read_b128 v[228:231], v157 offset:49152
	ds_read_b128 v[232:235], v158 offset:49152
	global_load_lds_dwordx4 v[238:239], off
	v_lshl_add_u64 v[238:239], v[236:237], 0, s[40:41]
	s_mov_b32 m0, s63
	s_nop 0
	global_load_lds_dwordx4 v[238:239], off
	s_barrier
	s_waitcnt lgkmcnt(0)
	s_waitcnt lgkmcnt(0)
	v_mfma_f32_32x32x16_bf16 v[80:95], v[184:187], v[220:223], v[80:95]
	v_mfma_f32_32x32x16_bf16 v[64:79], v[192:195], v[220:223], v[64:79]
	v_mfma_f32_32x32x16_bf16 v[80:95], v[196:199], v[224:227], v[80:95]
	v_mfma_f32_32x32x16_bf16 v[64:79], v[200:203], v[224:227], v[64:79]
	v_mfma_f32_32x32x16_bf16 v[80:95], v[204:207], v[228:231], v[80:95]
	v_mfma_f32_32x32x16_bf16 v[64:79], v[208:211], v[228:231], v[64:79]
	v_mfma_f32_32x32x16_bf16 v[80:95], v[212:215], v[232:235], v[80:95]
	v_mfma_f32_32x32x16_bf16 v[64:79], v[216:219], v[232:235], v[64:79]
	s_barrier
	v_readfirstlane_b32 s63, v161
	v_lshl_add_u64 v[238:239], v[188:189], 0, s[42:43]
	s_mov_b32 m0, s63
	v_readfirstlane_b32 s63, v162
	ds_read_b128 v[184:187], v154 offset:49152
	ds_read_b128 v[192:195], v154 offset:53248
	ds_read_b128 v[196:199], v153 offset:49152
	ds_read_b128 v[200:203], v153 offset:53248
	ds_read_b128 v[204:207], v152 offset:49152
	ds_read_b128 v[208:211], v152 offset:53248
	ds_read_b128 v[212:215], v131 offset:49152
	ds_read_b128 v[216:219], v131 offset:53248
	global_load_lds_dwordx4 v[238:239], off
	v_lshl_add_u64 v[188:189], v[188:189], 0, s[44:45]
	s_mov_b32 m0, s63
	s_nop 0
	global_load_lds_dwordx4 v[188:189], off
	s_barrier
	s_waitcnt lgkmcnt(0)
	s_waitcnt lgkmcnt(0)
	v_mfma_f32_32x32x16_bf16 v[48:63], v[184:187], v[168:171], v[48:63]
	v_mfma_f32_32x32x16_bf16 v[32:47], v[192:195], v[168:171], v[32:47]
	v_mfma_f32_32x32x16_bf16 v[48:63], v[196:199], v[172:175], v[48:63]
	v_mfma_f32_32x32x16_bf16 v[32:47], v[200:203], v[172:175], v[32:47]
	v_mfma_f32_32x32x16_bf16 v[48:63], v[204:207], v[176:179], v[48:63]
	v_mfma_f32_32x32x16_bf16 v[32:47], v[208:211], v[176:179], v[32:47]
	v_mfma_f32_32x32x16_bf16 v[48:63], v[212:215], v[180:183], v[48:63]
	v_mfma_f32_32x32x16_bf16 v[32:47], v[216:219], v[180:183], v[32:47]
	s_barrier
	v_readfirstlane_b32 s63, v163
	v_lshl_add_u64 v[168:169], v[236:237], 0, s[46:47]
	s_mov_b32 m0, s63
	v_readfirstlane_b32 s63, v164
	global_load_lds_dwordx4 v[168:169], off
	v_lshl_add_u64 v[168:169], v[236:237], 0, s[48:49]
	s_mov_b32 m0, s63
	s_nop 0
	global_load_lds_dwordx4 v[168:169], off
	s_waitcnt vmcnt(6)
	s_barrier
	v_mfma_f32_32x32x16_bf16 v[16:31], v[184:187], v[220:223], v[16:31]
	v_mfma_f32_32x32x16_bf16 v[0:15], v[192:195], v[220:223], v[0:15]
	v_mfma_f32_32x32x16_bf16 v[16:31], v[196:199], v[224:227], v[16:31]
	v_mfma_f32_32x32x16_bf16 v[0:15], v[200:203], v[224:227], v[0:15]
	v_mfma_f32_32x32x16_bf16 v[16:31], v[204:207], v[228:231], v[16:31]
	v_mfma_f32_32x32x16_bf16 v[0:15], v[208:211], v[228:231], v[0:15]
	v_mfma_f32_32x32x16_bf16 v[16:31], v[212:215], v[232:235], v[16:31]
	v_mfma_f32_32x32x16_bf16 v[0:15], v[216:219], v[232:235], v[0:15]
	s_barrier
	s_add_i32 s59, s59, 2
	v_lshl_add_u64 v[136:137], v[136:137], 0, s[50:51]
	s_cmp_lt_u32 s59, 12
	v_lshl_add_u64 v[138:139], v[138:139], 0, s[50:51]
	s_cbranch_scc1 .LBB0_1623
	v_readfirstlane_b32 s59, v166
	v_lshl_add_u64 v[188:189], v[134:135], 0, s[52:53]
	s_mov_b32 m0, s59
	v_readfirstlane_b32 s59, v165
	ds_read_b128 v[136:139], v155
	ds_read_b128 v[160:163], v156
	ds_read_b128 v[168:171], v157
	ds_read_b128 v[172:175], v158
	ds_read_b128 v[176:179], v154
	ds_read_b128 v[180:183], v154 offset:4096
	ds_read_b128 v[184:187], v153
	ds_read_b128 v[192:195], v153 offset:4096
	ds_read_b128 v[196:199], v152
	ds_read_b128 v[200:203], v152 offset:4096
	ds_read_b128 v[204:207], v131
	ds_read_b128 v[208:211], v131 offset:4096
	global_load_lds_dwordx4 v[188:189], off
	v_lshl_add_u64 v[134:135], v[134:135], 0, s[54:55]
	s_mov_b32 m0, s59
	s_nop 0
	global_load_lds_dwordx4 v[134:135], off
	s_barrier
	s_waitcnt lgkmcnt(0)
	s_waitcnt lgkmcnt(0)
	v_mfma_f32_32x32x16_bf16 v[112:127], v[176:179], v[136:139], v[112:127]
	v_mfma_f32_32x32x16_bf16 v[96:111], v[180:183], v[136:139], v[96:111]
	v_mfma_f32_32x32x16_bf16 v[112:127], v[184:187], v[160:163], v[112:127]
	v_mfma_f32_32x32x16_bf16 v[96:111], v[192:195], v[160:163], v[96:111]
	v_mfma_f32_32x32x16_bf16 v[112:127], v[196:199], v[168:171], v[112:127]
	v_mfma_f32_32x32x16_bf16 v[96:111], v[200:203], v[168:171], v[96:111]
	v_mfma_f32_32x32x16_bf16 v[112:127], v[204:207], v[172:175], v[112:127]
	v_mfma_f32_32x32x16_bf16 v[96:111], v[208:211], v[172:175], v[96:111]
	s_barrier
	ds_read_b128 v[164:167], v155 offset:16384
	ds_read_b128 v[212:215], v156 offset:16384
	ds_read_b128 v[216:219], v157 offset:16384
	ds_read_b128 v[220:223], v158 offset:16384
	s_barrier
; #define G8_LDA(b, h) do { _Pragma("unroll") for (int m_ = 0; m_ < 2; ++m_) _Pragma("unroll") for (int k_ = 0; k_ < 4; ++k_) \
;     At[m_][k_] = *reinterpret_cast<const LAS bf16x8*>(la + ((b) * 2 + (h)) * 16384 + m_ * 4096 + (((k_ * 2 + hi) ^ swz) << 4)); } while (0)
; #define G8_LDB(dst, b, h) do { _Pragma("unroll") for (int k_ = 0; k_ < 4; ++k_) \
;     dst[k_] = *reinterpret_cast<const LAS bf16x8*>(lb + ((b) * 2 + (h)) * 16384 + (((k_ * 2 + hi) ^ swz) << 4)); } while (0)
; #define G8_MMA(ai, bj, Bx) do { __builtin_amdgcn_s_setprio(1); _Pragma("unroll") for (int k_ = 0; k_ < 4; ++k_) _Pragma("unroll") for (int m_ = 0; m_ < 2; ++m_) \
;     acc[ai][bj][m_] = __builtin_amdgcn_mfma_f32_32x32x16_bf16(At[m_][k_], Bx[k_], acc[ai][bj][m_], 0, 0, 0); __builtin_amdgcn_s_setprio(0); } while (0)
; #define G8_WV(n) asm volatile("s_waitcnt vmcnt(" #n ")" ::: "memory")
; #define G8_WL(n) asm volatile("s_waitcnt lgkmcnt(" #n ")" ::: "memory")
; #define G8_BAR __builtin_amdgcn_s_barrier()
; #define G8_SCHED __builtin_amdgcn_sched_barrier(0)
; template <class Epi>
; __device__ __forceinline__ void gemm8p(const bf16_t* __restrict__ A, int lda, const bf16_t* __restrict__ Bt, int ldb, int K,
;                                        LP lds, const Epi& epi, bool pre = false, const bf16_t* An = nullptr, const bf16_t* Bn = nullptr) {
;     ...
;     G8_LDB(B1, 0, 1); G8_BAR; G8_WL(0); G8_MMA(0, 1, B1); G8_BAR; G8_SCHED;
;     G8_LDA(0, 1); G8_WV(4); G8_BAR; G8_WL(0); G8_MMA(1, 0, B0); G8_MMA(1, 1, B1); G8_BAR; G8_SCHED; }
;   { G8_LDB(B0, 1, 0); G8_LDA(1, 0); G8_WV(2); G8_BAR; G8_WL(0); G8_MMA(0, 0, B0); G8_BAR; G8_SCHED;
;     G8_LDB(B1, 1, 1); G8_WV(0); G8_BAR; G8_WL(0); G8_MMA(0, 1, B1); G8_BAR; G8_SCHED;
;     G8_LDA(1, 1); G8_BAR; G8_WL(0); G8_MMA(1, 0, B0); G8_MMA(1, 1, B1); G8_BAR; G8_SCHED; }
;   if (wr == 0) G8_BAR;
	s_waitcnt lgkmcnt(0)
	s_waitcnt lgkmcnt(0)
	v_mfma_f32_32x32x16_bf16 v[80:95], v[176:179], v[164:167], v[80:95]
	v_mfma_f32_32x32x16_bf16 v[64:79], v[180:183], v[164:167], v[64:79]
	v_mfma_f32_32x32x16_bf16 v[80:95], v[184:187], v[212:215], v[80:95]
	v_mfma_f32_32x32x16_bf16 v[64:79], v[192:195], v[212:215], v[64:79]
	v_mfma_f32_32x32x16_bf16 v[80:95], v[196:199], v[216:219], v[80:95]
	v_mfma_f32_32x32x16_bf16 v[64:79], v[200:203], v[216:219], v[64:79]
	v_mfma_f32_32x32x16_bf16 v[80:95], v[204:207], v[220:223], v[80:95]
	v_mfma_f32_32x32x16_bf16 v[64:79], v[208:211], v[220:223], v[64:79]
	s_barrier
	ds_read_b128 v[176:179], v154 offset:16384
	ds_read_b128 v[180:183], v154 offset:20480
	ds_read_b128 v[184:187], v153 offset:16384
	ds_read_b128 v[192:195], v153 offset:20480
	ds_read_b128 v[196:199], v152 offset:16384
	ds_read_b128 v[200:203], v152 offset:20480
	ds_read_b128 v[204:207], v131 offset:16384
	ds_read_b128 v[208:211], v131 offset:20480
	s_waitcnt vmcnt(4)
	s_barrier
	s_waitcnt lgkmcnt(0)
	s_waitcnt lgkmcnt(0)
	v_mfma_f32_32x32x16_bf16 v[48:63], v[176:179], v[136:139], v[48:63]
	v_mfma_f32_32x32x16_bf16 v[32:47], v[180:183], v[136:139], v[32:47]
	v_mfma_f32_32x32x16_bf16 v[48:63], v[184:187], v[160:163], v[48:63]
	v_mfma_f32_32x32x16_bf16 v[32:47], v[192:195], v[160:163], v[32:47]
	v_mfma_f32_32x32x16_bf16 v[48:63], v[196:199], v[168:171], v[48:63]
	v_mfma_f32_32x32x16_bf16 v[32:47], v[200:203], v[168:171], v[32:47]
	v_mfma_f32_32x32x16_bf16 v[48:63], v[204:207], v[172:175], v[48:63]
	v_mfma_f32_32x32x16_bf16 v[32:47], v[208:211], v[172:175], v[32:47]
	v_mfma_f32_32x32x16_bf16 v[16:31], v[176:179], v[164:167], v[16:31]
	v_mfma_f32_32x32x16_bf16 v[0:15], v[180:183], v[164:167], v[0:15]
	v_mfma_f32_32x32x16_bf16 v[16:31], v[184:187], v[212:215], v[16:31]
	v_mfma_f32_32x32x16_bf16 v[0:15], v[192:195], v[212:215], v[0:15]
	v_mfma_f32_32x32x16_bf16 v[16:31], v[196:199], v[216:219], v[16:31]
	v_mfma_f32_32x32x16_bf16 v[0:15], v[200:203], v[216:219], v[0:15]
	v_mfma_f32_32x32x16_bf16 v[16:31], v[204:207], v[220:223], v[16:31]
	v_mfma_f32_32x32x16_bf16 v[0:15], v[208:211], v[220:223], v[0:15]
	s_barrier
	ds_read_b128 v[134:137], v155 offset:32768
	ds_read_b128 v[160:163], v156 offset:32768
	ds_read_b128 v[164:167], v157 offset:32768
	ds_read_b128 v[168:171], v158 offset:32768
	ds_read_b128 v[172:175], v154 offset:32768
	ds_read_b128 v[176:179], v154 offset:36864
	ds_read_b128 v[180:183], v153 offset:32768
	ds_read_b128 v[184:187], v153 offset:36864
	ds_read_b128 v[192:195], v152 offset:32768
	ds_read_b128 v[196:199], v152 offset:36864
	ds_read_b128 v[200:203], v131 offset:32768
	ds_read_b128 v[204:207], v131 offset:36864
	s_waitcnt vmcnt(2)
	s_barrier
	s_waitcnt lgkmcnt(0)
	s_waitcnt lgkmcnt(0)
	v_mfma_f32_32x32x16_bf16 v[112:127], v[172:175], v[134:137], v[112:127]
	v_mfma_f32_32x32x16_bf16 v[96:111], v[176:179], v[134:137], v[96:111]
	v_mfma_f32_32x32x16_bf16 v[112:127], v[180:183], v[160:163], v[112:127]
	v_mfma_f32_32x32x16_bf16 v[96:111], v[184:187], v[160:163], v[96:111]
	v_mfma_f32_32x32x16_bf16 v[112:127], v[192:195], v[164:167], v[112:127]
	v_mfma_f32_32x32x16_bf16 v[96:111], v[196:199], v[164:167], v[96:111]
	v_mfma_f32_32x32x16_bf16 v[112:127], v[200:203], v[168:171], v[112:127]
	v_mfma_f32_32x32x16_bf16 v[96:111], v[204:207], v[168:171], v[96:111]
	s_barrier
	ds_read_b128 v[208:211], v155 offset:49152
	ds_read_b128 v[212:215], v156 offset:49152
	ds_read_b128 v[216:219], v157 offset:49152
	ds_read_b128 v[156:159], v158 offset:49152
	s_waitcnt vmcnt(0)
	s_barrier
	s_waitcnt lgkmcnt(0)
	s_waitcnt lgkmcnt(0)
	v_mfma_f32_32x32x16_bf16 v[80:95], v[172:175], v[208:211], v[80:95]
	v_mfma_f32_32x32x16_bf16 v[64:79], v[176:179], v[208:211], v[64:79]
	v_mfma_f32_32x32x16_bf16 v[80:95], v[180:183], v[212:215], v[80:95]
	v_mfma_f32_32x32x16_bf16 v[64:79], v[184:187], v[212:215], v[64:79]
	v_mfma_f32_32x32x16_bf16 v[80:95], v[192:195], v[216:219], v[80:95]
	v_mfma_f32_32x32x16_bf16 v[64:79], v[196:199], v[216:219], v[64:79]
	v_mfma_f32_32x32x16_bf16 v[80:95], v[200:203], v[156:159], v[80:95]
	v_mfma_f32_32x32x16_bf16 v[64:79], v[204:207], v[156:159], v[64:79]
	s_barrier
	ds_read_b128 v[172:175], v154 offset:49152
	ds_read_b128 v[176:179], v154 offset:53248
	ds_read_b128 v[180:183], v153 offset:49152
	ds_read_b128 v[184:187], v153 offset:53248
	ds_read_b128 v[192:195], v152 offset:49152
	ds_read_b128 v[152:155], v152 offset:53248
	ds_read_b128 v[196:199], v131 offset:49152
	ds_read_b128 v[200:203], v131 offset:53248
	s_barrier
	s_waitcnt lgkmcnt(0)
	s_waitcnt lgkmcnt(0)
	v_mfma_f32_32x32x16_bf16 v[48:63], v[172:175], v[134:137], v[48:63]
	v_mfma_f32_32x32x16_bf16 v[32:47], v[176:179], v[134:137], v[32:47]
	v_mfma_f32_32x32x16_bf16 v[48:63], v[180:183], v[160:163], v[48:63]
	v_mfma_f32_32x32x16_bf16 v[32:47], v[184:187], v[160:163], v[32:47]
	v_mfma_f32_32x32x16_bf16 v[48:63], v[192:195], v[164:167], v[48:63]
	v_mfma_f32_32x32x16_bf16 v[32:47], v[152:155], v[164:167], v[32:47]
	v_mfma_f32_32x32x16_bf16 v[48:63], v[196:199], v[168:171], v[48:63]
	v_mfma_f32_32x32x16_bf16 v[32:47], v[200:203], v[168:171], v[32:47]
	v_mfma_f32_32x32x16_bf16 v[16:31], v[172:175], v[208:211], v[16:31]
	v_mfma_f32_32x32x16_bf16 v[0:15], v[176:179], v[208:211], v[0:15]
	v_mfma_f32_32x32x16_bf16 v[16:31], v[180:183], v[212:215], v[16:31]
	v_mfma_f32_32x32x16_bf16 v[0:15], v[184:187], v[212:215], v[0:15]
	v_mfma_f32_32x32x16_bf16 v[16:31], v[192:195], v[216:219], v[16:31]
	v_mfma_f32_32x32x16_bf16 v[0:15], v[152:155], v[216:219], v[0:15]
	v_mfma_f32_32x32x16_bf16 v[16:31], v[196:199], v[156:159], v[16:31]
	v_mfma_f32_32x32x16_bf16 v[0:15], v[200:203], v[156:159], v[0:15]
	s_barrier
	s_movk_i32 s59, 0x100
	v_cmp_gt_u32_e32 vcc, s59, v148
	s_and_saveexec_b64 s[66:67], vcc
	s_cbranch_execz .LBB0_1626
	s_barrier

; #define G8_STA(b, h, kt) G8_STAGE(G8_SA(b, h), Ag, lda, h, kt)
; #define G8_STB(b, h, kt) G8_STAGE(G8_SB(b, h), Bg, ldb, h, kt)
; #define G8_LDA(b, h) do { _Pragma("unroll") for (int m_ = 0; m_ < 2; ++m_) _Pragma("unroll") for (int k_ = 0; k_ < 4; ++k_) \
;     At[m_][k_] = *reinterpret_cast<const LAS bf16x8*>(la + ((b) * 2 + (h)) * 16384 + m_ * 4096 + (((k_ * 2 + hi) ^ swz) << 4)); } while (0)
; #define G8_LDB(dst, b, h) do { _Pragma("unroll") for (int k_ = 0; k_ < 4; ++k_) \
;     dst[k_] = *reinterpret_cast<const LAS bf16x8*>(lb + ((b) * 2 + (h)) * 16384 + (((k_ * 2 + hi) ^ swz) << 4)); } while (0)
; #define G8_MMA(ai, bj, Bx) do { __builtin_amdgcn_s_setprio(1); _Pragma("unroll") for (int k_ = 0; k_ < 4; ++k_) _Pragma("unroll") for (int m_ = 0; m_ < 2; ++m_) \
;     acc[ai][bj][m_] = __builtin_amdgcn_mfma_f32_32x32x16_bf16(At[m_][k_], Bx[k_], acc[ai][bj][m_], 0, 0, 0); __builtin_amdgcn_s_setprio(0); } while (0)
; #define G8_WV(n) asm volatile("s_waitcnt vmcnt(" #n ")" ::: "memory")
; #define G8_WL(n) asm volatile("s_waitcnt lgkmcnt(" #n ")" ::: "memory")
; #define G8_BAR __builtin_amdgcn_s_barrier()
; #define G8_SCHED __builtin_amdgcn_sched_barrier(0)
; template <class Epi>
; __device__ __forceinline__ void gemm8p(const bf16_t* __restrict__ A, int lda, const bf16_t* __restrict__ Bt, int ldb, int K,
;                                        LP lds, const Epi& epi, bool pre = false, const bf16_t* An = nullptr, const bf16_t* Bn = nullptr) {
;     ...
;   if (wr == 1) G8_BAR;
;   G8_WV(4); G8_BAR;
;   G8_STB(1, 0, 1); G8_STA(1, 0, 1); G8_STB(1, 1, 1);
;   G8_WV(6); G8_BAR;
;   G8_SCHED;
;   for (int t = 0; t < nt - 2; t += 2) {
;     G8_LDB(B0, 0, 0); G8_SCHED; G8_LDA(0, 0); G8_STA(1, 1, t + 1);
;     G8_WL(8); G8_BAR; G8_WL(0); G8_MMA(0, 0, B0); G8_BAR; G8_SCHED;
;     G8_LDB(B1, 0, 1); G8_STB(0, 0, t + 2);
;     G8_BAR; G8_WL(0); G8_MMA(0, 1, B1); G8_BAR; G8_SCHED;
;     G8_LDA(0, 1); G8_STA(0, 0, t + 2);
;     G8_BAR; G8_WL(0); G8_MMA(1, 0, B0); G8_BAR; G8_SCHED;
.LBB0_1633:
	s_or_b64 exec, exec, s[40:41]
	v_add_u32_e32 v10, 0x18000, v2
	v_lshl_add_u64 v[8:9], v[132:133], 0, s[10:11]
	v_readfirstlane_b32 s54, v10
	v_add_u32_e32 v10, 0x1a000, v2
	s_mov_b32 m0, s54
	v_readfirstlane_b32 s53, v10
	v_add_u32_e32 v10, 0x8000, v2
	s_waitcnt vmcnt(4)
	s_barrier
	global_load_lds_dwordx4 v[8:9], off
	v_lshl_add_u64 v[8:9], v[132:133], 0, s[12:13]
	s_mov_b32 m0, s53
	v_readfirstlane_b32 s52, v10
	v_add_u32_e32 v10, 0xa000, v2
	global_load_lds_dwordx4 v[8:9], off
	v_lshl_add_u64 v[8:9], v[130:131], 0, s[10:11]
	s_mov_b32 m0, s52
	v_readfirstlane_b32 s50, v10
	v_add_u32_e32 v10, 0x1c000, v2
	global_load_lds_dwordx4 v[8:9], off
	v_lshl_add_u64 v[8:9], v[130:131], 0, s[12:13]
	s_mov_b32 m0, s50
	v_readfirstlane_b32 s40, v10
	v_add_u32_e32 v10, 0x1e000, v2
	global_load_lds_dwordx4 v[8:9], off
	v_lshl_add_u64 v[8:9], v[132:133], 0, s[14:15]
	s_mov_b32 m0, s40
	v_readfirstlane_b32 s39, v10
	global_load_lds_dwordx4 v[8:9], off
	v_lshl_add_u64 v[8:9], v[132:133], 0, s[16:17]
	s_mov_b32 m0, s39
	v_lshlrev_b32_e32 v135, 6, v7
	global_load_lds_dwordx4 v[8:9], off
	v_and_b32_e32 v9, 31, v134
	v_lshlrev_b32_e32 v6, 5, v6
	s_waitcnt vmcnt(6)
	v_or_b32_e32 v7, v135, v9
	v_and_or_b32 v136, v6, s46, v9
	v_lshrrev_b32_e32 v8, 5, v134
	v_bfe_u32 v128, v134, 5, 1
	v_lshl_add_u32 v22, v7, 7, 0
	v_bfe_u32 v14, v134, 1, 3
	v_lshl_add_u32 v15, v136, 7, s74
	s_barrier
	v_bitop3_b32 v6, v8, v14, 1 bitop3:0x6c
	v_bitop3_b32 v16, v128, v14, 4 bitop3:0x36
	v_lshlrev_b32_e32 v23, 4, v6
	v_bitop3_b32 v6, v128, v14, 2 bitop3:0x36
	v_lshlrev_b32_e32 v25, 4, v16
	v_bitop3_b32 v14, v128, v14, 6 bitop3:0x36
	v_add_u32_e32 v191, v15, v23
	v_lshlrev_b32_e32 v24, 4, v6
	v_add_u32_e32 v209, v15, v25
	s_waitcnt vmcnt(0)
	v_lshlrev_b32_e32 v26, 4, v14
	v_add_u32_e32 v208, v15, v24
	ds_read_b128 v[6:9], v191
	ds_read_b128 v[10:13], v208
	v_add_u32_e32 v210, v15, v26
	ds_read_b128 v[14:17], v209
	ds_read_b128 v[18:21], v210
	v_add_u32_e32 v56, 0xc000, v2
	s_nop 0
	v_readfirstlane_b32 s51, v56
	v_add_u32_e32 v56, 0xe000, v2
	v_add_u32_e32 v211, v22, v23
	v_lshl_add_u64 v[54:55], v[130:131], 0, s[14:15]
	s_mov_b32 m0, s51
	v_readfirstlane_b32 s41, v56
	v_add_u32_e32 v212, v22, v24
	v_add_u32_e32 v213, v22, v25
	v_add_u32_e32 v214, v22, v26
	ds_read_b128 v[22:25], v211
	ds_read_b128 v[26:29], v211 offset:4096
	ds_read_b128 v[30:33], v212
	ds_read_b128 v[34:37], v212 offset:4096
	ds_read_b128 v[38:41], v213
	ds_read_b128 v[42:45], v213 offset:4096
	ds_read_b128 v[46:49], v214
	ds_read_b128 v[50:53], v214 offset:4096
	global_load_lds_dwordx4 v[54:55], off
	v_lshl_add_u64 v[54:55], v[130:131], 0, s[16:17]
	s_mov_b32 m0, s41
	s_nop 0
	global_load_lds_dwordx4 v[54:55], off
	s_waitcnt lgkmcnt(8)
	s_barrier
	s_waitcnt lgkmcnt(0)
	s_waitcnt lgkmcnt(0)
	v_mfma_f32_32x32x16_bf16 v[112:127], v[22:25], v[6:9], 0
	v_mfma_f32_32x32x16_bf16 v[96:111], v[26:29], v[6:9], 0
	v_mfma_f32_32x32x16_bf16 v[112:127], v[30:33], v[10:13], v[112:127]
	v_mfma_f32_32x32x16_bf16 v[96:111], v[34:37], v[10:13], v[96:111]
	v_mfma_f32_32x32x16_bf16 v[112:127], v[38:41], v[14:17], v[112:127]
	v_mfma_f32_32x32x16_bf16 v[96:111], v[42:45], v[14:17], v[96:111]
	v_mfma_f32_32x32x16_bf16 v[112:127], v[46:49], v[18:21], v[112:127]
	v_mfma_f32_32x32x16_bf16 v[96:111], v[50:53], v[18:21], v[96:111]
	s_barrier
	v_readfirstlane_b32 s55, v4
	v_lshl_add_u64 v[54:55], v[132:133], 0, s[18:19]
	s_mov_b32 m0, s55
	v_readfirstlane_b32 s55, v5
	ds_read_b128 v[140:143], v191 offset:16384
	ds_read_b128 v[144:147], v208 offset:16384
	ds_read_b128 v[148:151], v209 offset:16384
	ds_read_b128 v[152:155], v210 offset:16384
	global_load_lds_dwordx4 v[54:55], off
	v_lshl_add_u64 v[54:55], v[132:133], 0, s[20:21]
	s_mov_b32 m0, s55
	s_nop 0
	global_load_lds_dwordx4 v[54:55], off
	s_barrier
	s_waitcnt lgkmcnt(0)
	s_waitcnt lgkmcnt(0)
	v_mfma_f32_32x32x16_bf16 v[80:95], v[22:25], v[140:143], 0
	v_mfma_f32_32x32x16_bf16 v[64:79], v[26:29], v[140:143], 0
	v_mfma_f32_32x32x16_bf16 v[80:95], v[30:33], v[144:147], v[80:95]
	v_mfma_f32_32x32x16_bf16 v[64:79], v[34:37], v[144:147], v[64:79]
	v_mfma_f32_32x32x16_bf16 v[80:95], v[38:41], v[148:151], v[80:95]
	v_mfma_f32_32x32x16_bf16 v[64:79], v[42:45], v[148:151], v[64:79]
	v_mfma_f32_32x32x16_bf16 v[80:95], v[46:49], v[152:155], v[80:95]
	v_mfma_f32_32x32x16_bf16 v[64:79], v[50:53], v[152:155], v[64:79]
	s_barrier
	v_readfirstlane_b32 s55, v2
	v_lshl_add_u64 v[4:5], v[130:131], 0, s[18:19]
	s_mov_b32 m0, s55
	v_readfirstlane_b32 s55, v3
	ds_read_b128 v[22:25], v211 offset:16384
	ds_read_b128 v[156:159], v211 offset:20480
	ds_read_b128 v[160:163], v212 offset:16384
	ds_read_b128 v[164:167], v212 offset:20480
	ds_read_b128 v[168:171], v213 offset:16384
	ds_read_b128 v[172:175], v213 offset:20480
	ds_read_b128 v[176:179], v214 offset:16384
	ds_read_b128 v[180:183], v214 offset:20480
	global_load_lds_dwordx4 v[4:5], off
	v_lshl_add_u64 v[4:5], v[130:131], 0, s[20:21]
	s_mov_b32 m0, s55
	s_nop 0
	global_load_lds_dwordx4 v[4:5], off
	s_barrier
	s_waitcnt lgkmcnt(0)
	s_waitcnt lgkmcnt(0)
	v_mfma_f32_32x32x16_bf16 v[48:63], v[22:25], v[6:9], 0
	v_mfma_f32_32x32x16_bf16 v[32:47], v[156:159], v[6:9], 0
	v_mfma_f32_32x32x16_bf16 v[48:63], v[160:163], v[10:13], v[48:63]
	v_mfma_f32_32x32x16_bf16 v[32:47], v[164:167], v[10:13], v[32:47]
	v_mfma_f32_32x32x16_bf16 v[48:63], v[168:171], v[14:17], v[48:63]
	v_mfma_f32_32x32x16_bf16 v[32:47], v[172:175], v[14:17], v[32:47]
	v_mfma_f32_32x32x16_bf16 v[48:63], v[176:179], v[18:21], v[48:63]
	v_mfma_f32_32x32x16_bf16 v[32:47], v[180:183], v[18:21], v[32:47]
	s_barrier
; #define G8_STA(b, h, kt) G8_STAGE(G8_SA(b, h), Ag, lda, h, kt)
; #define G8_STB(b, h, kt) G8_STAGE(G8_SB(b, h), Bg, ldb, h, kt)
; #define G8_LDA(b, h) do { _Pragma("unroll") for (int m_ = 0; m_ < 2; ++m_) _Pragma("unroll") for (int k_ = 0; k_ < 4; ++k_) \
;     At[m_][k_] = *reinterpret_cast<const LAS bf16x8*>(la + ((b) * 2 + (h)) * 16384 + m_ * 4096 + (((k_ * 2 + hi) ^ swz) << 4)); } while (0)
; #define G8_LDB(dst, b, h) do { _Pragma("unroll") for (int k_ = 0; k_ < 4; ++k_) \
;     dst[k_] = *reinterpret_cast<const LAS bf16x8*>(lb + ((b) * 2 + (h)) * 16384 + (((k_ * 2 + hi) ^ swz) << 4)); } while (0)
; #define G8_MMA(ai, bj, Bx) do { __builtin_amdgcn_s_setprio(1); _Pragma("unroll") for (int k_ = 0; k_ < 4; ++k_) _Pragma("unroll") for (int m_ = 0; m_ < 2; ++m_) \
;     acc[ai][bj][m_] = __builtin_amdgcn_mfma_f32_32x32x16_bf16(At[m_][k_], Bx[k_], acc[ai][bj][m_], 0, 0, 0); __builtin_amdgcn_s_setprio(0); } while (0)
; #define G8_WV(n) asm volatile("s_waitcnt vmcnt(" #n ")" ::: "memory")
; #define G8_WL(n) asm volatile("s_waitcnt lgkmcnt(" #n ")" ::: "memory")
; #define G8_BAR __builtin_amdgcn_s_barrier()
; #define G8_SCHED __builtin_amdgcn_sched_barrier(0)
; template <class Epi>
; __device__ __forceinline__ void gemm8p(const bf16_t* __restrict__ A, int lda, const bf16_t* __restrict__ Bt, int ldb, int K,
;                                        LP lds, const Epi& epi, bool pre = false, const bf16_t* An = nullptr, const bf16_t* Bn = nullptr) {
;     ...
;     G8_STB(0, 1, t + 2);
;     G8_WV(6); G8_BAR; G8_MMA(1, 1, B1); G8_BAR; G8_SCHED;
;     G8_LDB(B0, 1, 0); G8_SCHED; G8_LDA(1, 0); G8_STA(0, 1, t + 2);
;     G8_WL(8); G8_BAR; G8_WL(0); G8_MMA(0, 0, B0); G8_BAR; G8_SCHED;
;     G8_LDB(B1, 1, 1); G8_STB(1, 0, t + 3);
;     G8_BAR; G8_WL(0); G8_MMA(0, 1, B1); G8_BAR; G8_SCHED;
;     G8_LDA(1, 1); G8_STA(1, 0, t + 3);
;     G8_BAR; G8_WL(0); G8_MMA(1, 0, B0); G8_BAR; G8_SCHED;
;     G8_STB(1, 1, t + 3);
;     G8_WV(6); G8_BAR; G8_MMA(1, 1, B1); G8_BAR; G8_SCHED;
	v_readfirstlane_b32 s55, v0
	v_lshl_add_u64 v[2:3], v[132:133], 0, s[22:23]
	s_mov_b32 m0, s55
	v_readfirstlane_b32 s55, v1
	global_load_lds_dwordx4 v[2:3], off
	v_lshl_add_u64 v[2:3], v[132:133], 0, s[24:25]
	s_mov_b32 m0, s55
	s_nop 0
	global_load_lds_dwordx4 v[2:3], off
	s_waitcnt vmcnt(6)
	s_barrier
	v_mfma_f32_32x32x16_bf16 v[16:31], v[22:25], v[140:143], 0
	v_mfma_f32_32x32x16_bf16 v[0:15], v[156:159], v[140:143], 0
	v_mfma_f32_32x32x16_bf16 v[16:31], v[160:163], v[144:147], v[16:31]
	v_mfma_f32_32x32x16_bf16 v[0:15], v[164:167], v[144:147], v[0:15]
	v_mfma_f32_32x32x16_bf16 v[16:31], v[168:171], v[148:151], v[16:31]
	v_mfma_f32_32x32x16_bf16 v[0:15], v[172:175], v[148:151], v[0:15]
	v_mfma_f32_32x32x16_bf16 v[16:31], v[176:179], v[152:155], v[16:31]
	v_mfma_f32_32x32x16_bf16 v[0:15], v[180:183], v[152:155], v[0:15]
	s_barrier
	ds_read_b128 v[140:143], v191 offset:32768
	ds_read_b128 v[144:147], v208 offset:32768
	ds_read_b128 v[148:151], v209 offset:32768
	ds_read_b128 v[152:155], v210 offset:32768
	v_readfirstlane_b32 s55, v137
	v_lshl_add_u64 v[188:189], v[130:131], 0, s[22:23]
	s_mov_b32 m0, s55
	v_readfirstlane_b32 s55, v138
	ds_read_b128 v[156:159], v211 offset:32768
	ds_read_b128 v[160:163], v211 offset:36864
	ds_read_b128 v[164:167], v212 offset:32768
	ds_read_b128 v[168:171], v212 offset:36864
	ds_read_b128 v[172:175], v213 offset:32768
	ds_read_b128 v[176:179], v213 offset:36864
	ds_read_b128 v[180:183], v214 offset:32768
	ds_read_b128 v[184:187], v214 offset:36864
	global_load_lds_dwordx4 v[188:189], off
	v_lshl_add_u64 v[188:189], v[130:131], 0, s[24:25]
	s_mov_b32 m0, s55
	s_nop 0
	global_load_lds_dwordx4 v[188:189], off
	s_waitcnt lgkmcnt(8)
	s_barrier
	s_waitcnt lgkmcnt(0)
	s_waitcnt lgkmcnt(0)
	v_mfma_f32_32x32x16_bf16 v[112:127], v[156:159], v[140:143], v[112:127]
	v_mfma_f32_32x32x16_bf16 v[96:111], v[160:163], v[140:143], v[96:111]
	v_mfma_f32_32x32x16_bf16 v[112:127], v[164:167], v[144:147], v[112:127]
	v_mfma_f32_32x32x16_bf16 v[96:111], v[168:171], v[144:147], v[96:111]
	v_mfma_f32_32x32x16_bf16 v[112:127], v[172:175], v[148:151], v[112:127]
	v_mfma_f32_32x32x16_bf16 v[96:111], v[176:179], v[148:151], v[96:111]
	v_mfma_f32_32x32x16_bf16 v[112:127], v[180:183], v[152:155], v[112:127]
	v_mfma_f32_32x32x16_bf16 v[96:111], v[184:187], v[152:155], v[96:111]
	s_barrier
	s_mov_b32 m0, s54
	v_lshl_add_u64 v[138:139], v[132:133], 0, s[26:27]
	ds_read_b128 v[192:195], v191 offset:49152
	ds_read_b128 v[196:199], v208 offset:49152
	ds_read_b128 v[200:203], v209 offset:49152
	ds_read_b128 v[204:207], v210 offset:49152
	global_load_lds_dwordx4 v[138:139], off
	v_lshl_add_u64 v[138:139], v[132:133], 0, s[28:29]
	s_mov_b32 m0, s53
	s_nop 0
	global_load_lds_dwordx4 v[138:139], off
	s_barrier
	s_waitcnt lgkmcnt(0)
	s_waitcnt lgkmcnt(0)
	v_mfma_f32_32x32x16_bf16 v[80:95], v[156:159], v[192:195], v[80:95]
	v_mfma_f32_32x32x16_bf16 v[64:79], v[160:163], v[192:195], v[64:79]
	v_mfma_f32_32x32x16_bf16 v[80:95], v[164:167], v[196:199], v[80:95]
	v_mfma_f32_32x32x16_bf16 v[64:79], v[168:171], v[196:199], v[64:79]
	v_mfma_f32_32x32x16_bf16 v[80:95], v[172:175], v[200:203], v[80:95]
	v_mfma_f32_32x32x16_bf16 v[64:79], v[176:179], v[200:203], v[64:79]
	v_mfma_f32_32x32x16_bf16 v[80:95], v[180:183], v[204:207], v[80:95]
	v_mfma_f32_32x32x16_bf16 v[64:79], v[184:187], v[204:207], v[64:79]
	s_barrier
	s_mov_b32 m0, s52
	v_lshl_add_u64 v[138:139], v[130:131], 0, s[26:27]
	ds_read_b128 v[156:159], v211 offset:49152
	ds_read_b128 v[160:163], v211 offset:53248
	ds_read_b128 v[164:167], v212 offset:49152
	ds_read_b128 v[168:171], v212 offset:53248
	ds_read_b128 v[172:175], v213 offset:49152
	ds_read_b128 v[176:179], v213 offset:53248
	ds_read_b128 v[180:183], v214 offset:49152
	ds_read_b128 v[184:187], v214 offset:53248
	global_load_lds_dwordx4 v[138:139], off
	v_lshl_add_u64 v[138:139], v[130:131], 0, s[28:29]
	s_mov_b32 m0, s50
	s_nop 0
	global_load_lds_dwordx4 v[138:139], off
	s_barrier
	s_waitcnt lgkmcnt(0)
	s_waitcnt lgkmcnt(0)
	v_mfma_f32_32x32x16_bf16 v[48:63], v[156:159], v[140:143], v[48:63]
	v_mfma_f32_32x32x16_bf16 v[32:47], v[160:163], v[140:143], v[32:47]
	v_mfma_f32_32x32x16_bf16 v[48:63], v[164:167], v[144:147], v[48:63]
	v_mfma_f32_32x32x16_bf16 v[32:47], v[168:171], v[144:147], v[32:47]
	v_mfma_f32_32x32x16_bf16 v[48:63], v[172:175], v[148:151], v[48:63]
	v_mfma_f32_32x32x16_bf16 v[32:47], v[176:179], v[148:151], v[32:47]
	v_mfma_f32_32x32x16_bf16 v[48:63], v[180:183], v[152:155], v[48:63]
	v_mfma_f32_32x32x16_bf16 v[32:47], v[184:187], v[152:155], v[32:47]
	s_barrier
	s_mov_b32 m0, s40
	v_lshl_add_u64 v[138:139], v[132:133], 0, s[30:31]
	global_load_lds_dwordx4 v[138:139], off
	v_lshl_add_u64 v[132:133], v[132:133], 0, s[36:37]
	s_mov_b32 m0, s39
	s_nop 0
	global_load_lds_dwordx4 v[132:133], off
	s_waitcnt vmcnt(6)
	s_barrier
	v_mfma_f32_32x32x16_bf16 v[16:31], v[156:159], v[192:195], v[16:31]
	v_mfma_f32_32x32x16_bf16 v[0:15], v[160:163], v[192:195], v[0:15]
	v_mfma_f32_32x32x16_bf16 v[16:31], v[164:167], v[196:199], v[16:31]
	v_mfma_f32_32x32x16_bf16 v[0:15], v[168:171], v[196:199], v[0:15]
	v_mfma_f32_32x32x16_bf16 v[16:31], v[172:175], v[200:203], v[16:31]
	v_mfma_f32_32x32x16_bf16 v[0:15], v[176:179], v[200:203], v[0:15]
	v_mfma_f32_32x32x16_bf16 v[16:31], v[180:183], v[204:207], v[16:31]
	v_mfma_f32_32x32x16_bf16 v[0:15], v[184:187], v[204:207], v[0:15]
	s_barrier
; #define G8_STA(b, h, kt) G8_STAGE(G8_SA(b, h), Ag, lda, h, kt)
; #define G8_LDA(b, h) do { _Pragma("unroll") for (int m_ = 0; m_ < 2; ++m_) _Pragma("unroll") for (int k_ = 0; k_ < 4; ++k_) \
;     At[m_][k_] = *reinterpret_cast<const LAS bf16x8*>(la + ((b) * 2 + (h)) * 16384 + m_ * 4096 + (((k_ * 2 + hi) ^ swz) << 4)); } while (0)
; #define G8_LDB(dst, b, h) do { _Pragma("unroll") for (int k_ = 0; k_ < 4; ++k_) \
;     dst[k_] = *reinterpret_cast<const LAS bf16x8*>(lb + ((b) * 2 + (h)) * 16384 + (((k_ * 2 + hi) ^ swz) << 4)); } while (0)
; #define G8_MMA(ai, bj, Bx) do { __builtin_amdgcn_s_setprio(1); _Pragma("unroll") for (int k_ = 0; k_ < 4; ++k_) _Pragma("unroll") for (int m_ = 0; m_ < 2; ++m_) \
;     acc[ai][bj][m_] = __builtin_amdgcn_mfma_f32_32x32x16_bf16(At[m_][k_], Bx[k_], acc[ai][bj][m_], 0, 0, 0); __builtin_amdgcn_s_setprio(0); } while (0)
; #define G8_WV(n) asm volatile("s_waitcnt vmcnt(" #n ")" ::: "memory")
; #define G8_WL(n) asm volatile("s_waitcnt lgkmcnt(" #n ")" ::: "memory")
; #define G8_BAR __builtin_amdgcn_s_barrier()
; #define G8_SCHED __builtin_amdgcn_sched_barrier(0)
; template <class Epi>
; __device__ __forceinline__ void gemm8p(const bf16_t* __restrict__ A, int lda, const bf16_t* __restrict__ Bt, int ldb, int K,
;                                        LP lds, const Epi& epi, bool pre = false, const bf16_t* An = nullptr, const bf16_t* Bn = nullptr) {
;     ...
;   { G8_LDB(B0, 0, 0); G8_LDA(0, 0); G8_STA(1, 1, nt - 1);
;     G8_BAR; G8_WL(0); G8_MMA(0, 0, B0); G8_BAR; G8_SCHED;
;     G8_LDB(B1, 0, 1); G8_BAR; G8_WL(0); G8_MMA(0, 1, B1); G8_BAR; G8_SCHED;
;     G8_LDA(0, 1); G8_WV(4); G8_BAR; G8_WL(0); G8_MMA(1, 0, B0); G8_MMA(1, 1, B1); G8_BAR; G8_SCHED; }
	s_mov_b32 m0, s51
	v_lshl_add_u64 v[132:133], v[130:131], 0, s[30:31]
	ds_read_b128 v[138:141], v191
	ds_read_b128 v[142:145], v208
	ds_read_b128 v[146:149], v209
	ds_read_b128 v[150:153], v210
	ds_read_b128 v[154:157], v211
	ds_read_b128 v[158:161], v211 offset:4096
	ds_read_b128 v[162:165], v212
	ds_read_b128 v[166:169], v212 offset:4096
	ds_read_b128 v[170:173], v213
	ds_read_b128 v[174:177], v213 offset:4096
	ds_read_b128 v[178:181], v214
	ds_read_b128 v[182:185], v214 offset:4096
	global_load_lds_dwordx4 v[132:133], off
	v_lshl_add_u64 v[130:131], v[130:131], 0, s[36:37]
	s_mov_b32 m0, s41
	s_nop 0
	global_load_lds_dwordx4 v[130:131], off
	s_barrier
	s_waitcnt lgkmcnt(0)
	s_waitcnt lgkmcnt(0)
	v_mfma_f32_32x32x16_bf16 v[112:127], v[154:157], v[138:141], v[112:127]
	v_mfma_f32_32x32x16_bf16 v[96:111], v[158:161], v[138:141], v[96:111]
	v_mfma_f32_32x32x16_bf16 v[112:127], v[162:165], v[142:145], v[112:127]
	v_mfma_f32_32x32x16_bf16 v[96:111], v[166:169], v[142:145], v[96:111]
	v_mfma_f32_32x32x16_bf16 v[112:127], v[170:173], v[146:149], v[112:127]
	v_mfma_f32_32x32x16_bf16 v[96:111], v[174:177], v[146:149], v[96:111]
	v_mfma_f32_32x32x16_bf16 v[112:127], v[178:181], v[150:153], v[112:127]
	v_mfma_f32_32x32x16_bf16 v[96:111], v[182:185], v[150:153], v[96:111]
	s_barrier
	ds_read_b128 v[130:133], v191 offset:16384
	ds_read_b128 v[186:189], v208 offset:16384
	ds_read_b128 v[192:195], v209 offset:16384
	ds_read_b128 v[196:199], v210 offset:16384
	s_barrier
	s_waitcnt lgkmcnt(0)
	s_waitcnt lgkmcnt(0)
	v_mfma_f32_32x32x16_bf16 v[80:95], v[154:157], v[130:133], v[80:95]
	v_mfma_f32_32x32x16_bf16 v[64:79], v[158:161], v[130:133], v[64:79]
	v_mfma_f32_32x32x16_bf16 v[80:95], v[162:165], v[186:189], v[80:95]
	v_mfma_f32_32x32x16_bf16 v[64:79], v[166:169], v[186:189], v[64:79]
	v_mfma_f32_32x32x16_bf16 v[80:95], v[170:173], v[192:195], v[80:95]
	v_mfma_f32_32x32x16_bf16 v[64:79], v[174:177], v[192:195], v[64:79]
	v_mfma_f32_32x32x16_bf16 v[80:95], v[178:181], v[196:199], v[80:95]
	v_mfma_f32_32x32x16_bf16 v[64:79], v[182:185], v[196:199], v[64:79]
	s_barrier
	ds_read_b128 v[154:157], v211 offset:16384
	ds_read_b128 v[158:161], v211 offset:20480
	ds_read_b128 v[162:165], v212 offset:16384
	ds_read_b128 v[166:169], v212 offset:20480
	ds_read_b128 v[170:173], v213 offset:16384
	ds_read_b128 v[174:177], v213 offset:20480
	ds_read_b128 v[178:181], v214 offset:16384
	ds_read_b128 v[182:185], v214 offset:20480
	s_waitcnt vmcnt(4)
	s_barrier
	s_waitcnt lgkmcnt(0)
	s_waitcnt lgkmcnt(0)
	v_mfma_f32_32x32x16_bf16 v[48:63], v[154:157], v[138:141], v[48:63]
	v_mfma_f32_32x32x16_bf16 v[32:47], v[158:161], v[138:141], v[32:47]
	v_mfma_f32_32x32x16_bf16 v[48:63], v[162:165], v[142:145], v[48:63]
	v_mfma_f32_32x32x16_bf16 v[32:47], v[166:169], v[142:145], v[32:47]
	v_mfma_f32_32x32x16_bf16 v[48:63], v[170:173], v[146:149], v[48:63]
	v_mfma_f32_32x32x16_bf16 v[32:47], v[174:177], v[146:149], v[32:47]
	v_mfma_f32_32x32x16_bf16 v[48:63], v[178:181], v[150:153], v[48:63]
	v_mfma_f32_32x32x16_bf16 v[32:47], v[182:185], v[150:153], v[32:47]
	v_mfma_f32_32x32x16_bf16 v[16:31], v[154:157], v[130:133], v[16:31]
	v_mfma_f32_32x32x16_bf16 v[0:15], v[158:161], v[130:133], v[0:15]
	v_mfma_f32_32x32x16_bf16 v[16:31], v[162:165], v[186:189], v[16:31]
	v_mfma_f32_32x32x16_bf16 v[0:15], v[166:169], v[186:189], v[0:15]
	v_mfma_f32_32x32x16_bf16 v[16:31], v[170:173], v[192:195], v[16:31]
	v_mfma_f32_32x32x16_bf16 v[0:15], v[174:177], v[192:195], v[0:15]
	v_mfma_f32_32x32x16_bf16 v[16:31], v[178:181], v[196:199], v[16:31]
	v_mfma_f32_32x32x16_bf16 v[0:15], v[182:185], v[196:199], v[0:15]
	s_barrier
; #define G8_LDA(b, h) do { _Pragma("unroll") for (int m_ = 0; m_ < 2; ++m_) _Pragma("unroll") for (int k_ = 0; k_ < 4; ++k_) \
;     At[m_][k_] = *reinterpret_cast<const LAS bf16x8*>(la + ((b) * 2 + (h)) * 16384 + m_ * 4096 + (((k_ * 2 + hi) ^ swz) << 4)); } while (0)
; #define G8_LDB(dst, b, h) do { _Pragma("unroll") for (int k_ = 0; k_ < 4; ++k_) \
;     dst[k_] = *reinterpret_cast<const LAS bf16x8*>(lb + ((b) * 2 + (h)) * 16384 + (((k_ * 2 + hi) ^ swz) << 4)); } while (0)
; #define G8_MMA(ai, bj, Bx) do { __builtin_amdgcn_s_setprio(1); _Pragma("unroll") for (int k_ = 0; k_ < 4; ++k_) _Pragma("unroll") for (int m_ = 0; m_ < 2; ++m_) \
;     acc[ai][bj][m_] = __builtin_amdgcn_mfma_f32_32x32x16_bf16(At[m_][k_], Bx[k_], acc[ai][bj][m_], 0, 0, 0); __builtin_amdgcn_s_setprio(0); } while (0)
; #define G8_WV(n) asm volatile("s_waitcnt vmcnt(" #n ")" ::: "memory")
; #define G8_WL(n) asm volatile("s_waitcnt lgkmcnt(" #n ")" ::: "memory")
; #define G8_BAR __builtin_amdgcn_s_barrier()
; #define G8_SCHED __builtin_amdgcn_sched_barrier(0)
; template <class Epi>
; __device__ __forceinline__ void gemm8p(const bf16_t* __restrict__ A, int lda, const bf16_t* __restrict__ Bt, int ldb, int K,
;                                        LP lds, const Epi& epi, bool pre = false, const bf16_t* An = nullptr, const bf16_t* Bn = nullptr) {
;     ...
;   { G8_LDB(B0, 1, 0); G8_LDA(1, 0); G8_WV(2); G8_BAR; G8_WL(0); G8_MMA(0, 0, B0); G8_BAR; G8_SCHED;
;     G8_LDB(B1, 1, 1); G8_WV(0); G8_BAR; G8_WL(0); G8_MMA(0, 1, B1); G8_BAR; G8_SCHED;
;     G8_LDA(1, 1); G8_BAR; G8_WL(0); G8_MMA(1, 0, B0); G8_MMA(1, 1, B1); G8_BAR; G8_SCHED; }
;   if (wr == 0) G8_BAR;
	ds_read_b128 v[130:133], v191 offset:32768
	ds_read_b128 v[138:141], v208 offset:32768
	ds_read_b128 v[142:145], v209 offset:32768
	ds_read_b128 v[146:149], v210 offset:32768
	ds_read_b128 v[150:153], v211 offset:32768
	ds_read_b128 v[154:157], v211 offset:36864
	ds_read_b128 v[158:161], v212 offset:32768
	ds_read_b128 v[162:165], v212 offset:36864
	ds_read_b128 v[166:169], v213 offset:32768
	ds_read_b128 v[170:173], v213 offset:36864
	ds_read_b128 v[174:177], v214 offset:32768
	ds_read_b128 v[178:181], v214 offset:36864
	s_waitcnt vmcnt(2)
	s_barrier
	s_waitcnt lgkmcnt(0)
	s_waitcnt lgkmcnt(0)
	v_mfma_f32_32x32x16_bf16 v[112:127], v[150:153], v[130:133], v[112:127]
	v_mfma_f32_32x32x16_bf16 v[96:111], v[154:157], v[130:133], v[96:111]
	v_mfma_f32_32x32x16_bf16 v[112:127], v[158:161], v[138:141], v[112:127]
	v_mfma_f32_32x32x16_bf16 v[96:111], v[162:165], v[138:141], v[96:111]
	v_mfma_f32_32x32x16_bf16 v[112:127], v[166:169], v[142:145], v[112:127]
	v_mfma_f32_32x32x16_bf16 v[96:111], v[170:173], v[142:145], v[96:111]
	v_mfma_f32_32x32x16_bf16 v[112:127], v[174:177], v[146:149], v[112:127]
	v_mfma_f32_32x32x16_bf16 v[96:111], v[178:181], v[146:149], v[96:111]
	s_barrier
	ds_read_b128 v[182:185], v191 offset:49152
	ds_read_b128 v[186:189], v208 offset:49152
	ds_read_b128 v[192:195], v209 offset:49152
	ds_read_b128 v[196:199], v210 offset:49152
	s_waitcnt vmcnt(0)
	s_barrier
	s_waitcnt lgkmcnt(0)
	s_waitcnt lgkmcnt(0)
	v_mfma_f32_32x32x16_bf16 v[80:95], v[150:153], v[182:185], v[80:95]
	v_mfma_f32_32x32x16_bf16 v[64:79], v[154:157], v[182:185], v[64:79]
	v_mfma_f32_32x32x16_bf16 v[80:95], v[158:161], v[186:189], v[80:95]
	v_mfma_f32_32x32x16_bf16 v[64:79], v[162:165], v[186:189], v[64:79]
	v_mfma_f32_32x32x16_bf16 v[80:95], v[166:169], v[192:195], v[80:95]
	v_mfma_f32_32x32x16_bf16 v[64:79], v[170:173], v[192:195], v[64:79]
	v_mfma_f32_32x32x16_bf16 v[80:95], v[174:177], v[196:199], v[80:95]
	v_mfma_f32_32x32x16_bf16 v[64:79], v[178:181], v[196:199], v[64:79]
	s_barrier
	ds_read_b128 v[150:153], v211 offset:49152
	ds_read_b128 v[154:157], v211 offset:53248
	ds_read_b128 v[158:161], v212 offset:49152
	ds_read_b128 v[162:165], v212 offset:53248
	ds_read_b128 v[166:169], v213 offset:49152
	ds_read_b128 v[170:173], v213 offset:53248
	ds_read_b128 v[174:177], v214 offset:49152
	ds_read_b128 v[178:181], v214 offset:53248
	s_barrier
	s_waitcnt lgkmcnt(0)
	s_waitcnt lgkmcnt(0)
	v_mfma_f32_32x32x16_bf16 v[48:63], v[150:153], v[130:133], v[48:63]
	v_mfma_f32_32x32x16_bf16 v[32:47], v[154:157], v[130:133], v[32:47]
	v_mfma_f32_32x32x16_bf16 v[48:63], v[158:161], v[138:141], v[48:63]
	v_mfma_f32_32x32x16_bf16 v[32:47], v[162:165], v[138:141], v[32:47]
	v_mfma_f32_32x32x16_bf16 v[48:63], v[166:169], v[142:145], v[48:63]
	v_mfma_f32_32x32x16_bf16 v[32:47], v[170:173], v[142:145], v[32:47]
	v_mfma_f32_32x32x16_bf16 v[48:63], v[174:177], v[146:149], v[48:63]
	v_mfma_f32_32x32x16_bf16 v[32:47], v[178:181], v[146:149], v[32:47]
	v_mfma_f32_32x32x16_bf16 v[16:31], v[150:153], v[182:185], v[16:31]
	v_mfma_f32_32x32x16_bf16 v[0:15], v[154:157], v[182:185], v[0:15]
	v_mfma_f32_32x32x16_bf16 v[16:31], v[158:161], v[186:189], v[16:31]
	v_mfma_f32_32x32x16_bf16 v[0:15], v[162:165], v[186:189], v[0:15]
	v_mfma_f32_32x32x16_bf16 v[16:31], v[166:169], v[192:195], v[16:31]
	v_mfma_f32_32x32x16_bf16 v[0:15], v[170:173], v[192:195], v[0:15]
	v_mfma_f32_32x32x16_bf16 v[16:31], v[174:177], v[196:199], v[16:31]
	v_mfma_f32_32x32x16_bf16 v[0:15], v[178:181], v[196:199], v[0:15]
	s_barrier
	v_cmp_gt_u32_e32 vcc, s47, v134
	s_and_saveexec_b64 s[40:41], vcc
	s_cbranch_execz .LBB0_1630
	s_barrier
	s_branch .LBB0_1630

; #define G8_STA(b, h, kt) G8_STAGE(G8_SA(b, h), Ag, lda, h, kt)
; #define G8_STB(b, h, kt) G8_STAGE(G8_SB(b, h), Bg, ldb, h, kt)
; #define G8_LDA(b, h) do { _Pragma("unroll") for (int m_ = 0; m_ < 2; ++m_) _Pragma("unroll") for (int k_ = 0; k_ < 4; ++k_) \
;     At[m_][k_] = *reinterpret_cast<const LAS bf16x8*>(la + ((b) * 2 + (h)) * 16384 + m_ * 4096 + (((k_ * 2 + hi) ^ swz) << 4)); } while (0)
; #define G8_LDB(dst, b, h) do { _Pragma("unroll") for (int k_ = 0; k_ < 4; ++k_) \
;     dst[k_] = *reinterpret_cast<const LAS bf16x8*>(lb + ((b) * 2 + (h)) * 16384 + (((k_ * 2 + hi) ^ swz) << 4)); } while (0)
; #define G8_MMA(ai, bj, Bx) do { __builtin_amdgcn_s_setprio(1); _Pragma("unroll") for (int k_ = 0; k_ < 4; ++k_) _Pragma("unroll") for (int m_ = 0; m_ < 2; ++m_) \
;     acc[ai][bj][m_] = __builtin_amdgcn_mfma_f32_32x32x16_bf16(At[m_][k_], Bx[k_], acc[ai][bj][m_], 0, 0, 0); __builtin_amdgcn_s_setprio(0); } while (0)
; #define G8_WV(n) asm volatile("s_waitcnt vmcnt(" #n ")" ::: "memory")
; #define G8_WL(n) asm volatile("s_waitcnt lgkmcnt(" #n ")" ::: "memory")
; #define G8_BAR __builtin_amdgcn_s_barrier()
; #define G8_SCHED __builtin_amdgcn_sched_barrier(0)
; template <class Epi>
; __device__ __forceinline__ void gemm8p(const bf16_t* __restrict__ A, int lda, const bf16_t* __restrict__ Bt, int ldb, int K,
;                                        LP lds, const Epi& epi, bool pre = false, const bf16_t* An = nullptr, const bf16_t* Bn = nullptr) {
;     ...
;     G8_LDB(B0, 0, 0); G8_SCHED; G8_LDA(0, 0); G8_STA(1, 1, t + 1);
;     G8_WL(8); G8_BAR; G8_WL(0); G8_MMA(0, 0, B0); G8_BAR; G8_SCHED;
;     G8_LDB(B1, 0, 1); G8_STB(0, 0, t + 2);
;     G8_BAR; G8_WL(0); G8_MMA(0, 1, B1); G8_BAR; G8_SCHED;
;     G8_LDA(0, 1); G8_STA(0, 0, t + 2);
;     G8_BAR; G8_WL(0); G8_MMA(1, 0, B0); G8_BAR; G8_SCHED;
;     G8_STB(0, 1, t + 2);
;     G8_WV(6); G8_BAR; G8_MMA(1, 1, B1); G8_BAR; G8_SCHED;
;     G8_LDB(B0, 1, 0); G8_SCHED; G8_LDA(1, 0); G8_STA(0, 1, t + 2);
.LBB0_1759:
	ds_read_b128 v[168:171], v155
	ds_read_b128 v[172:175], v156
	ds_read_b128 v[176:179], v157
	ds_read_b128 v[180:183], v158
	v_lshl_add_u64 v[188:189], v[136:137], 0, v[128:129]
	s_mov_b64 s[66:67], 0x3ab6080
	v_lshl_add_u64 v[220:221], v[188:189], 0, s[66:67]
	v_readfirstlane_b32 s66, v166
	s_mov_b32 m0, s66
	s_mov_b64 s[66:67], 0x3ad6080
	ds_read_b128 v[184:187], v154
	ds_read_b128 v[192:195], v154 offset:4096
	ds_read_b128 v[196:199], v153
	ds_read_b128 v[200:203], v153 offset:4096
	ds_read_b128 v[204:207], v152
	ds_read_b128 v[208:211], v152 offset:4096
	ds_read_b128 v[212:215], v131
	ds_read_b128 v[216:219], v131 offset:4096
	global_load_lds_dwordx4 v[220:221], off
	v_lshl_add_u64 v[220:221], v[188:189], 0, s[66:67]
	v_readfirstlane_b32 s66, v165
	s_mov_b32 m0, s66
	s_nop 0
	global_load_lds_dwordx4 v[220:221], off
	s_waitcnt lgkmcnt(8)
	s_barrier
	s_waitcnt lgkmcnt(0)
	s_waitcnt lgkmcnt(0)
	v_mfma_f32_32x32x16_bf16 v[112:127], v[184:187], v[168:171], v[112:127]
	v_mfma_f32_32x32x16_bf16 v[96:111], v[192:195], v[168:171], v[96:111]
	v_mfma_f32_32x32x16_bf16 v[112:127], v[196:199], v[172:175], v[112:127]
	v_mfma_f32_32x32x16_bf16 v[96:111], v[200:203], v[172:175], v[96:111]
	v_mfma_f32_32x32x16_bf16 v[112:127], v[204:207], v[176:179], v[112:127]
	v_mfma_f32_32x32x16_bf16 v[96:111], v[208:211], v[176:179], v[96:111]
	v_mfma_f32_32x32x16_bf16 v[112:127], v[212:215], v[180:183], v[112:127]
	v_mfma_f32_32x32x16_bf16 v[96:111], v[216:219], v[180:183], v[96:111]
	s_barrier
	v_lshl_add_u64 v[236:237], v[138:139], 0, v[128:129]
	v_readfirstlane_b32 s66, v147
	v_lshl_add_u64 v[238:239], v[236:237], 0, s[20:21]
	s_mov_b32 m0, s66
	v_readfirstlane_b32 s66, v146
	ds_read_b128 v[220:223], v155 offset:16384
	ds_read_b128 v[224:227], v156 offset:16384
	ds_read_b128 v[228:231], v157 offset:16384
	ds_read_b128 v[232:235], v158 offset:16384
	global_load_lds_dwordx4 v[238:239], off
	v_lshl_add_u64 v[238:239], v[236:237], 0, s[22:23]
	s_mov_b32 m0, s66
	s_nop 0
	global_load_lds_dwordx4 v[238:239], off
	s_barrier
	s_waitcnt lgkmcnt(0)
	s_waitcnt lgkmcnt(0)
	v_mfma_f32_32x32x16_bf16 v[80:95], v[184:187], v[220:223], v[80:95]
	v_mfma_f32_32x32x16_bf16 v[64:79], v[192:195], v[220:223], v[64:79]
	v_mfma_f32_32x32x16_bf16 v[80:95], v[196:199], v[224:227], v[80:95]
	v_mfma_f32_32x32x16_bf16 v[64:79], v[200:203], v[224:227], v[64:79]
	v_mfma_f32_32x32x16_bf16 v[80:95], v[204:207], v[228:231], v[80:95]
	v_mfma_f32_32x32x16_bf16 v[64:79], v[208:211], v[228:231], v[64:79]
	v_mfma_f32_32x32x16_bf16 v[80:95], v[212:215], v[232:235], v[80:95]
	v_mfma_f32_32x32x16_bf16 v[64:79], v[216:219], v[232:235], v[64:79]
	s_barrier
	v_readfirstlane_b32 s66, v142
	v_lshl_add_u64 v[238:239], v[188:189], 0, s[24:25]
	s_mov_b32 m0, s66
	v_readfirstlane_b32 s66, v145
	ds_read_b128 v[184:187], v154 offset:16384
	ds_read_b128 v[192:195], v154 offset:20480
	ds_read_b128 v[196:199], v153 offset:16384
	ds_read_b128 v[200:203], v153 offset:20480
	ds_read_b128 v[204:207], v152 offset:16384
	ds_read_b128 v[208:211], v152 offset:20480
	ds_read_b128 v[212:215], v131 offset:16384
	ds_read_b128 v[216:219], v131 offset:20480
	global_load_lds_dwordx4 v[238:239], off
	v_lshl_add_u64 v[238:239], v[188:189], 0, s[26:27]
	s_mov_b32 m0, s66
	s_nop 0
	global_load_lds_dwordx4 v[238:239], off
	s_barrier
	s_waitcnt lgkmcnt(0)
	s_waitcnt lgkmcnt(0)
	v_mfma_f32_32x32x16_bf16 v[48:63], v[184:187], v[168:171], v[48:63]
	v_mfma_f32_32x32x16_bf16 v[32:47], v[192:195], v[168:171], v[32:47]
	v_mfma_f32_32x32x16_bf16 v[48:63], v[196:199], v[172:175], v[48:63]
	v_mfma_f32_32x32x16_bf16 v[32:47], v[200:203], v[172:175], v[32:47]
	v_mfma_f32_32x32x16_bf16 v[48:63], v[204:207], v[176:179], v[48:63]
	v_mfma_f32_32x32x16_bf16 v[32:47], v[208:211], v[176:179], v[32:47]
	v_mfma_f32_32x32x16_bf16 v[48:63], v[212:215], v[180:183], v[48:63]
	v_mfma_f32_32x32x16_bf16 v[32:47], v[216:219], v[180:183], v[32:47]
	s_barrier
	v_readfirstlane_b32 s66, v144
	v_lshl_add_u64 v[168:169], v[236:237], 0, s[28:29]
	s_mov_b32 m0, s66
	v_readfirstlane_b32 s66, v143
	global_load_lds_dwordx4 v[168:169], off
	v_lshl_add_u64 v[168:169], v[236:237], 0, s[30:31]
	s_mov_b32 m0, s66
	s_nop 0
	global_load_lds_dwordx4 v[168:169], off
	s_waitcnt vmcnt(6)
	s_barrier
	v_mfma_f32_32x32x16_bf16 v[16:31], v[184:187], v[220:223], v[16:31]
	v_mfma_f32_32x32x16_bf16 v[0:15], v[192:195], v[220:223], v[0:15]
	v_mfma_f32_32x32x16_bf16 v[16:31], v[196:199], v[224:227], v[16:31]
	v_mfma_f32_32x32x16_bf16 v[0:15], v[200:203], v[224:227], v[0:15]
	v_mfma_f32_32x32x16_bf16 v[16:31], v[204:207], v[228:231], v[16:31]
	v_mfma_f32_32x32x16_bf16 v[0:15], v[208:211], v[228:231], v[0:15]
	v_mfma_f32_32x32x16_bf16 v[16:31], v[212:215], v[232:235], v[16:31]
	v_mfma_f32_32x32x16_bf16 v[0:15], v[216:219], v[232:235], v[0:15]
	s_barrier
	ds_read_b128 v[168:171], v155 offset:32768
	ds_read_b128 v[172:175], v156 offset:32768
	ds_read_b128 v[176:179], v157 offset:32768
	ds_read_b128 v[180:183], v158 offset:32768
	v_readfirstlane_b32 s66, v141
	v_lshl_add_u64 v[220:221], v[188:189], 0, s[36:37]
	s_mov_b32 m0, s66
	v_readfirstlane_b32 s66, v140
	ds_read_b128 v[184:187], v154 offset:32768
	ds_read_b128 v[192:195], v154 offset:36864
	ds_read_b128 v[196:199], v153 offset:32768
	ds_read_b128 v[200:203], v153 offset:36864
	ds_read_b128 v[204:207], v152 offset:32768
	ds_read_b128 v[208:211], v152 offset:36864
	ds_read_b128 v[212:215], v131 offset:32768
	ds_read_b128 v[216:219], v131 offset:36864
	global_load_lds_dwordx4 v[220:221], off
	v_lshl_add_u64 v[220:221], v[188:189], 0, s[38:39]
	s_mov_b32 m0, s66
	s_nop 0
	global_load_lds_dwordx4 v[220:221], off
	s_waitcnt lgkmcnt(8)
	s_barrier
; #define G8_STA(b, h, kt) G8_STAGE(G8_SA(b, h), Ag, lda, h, kt)
; #define G8_STB(b, h, kt) G8_STAGE(G8_SB(b, h), Bg, ldb, h, kt)
; #define G8_LDA(b, h) do { _Pragma("unroll") for (int m_ = 0; m_ < 2; ++m_) _Pragma("unroll") for (int k_ = 0; k_ < 4; ++k_) \
;     At[m_][k_] = *reinterpret_cast<const LAS bf16x8*>(la + ((b) * 2 + (h)) * 16384 + m_ * 4096 + (((k_ * 2 + hi) ^ swz) << 4)); } while (0)
; #define G8_LDB(dst, b, h) do { _Pragma("unroll") for (int k_ = 0; k_ < 4; ++k_) \
;     dst[k_] = *reinterpret_cast<const LAS bf16x8*>(lb + ((b) * 2 + (h)) * 16384 + (((k_ * 2 + hi) ^ swz) << 4)); } while (0)
; #define G8_MMA(ai, bj, Bx) do { __builtin_amdgcn_s_setprio(1); _Pragma("unroll") for (int k_ = 0; k_ < 4; ++k_) _Pragma("unroll") for (int m_ = 0; m_ < 2; ++m_) \
;     acc[ai][bj][m_] = __builtin_amdgcn_mfma_f32_32x32x16_bf16(At[m_][k_], Bx[k_], acc[ai][bj][m_], 0, 0, 0); __builtin_amdgcn_s_setprio(0); } while (0)
; #define G8_WV(n) asm volatile("s_waitcnt vmcnt(" #n ")" ::: "memory")
; #define G8_WL(n) asm volatile("s_waitcnt lgkmcnt(" #n ")" ::: "memory")
; #define G8_BAR __builtin_amdgcn_s_barrier()
; #define G8_SCHED __builtin_amdgcn_sched_barrier(0)
; template <class Epi>
; __device__ __forceinline__ void gemm8p(const bf16_t* __restrict__ A, int lda, const bf16_t* __restrict__ Bt, int ldb, int K,
;                                        LP lds, const Epi& epi, bool pre = false, const bf16_t* An = nullptr, const bf16_t* Bn = nullptr) {
;     ...
;     G8_WL(8); G8_BAR; G8_WL(0); G8_MMA(0, 0, B0); G8_BAR; G8_SCHED;
;     G8_LDB(B1, 1, 1); G8_STB(1, 0, t + 3);
;     G8_BAR; G8_WL(0); G8_MMA(0, 1, B1); G8_BAR; G8_SCHED;
;     G8_LDA(1, 1); G8_STA(1, 0, t + 3);
;     G8_BAR; G8_WL(0); G8_MMA(1, 0, B0); G8_BAR; G8_SCHED;
;     G8_STB(1, 1, t + 3);
;     G8_WV(6); G8_BAR; G8_MMA(1, 1, B1); G8_BAR; G8_SCHED;
;   }
;   { G8_LDB(B0, 0, 0); G8_LDA(0, 0); G8_STA(1, 1, nt - 1);
;     G8_BAR; G8_WL(0); G8_MMA(0, 0, B0); G8_BAR; G8_SCHED;
;     G8_LDB(B1, 0, 1); G8_BAR; G8_WL(0); G8_MMA(0, 1, B1); G8_BAR; G8_SCHED;
	s_waitcnt lgkmcnt(0)
	s_waitcnt lgkmcnt(0)
	v_mfma_f32_32x32x16_bf16 v[112:127], v[184:187], v[168:171], v[112:127]
	v_mfma_f32_32x32x16_bf16 v[96:111], v[192:195], v[168:171], v[96:111]
	v_mfma_f32_32x32x16_bf16 v[112:127], v[196:199], v[172:175], v[112:127]
	v_mfma_f32_32x32x16_bf16 v[96:111], v[200:203], v[172:175], v[96:111]
	v_mfma_f32_32x32x16_bf16 v[112:127], v[204:207], v[176:179], v[112:127]
	v_mfma_f32_32x32x16_bf16 v[96:111], v[208:211], v[176:179], v[96:111]
	v_mfma_f32_32x32x16_bf16 v[112:127], v[212:215], v[180:183], v[112:127]
	v_mfma_f32_32x32x16_bf16 v[96:111], v[216:219], v[180:183], v[96:111]
	s_barrier
	v_readfirstlane_b32 s66, v159
	v_lshl_add_u64 v[238:239], v[236:237], 0, s[40:41]
	s_mov_b32 m0, s66
	v_readfirstlane_b32 s66, v160
	ds_read_b128 v[220:223], v155 offset:49152
	ds_read_b128 v[224:227], v156 offset:49152
	ds_read_b128 v[228:231], v157 offset:49152
	ds_read_b128 v[232:235], v158 offset:49152
	global_load_lds_dwordx4 v[238:239], off
	v_lshl_add_u64 v[238:239], v[236:237], 0, s[42:43]
	s_mov_b32 m0, s66
	s_nop 0
	global_load_lds_dwordx4 v[238:239], off
	s_barrier
	s_waitcnt lgkmcnt(0)
	s_waitcnt lgkmcnt(0)
	v_mfma_f32_32x32x16_bf16 v[80:95], v[184:187], v[220:223], v[80:95]
	v_mfma_f32_32x32x16_bf16 v[64:79], v[192:195], v[220:223], v[64:79]
	v_mfma_f32_32x32x16_bf16 v[80:95], v[196:199], v[224:227], v[80:95]
	v_mfma_f32_32x32x16_bf16 v[64:79], v[200:203], v[224:227], v[64:79]
	v_mfma_f32_32x32x16_bf16 v[80:95], v[204:207], v[228:231], v[80:95]
	v_mfma_f32_32x32x16_bf16 v[64:79], v[208:211], v[228:231], v[64:79]
	v_mfma_f32_32x32x16_bf16 v[80:95], v[212:215], v[232:235], v[80:95]
	v_mfma_f32_32x32x16_bf16 v[64:79], v[216:219], v[232:235], v[64:79]
	s_barrier
	v_readfirstlane_b32 s66, v161
	v_lshl_add_u64 v[238:239], v[188:189], 0, s[44:45]
	s_mov_b32 m0, s66
	v_readfirstlane_b32 s66, v162
	ds_read_b128 v[184:187], v154 offset:49152
	ds_read_b128 v[192:195], v154 offset:53248
	ds_read_b128 v[196:199], v153 offset:49152
	ds_read_b128 v[200:203], v153 offset:53248
	ds_read_b128 v[204:207], v152 offset:49152
	ds_read_b128 v[208:211], v152 offset:53248
	ds_read_b128 v[212:215], v131 offset:49152
	ds_read_b128 v[216:219], v131 offset:53248
	global_load_lds_dwordx4 v[238:239], off
	v_lshl_add_u64 v[188:189], v[188:189], 0, s[46:47]
	s_mov_b32 m0, s66
	s_nop 0
	global_load_lds_dwordx4 v[188:189], off
	s_barrier
	s_waitcnt lgkmcnt(0)
	s_waitcnt lgkmcnt(0)
	v_mfma_f32_32x32x16_bf16 v[48:63], v[184:187], v[168:171], v[48:63]
	v_mfma_f32_32x32x16_bf16 v[32:47], v[192:195], v[168:171], v[32:47]
	v_mfma_f32_32x32x16_bf16 v[48:63], v[196:199], v[172:175], v[48:63]
	v_mfma_f32_32x32x16_bf16 v[32:47], v[200:203], v[172:175], v[32:47]
	v_mfma_f32_32x32x16_bf16 v[48:63], v[204:207], v[176:179], v[48:63]
	v_mfma_f32_32x32x16_bf16 v[32:47], v[208:211], v[176:179], v[32:47]
	v_mfma_f32_32x32x16_bf16 v[48:63], v[212:215], v[180:183], v[48:63]
	v_mfma_f32_32x32x16_bf16 v[32:47], v[216:219], v[180:183], v[32:47]
	s_barrier
	v_readfirstlane_b32 s66, v163
	v_lshl_add_u64 v[168:169], v[236:237], 0, s[48:49]
	s_mov_b32 m0, s66
	v_readfirstlane_b32 s66, v164
	global_load_lds_dwordx4 v[168:169], off
	v_lshl_add_u64 v[168:169], v[236:237], 0, s[50:51]
	s_mov_b32 m0, s66
	s_nop 0
	global_load_lds_dwordx4 v[168:169], off
	s_waitcnt vmcnt(6)
	s_barrier
	v_mfma_f32_32x32x16_bf16 v[16:31], v[184:187], v[220:223], v[16:31]
	v_mfma_f32_32x32x16_bf16 v[0:15], v[192:195], v[220:223], v[0:15]
	v_mfma_f32_32x32x16_bf16 v[16:31], v[196:199], v[224:227], v[16:31]
	v_mfma_f32_32x32x16_bf16 v[0:15], v[200:203], v[224:227], v[0:15]
	v_mfma_f32_32x32x16_bf16 v[16:31], v[204:207], v[228:231], v[16:31]
	v_mfma_f32_32x32x16_bf16 v[0:15], v[208:211], v[228:231], v[0:15]
	v_mfma_f32_32x32x16_bf16 v[16:31], v[212:215], v[232:235], v[16:31]
	v_mfma_f32_32x32x16_bf16 v[0:15], v[216:219], v[232:235], v[0:15]
	s_barrier
	s_add_i32 s61, s61, 2
	v_lshl_add_u64 v[136:137], v[136:137], 0, s[52:53]
	s_cmp_lt_u32 s61, 12
	v_lshl_add_u64 v[138:139], v[138:139], 0, s[52:53]
	s_cbranch_scc1 .LBB0_1759
	v_readfirstlane_b32 s61, v166
	v_lshl_add_u64 v[188:189], v[134:135], 0, s[54:55]
	s_mov_b32 m0, s61
	v_readfirstlane_b32 s61, v165
	ds_read_b128 v[136:139], v155
	ds_read_b128 v[160:163], v156
	ds_read_b128 v[168:171], v157
	ds_read_b128 v[172:175], v158
	ds_read_b128 v[176:179], v154
	ds_read_b128 v[180:183], v154 offset:4096
	ds_read_b128 v[184:187], v153
	ds_read_b128 v[192:195], v153 offset:4096
	ds_read_b128 v[196:199], v152
	ds_read_b128 v[200:203], v152 offset:4096
	ds_read_b128 v[204:207], v131
	ds_read_b128 v[208:211], v131 offset:4096
	global_load_lds_dwordx4 v[188:189], off
	v_lshl_add_u64 v[134:135], v[134:135], 0, s[56:57]
	s_mov_b32 m0, s61
	s_nop 0
	global_load_lds_dwordx4 v[134:135], off
	s_barrier
	s_waitcnt lgkmcnt(0)
	s_waitcnt lgkmcnt(0)
	v_mfma_f32_32x32x16_bf16 v[112:127], v[176:179], v[136:139], v[112:127]
	v_mfma_f32_32x32x16_bf16 v[96:111], v[180:183], v[136:139], v[96:111]
	v_mfma_f32_32x32x16_bf16 v[112:127], v[184:187], v[160:163], v[112:127]
	v_mfma_f32_32x32x16_bf16 v[96:111], v[192:195], v[160:163], v[96:111]
	v_mfma_f32_32x32x16_bf16 v[112:127], v[196:199], v[168:171], v[112:127]
	v_mfma_f32_32x32x16_bf16 v[96:111], v[200:203], v[168:171], v[96:111]
	v_mfma_f32_32x32x16_bf16 v[112:127], v[204:207], v[172:175], v[112:127]
	v_mfma_f32_32x32x16_bf16 v[96:111], v[208:211], v[172:175], v[96:111]
	s_barrier
	ds_read_b128 v[164:167], v155 offset:16384
	ds_read_b128 v[212:215], v156 offset:16384
	ds_read_b128 v[216:219], v157 offset:16384
	ds_read_b128 v[220:223], v158 offset:16384
	s_barrier
; #define G8_LDA(b, h) do { _Pragma("unroll") for (int m_ = 0; m_ < 2; ++m_) _Pragma("unroll") for (int k_ = 0; k_ < 4; ++k_) \
;     At[m_][k_] = *reinterpret_cast<const LAS bf16x8*>(la + ((b) * 2 + (h)) * 16384 + m_ * 4096 + (((k_ * 2 + hi) ^ swz) << 4)); } while (0)
; #define G8_LDB(dst, b, h) do { _Pragma("unroll") for (int k_ = 0; k_ < 4; ++k_) \
;     dst[k_] = *reinterpret_cast<const LAS bf16x8*>(lb + ((b) * 2 + (h)) * 16384 + (((k_ * 2 + hi) ^ swz) << 4)); } while (0)
; #define G8_MMA(ai, bj, Bx) do { __builtin_amdgcn_s_setprio(1); _Pragma("unroll") for (int k_ = 0; k_ < 4; ++k_) _Pragma("unroll") for (int m_ = 0; m_ < 2; ++m_) \
;     acc[ai][bj][m_] = __builtin_amdgcn_mfma_f32_32x32x16_bf16(At[m_][k_], Bx[k_], acc[ai][bj][m_], 0, 0, 0); __builtin_amdgcn_s_setprio(0); } while (0)
; #define G8_WV(n) asm volatile("s_waitcnt vmcnt(" #n ")" ::: "memory")
; #define G8_WL(n) asm volatile("s_waitcnt lgkmcnt(" #n ")" ::: "memory")
; #define G8_BAR __builtin_amdgcn_s_barrier()
; #define G8_SCHED __builtin_amdgcn_sched_barrier(0)
; template <class Epi>
; __device__ __forceinline__ void gemm8p(const bf16_t* __restrict__ A, int lda, const bf16_t* __restrict__ Bt, int ldb, int K,
;                                        LP lds, const Epi& epi, bool pre = false, const bf16_t* An = nullptr, const bf16_t* Bn = nullptr) {
;     ...
;     G8_LDB(B1, 0, 1); G8_BAR; G8_WL(0); G8_MMA(0, 1, B1); G8_BAR; G8_SCHED;
;     G8_LDA(0, 1); G8_WV(4); G8_BAR; G8_WL(0); G8_MMA(1, 0, B0); G8_MMA(1, 1, B1); G8_BAR; G8_SCHED; }
;   { G8_LDB(B0, 1, 0); G8_LDA(1, 0); G8_WV(2); G8_BAR; G8_WL(0); G8_MMA(0, 0, B0); G8_BAR; G8_SCHED;
;     G8_LDB(B1, 1, 1); G8_WV(0); G8_BAR; G8_WL(0); G8_MMA(0, 1, B1); G8_BAR; G8_SCHED;
;     G8_LDA(1, 1); G8_BAR; G8_WL(0); G8_MMA(1, 0, B0); G8_MMA(1, 1, B1); G8_BAR; G8_SCHED; }
;   if (wr == 0) G8_BAR;
	s_waitcnt lgkmcnt(0)
	s_waitcnt lgkmcnt(0)
	v_mfma_f32_32x32x16_bf16 v[80:95], v[176:179], v[164:167], v[80:95]
	v_mfma_f32_32x32x16_bf16 v[64:79], v[180:183], v[164:167], v[64:79]
	v_mfma_f32_32x32x16_bf16 v[80:95], v[184:187], v[212:215], v[80:95]
	v_mfma_f32_32x32x16_bf16 v[64:79], v[192:195], v[212:215], v[64:79]
	v_mfma_f32_32x32x16_bf16 v[80:95], v[196:199], v[216:219], v[80:95]
	v_mfma_f32_32x32x16_bf16 v[64:79], v[200:203], v[216:219], v[64:79]
	v_mfma_f32_32x32x16_bf16 v[80:95], v[204:207], v[220:223], v[80:95]
	v_mfma_f32_32x32x16_bf16 v[64:79], v[208:211], v[220:223], v[64:79]
	s_barrier
	ds_read_b128 v[176:179], v154 offset:16384
	ds_read_b128 v[180:183], v154 offset:20480
	ds_read_b128 v[184:187], v153 offset:16384
	ds_read_b128 v[192:195], v153 offset:20480
	ds_read_b128 v[196:199], v152 offset:16384
	ds_read_b128 v[200:203], v152 offset:20480
	ds_read_b128 v[204:207], v131 offset:16384
	ds_read_b128 v[208:211], v131 offset:20480
	s_waitcnt vmcnt(4)
	s_barrier
	s_waitcnt lgkmcnt(0)
	s_waitcnt lgkmcnt(0)
	v_mfma_f32_32x32x16_bf16 v[48:63], v[176:179], v[136:139], v[48:63]
	v_mfma_f32_32x32x16_bf16 v[32:47], v[180:183], v[136:139], v[32:47]
	v_mfma_f32_32x32x16_bf16 v[48:63], v[184:187], v[160:163], v[48:63]
	v_mfma_f32_32x32x16_bf16 v[32:47], v[192:195], v[160:163], v[32:47]
	v_mfma_f32_32x32x16_bf16 v[48:63], v[196:199], v[168:171], v[48:63]
	v_mfma_f32_32x32x16_bf16 v[32:47], v[200:203], v[168:171], v[32:47]
	v_mfma_f32_32x32x16_bf16 v[48:63], v[204:207], v[172:175], v[48:63]
	v_mfma_f32_32x32x16_bf16 v[32:47], v[208:211], v[172:175], v[32:47]
	v_mfma_f32_32x32x16_bf16 v[16:31], v[176:179], v[164:167], v[16:31]
	v_mfma_f32_32x32x16_bf16 v[0:15], v[180:183], v[164:167], v[0:15]
	v_mfma_f32_32x32x16_bf16 v[16:31], v[184:187], v[212:215], v[16:31]
	v_mfma_f32_32x32x16_bf16 v[0:15], v[192:195], v[212:215], v[0:15]
	v_mfma_f32_32x32x16_bf16 v[16:31], v[196:199], v[216:219], v[16:31]
	v_mfma_f32_32x32x16_bf16 v[0:15], v[200:203], v[216:219], v[0:15]
	v_mfma_f32_32x32x16_bf16 v[16:31], v[204:207], v[220:223], v[16:31]
	v_mfma_f32_32x32x16_bf16 v[0:15], v[208:211], v[220:223], v[0:15]
	s_barrier
	ds_read_b128 v[134:137], v155 offset:32768
	ds_read_b128 v[160:163], v156 offset:32768
	ds_read_b128 v[164:167], v157 offset:32768
	ds_read_b128 v[168:171], v158 offset:32768
	ds_read_b128 v[172:175], v154 offset:32768
	ds_read_b128 v[176:179], v154 offset:36864
	ds_read_b128 v[180:183], v153 offset:32768
	ds_read_b128 v[184:187], v153 offset:36864
	ds_read_b128 v[192:195], v152 offset:32768
	ds_read_b128 v[196:199], v152 offset:36864
	ds_read_b128 v[200:203], v131 offset:32768
	ds_read_b128 v[204:207], v131 offset:36864
	s_waitcnt vmcnt(2)
	s_barrier
	s_waitcnt lgkmcnt(0)
	s_waitcnt lgkmcnt(0)
	v_mfma_f32_32x32x16_bf16 v[112:127], v[172:175], v[134:137], v[112:127]
	v_mfma_f32_32x32x16_bf16 v[96:111], v[176:179], v[134:137], v[96:111]
	v_mfma_f32_32x32x16_bf16 v[112:127], v[180:183], v[160:163], v[112:127]
	v_mfma_f32_32x32x16_bf16 v[96:111], v[184:187], v[160:163], v[96:111]
	v_mfma_f32_32x32x16_bf16 v[112:127], v[192:195], v[164:167], v[112:127]
	v_mfma_f32_32x32x16_bf16 v[96:111], v[196:199], v[164:167], v[96:111]
	v_mfma_f32_32x32x16_bf16 v[112:127], v[200:203], v[168:171], v[112:127]
	v_mfma_f32_32x32x16_bf16 v[96:111], v[204:207], v[168:171], v[96:111]
	s_barrier
	ds_read_b128 v[208:211], v155 offset:49152
	ds_read_b128 v[212:215], v156 offset:49152
	ds_read_b128 v[216:219], v157 offset:49152
	ds_read_b128 v[156:159], v158 offset:49152
	s_waitcnt vmcnt(0)
	s_barrier
	s_waitcnt lgkmcnt(0)
	s_waitcnt lgkmcnt(0)
	v_mfma_f32_32x32x16_bf16 v[80:95], v[172:175], v[208:211], v[80:95]
	v_mfma_f32_32x32x16_bf16 v[64:79], v[176:179], v[208:211], v[64:79]
	v_mfma_f32_32x32x16_bf16 v[80:95], v[180:183], v[212:215], v[80:95]
	v_mfma_f32_32x32x16_bf16 v[64:79], v[184:187], v[212:215], v[64:79]
	v_mfma_f32_32x32x16_bf16 v[80:95], v[192:195], v[216:219], v[80:95]
	v_mfma_f32_32x32x16_bf16 v[64:79], v[196:199], v[216:219], v[64:79]
	v_mfma_f32_32x32x16_bf16 v[80:95], v[200:203], v[156:159], v[80:95]
	v_mfma_f32_32x32x16_bf16 v[64:79], v[204:207], v[156:159], v[64:79]
	s_barrier
	ds_read_b128 v[172:175], v154 offset:49152
	ds_read_b128 v[176:179], v154 offset:53248
	ds_read_b128 v[180:183], v153 offset:49152
	ds_read_b128 v[184:187], v153 offset:53248
	ds_read_b128 v[192:195], v152 offset:49152
	ds_read_b128 v[152:155], v152 offset:53248
	ds_read_b128 v[196:199], v131 offset:49152
	ds_read_b128 v[200:203], v131 offset:53248
	s_barrier
	s_waitcnt lgkmcnt(0)
	s_waitcnt lgkmcnt(0)
	v_mfma_f32_32x32x16_bf16 v[48:63], v[172:175], v[134:137], v[48:63]
	v_mfma_f32_32x32x16_bf16 v[32:47], v[176:179], v[134:137], v[32:47]
	v_mfma_f32_32x32x16_bf16 v[48:63], v[180:183], v[160:163], v[48:63]
	v_mfma_f32_32x32x16_bf16 v[32:47], v[184:187], v[160:163], v[32:47]
	v_mfma_f32_32x32x16_bf16 v[48:63], v[192:195], v[164:167], v[48:63]
	v_mfma_f32_32x32x16_bf16 v[32:47], v[152:155], v[164:167], v[32:47]
	v_mfma_f32_32x32x16_bf16 v[48:63], v[196:199], v[168:171], v[48:63]
	v_mfma_f32_32x32x16_bf16 v[32:47], v[200:203], v[168:171], v[32:47]
	v_mfma_f32_32x32x16_bf16 v[16:31], v[172:175], v[208:211], v[16:31]
	v_mfma_f32_32x32x16_bf16 v[0:15], v[176:179], v[208:211], v[0:15]
	v_mfma_f32_32x32x16_bf16 v[16:31], v[180:183], v[212:215], v[16:31]
	v_mfma_f32_32x32x16_bf16 v[0:15], v[184:187], v[212:215], v[0:15]
	v_mfma_f32_32x32x16_bf16 v[16:31], v[192:195], v[216:219], v[16:31]
	v_mfma_f32_32x32x16_bf16 v[0:15], v[152:155], v[216:219], v[0:15]
	v_mfma_f32_32x32x16_bf16 v[16:31], v[196:199], v[156:159], v[16:31]
	v_mfma_f32_32x32x16_bf16 v[0:15], v[200:203], v[156:159], v[0:15]
	s_barrier
	v_cmp_gt_u32_e32 vcc, s77, v148
	s_and_saveexec_b64 s[66:67], vcc
	s_cbranch_execz .LBB0_1762
	s_barrier

; #define G8_STA(b, h, kt) G8_STAGE(G8_SA(b, h), Ag, lda, h, kt)
; #define G8_STB(b, h, kt) G8_STAGE(G8_SB(b, h), Bg, ldb, h, kt)
; #define G8_LDA(b, h) do { _Pragma("unroll") for (int m_ = 0; m_ < 2; ++m_) _Pragma("unroll") for (int k_ = 0; k_ < 4; ++k_) \
;     At[m_][k_] = *reinterpret_cast<const LAS bf16x8*>(la + ((b) * 2 + (h)) * 16384 + m_ * 4096 + (((k_ * 2 + hi) ^ swz) << 4)); } while (0)
; #define G8_LDB(dst, b, h) do { _Pragma("unroll") for (int k_ = 0; k_ < 4; ++k_) \
;     dst[k_] = *reinterpret_cast<const LAS bf16x8*>(lb + ((b) * 2 + (h)) * 16384 + (((k_ * 2 + hi) ^ swz) << 4)); } while (0)
; #define G8_MMA(ai, bj, Bx) do { __builtin_amdgcn_s_setprio(1); _Pragma("unroll") for (int k_ = 0; k_ < 4; ++k_) _Pragma("unroll") for (int m_ = 0; m_ < 2; ++m_) \
;     acc[ai][bj][m_] = __builtin_amdgcn_mfma_f32_32x32x16_bf16(At[m_][k_], Bx[k_], acc[ai][bj][m_], 0, 0, 0); __builtin_amdgcn_s_setprio(0); } while (0)
; #define G8_WV(n) asm volatile("s_waitcnt vmcnt(" #n ")" ::: "memory")
; #define G8_WL(n) asm volatile("s_waitcnt lgkmcnt(" #n ")" ::: "memory")
; #define G8_BAR __builtin_amdgcn_s_barrier()
; #define G8_SCHED __builtin_amdgcn_sched_barrier(0)
; template <class Epi>
; __device__ __forceinline__ void gemm8p(const bf16_t* __restrict__ A, int lda, const bf16_t* __restrict__ Bt, int ldb, int K,
;                                        LP lds, const Epi& epi, bool pre = false, const bf16_t* An = nullptr, const bf16_t* Bn = nullptr) {
;     ...
;     G8_LDB(B0, 0, 0); G8_SCHED; G8_LDA(0, 0); G8_STA(1, 1, t + 1);
;     G8_WL(8); G8_BAR; G8_WL(0); G8_MMA(0, 0, B0); G8_BAR; G8_SCHED;
;     G8_LDB(B1, 0, 1); G8_STB(0, 0, t + 2);
;     G8_BAR; G8_WL(0); G8_MMA(0, 1, B1); G8_BAR; G8_SCHED;
;     G8_LDA(0, 1); G8_STA(0, 0, t + 2);
;     G8_BAR; G8_WL(0); G8_MMA(1, 0, B0); G8_BAR; G8_SCHED;
;     G8_STB(0, 1, t + 2);
;     G8_WV(6); G8_BAR; G8_MMA(1, 1, B1); G8_BAR; G8_SCHED;
;     G8_LDB(B0, 1, 0); G8_SCHED; G8_LDA(1, 0); G8_STA(0, 1, t + 2);
.LBB0_1826:
	ds_read_b128 v[168:171], v155
	ds_read_b128 v[172:175], v156
	ds_read_b128 v[176:179], v157
	ds_read_b128 v[180:183], v158
	v_lshl_add_u64 v[188:189], v[138:139], 0, v[128:129]
	s_mov_b64 s[66:67], 0x7d76080
	v_lshl_add_u64 v[220:221], v[188:189], 0, s[66:67]
	v_readfirstlane_b32 s66, v166
	s_mov_b32 m0, s66
	s_mov_b64 s[66:67], 0x7df6080
	ds_read_b128 v[184:187], v154
	ds_read_b128 v[192:195], v154 offset:4096
	ds_read_b128 v[196:199], v153
	ds_read_b128 v[200:203], v153 offset:4096
	ds_read_b128 v[204:207], v152
	ds_read_b128 v[208:211], v152 offset:4096
	ds_read_b128 v[212:215], v131
	ds_read_b128 v[216:219], v131 offset:4096
	global_load_lds_dwordx4 v[220:221], off
	v_lshl_add_u64 v[220:221], v[188:189], 0, s[66:67]
	v_readfirstlane_b32 s66, v165
	s_mov_b32 m0, s66
	s_nop 0
	global_load_lds_dwordx4 v[220:221], off
	s_waitcnt lgkmcnt(8)
	s_barrier
	s_waitcnt lgkmcnt(0)
	s_waitcnt lgkmcnt(0)
	v_mfma_f32_32x32x16_bf16 v[112:127], v[184:187], v[168:171], v[112:127]
	v_mfma_f32_32x32x16_bf16 v[96:111], v[192:195], v[168:171], v[96:111]
	v_mfma_f32_32x32x16_bf16 v[112:127], v[196:199], v[172:175], v[112:127]
	v_mfma_f32_32x32x16_bf16 v[96:111], v[200:203], v[172:175], v[96:111]
	v_mfma_f32_32x32x16_bf16 v[112:127], v[204:207], v[176:179], v[112:127]
	v_mfma_f32_32x32x16_bf16 v[96:111], v[208:211], v[176:179], v[96:111]
	v_mfma_f32_32x32x16_bf16 v[112:127], v[212:215], v[180:183], v[112:127]
	v_mfma_f32_32x32x16_bf16 v[96:111], v[216:219], v[180:183], v[96:111]
	s_barrier
	v_lshl_add_u64 v[236:237], v[136:137], 0, v[128:129]
	v_readfirstlane_b32 s66, v147
	v_lshl_add_u64 v[238:239], v[236:237], 0, s[18:19]
	s_mov_b32 m0, s66
	v_readfirstlane_b32 s66, v146
	ds_read_b128 v[220:223], v155 offset:16384
	ds_read_b128 v[224:227], v156 offset:16384
	ds_read_b128 v[228:231], v157 offset:16384
	ds_read_b128 v[232:235], v158 offset:16384
	global_load_lds_dwordx4 v[238:239], off
	v_lshl_add_u64 v[238:239], v[236:237], 0, s[20:21]
	s_mov_b32 m0, s66
	s_nop 0
	global_load_lds_dwordx4 v[238:239], off
	s_barrier
	s_waitcnt lgkmcnt(0)
	s_waitcnt lgkmcnt(0)
	v_mfma_f32_32x32x16_bf16 v[80:95], v[184:187], v[220:223], v[80:95]
	v_mfma_f32_32x32x16_bf16 v[64:79], v[192:195], v[220:223], v[64:79]
	v_mfma_f32_32x32x16_bf16 v[80:95], v[196:199], v[224:227], v[80:95]
	v_mfma_f32_32x32x16_bf16 v[64:79], v[200:203], v[224:227], v[64:79]
	v_mfma_f32_32x32x16_bf16 v[80:95], v[204:207], v[228:231], v[80:95]
	v_mfma_f32_32x32x16_bf16 v[64:79], v[208:211], v[228:231], v[64:79]
	v_mfma_f32_32x32x16_bf16 v[80:95], v[212:215], v[232:235], v[80:95]
	v_mfma_f32_32x32x16_bf16 v[64:79], v[216:219], v[232:235], v[64:79]
	s_barrier
	v_readfirstlane_b32 s66, v142
	v_lshl_add_u64 v[238:239], v[188:189], 0, s[22:23]
	s_mov_b32 m0, s66
	v_readfirstlane_b32 s66, v145
	ds_read_b128 v[184:187], v154 offset:16384
	ds_read_b128 v[192:195], v154 offset:20480
	ds_read_b128 v[196:199], v153 offset:16384
	ds_read_b128 v[200:203], v153 offset:20480
	ds_read_b128 v[204:207], v152 offset:16384
	ds_read_b128 v[208:211], v152 offset:20480
	ds_read_b128 v[212:215], v131 offset:16384
	ds_read_b128 v[216:219], v131 offset:20480
	global_load_lds_dwordx4 v[238:239], off
	v_lshl_add_u64 v[238:239], v[188:189], 0, s[24:25]
	s_mov_b32 m0, s66
	s_nop 0
	global_load_lds_dwordx4 v[238:239], off
	s_barrier
	s_waitcnt lgkmcnt(0)
	s_waitcnt lgkmcnt(0)
	v_mfma_f32_32x32x16_bf16 v[48:63], v[184:187], v[168:171], v[48:63]
	v_mfma_f32_32x32x16_bf16 v[32:47], v[192:195], v[168:171], v[32:47]
	v_mfma_f32_32x32x16_bf16 v[48:63], v[196:199], v[172:175], v[48:63]
	v_mfma_f32_32x32x16_bf16 v[32:47], v[200:203], v[172:175], v[32:47]
	v_mfma_f32_32x32x16_bf16 v[48:63], v[204:207], v[176:179], v[48:63]
	v_mfma_f32_32x32x16_bf16 v[32:47], v[208:211], v[176:179], v[32:47]
	v_mfma_f32_32x32x16_bf16 v[48:63], v[212:215], v[180:183], v[48:63]
	v_mfma_f32_32x32x16_bf16 v[32:47], v[216:219], v[180:183], v[32:47]
	s_barrier
	v_readfirstlane_b32 s66, v144
	v_lshl_add_u64 v[168:169], v[236:237], 0, s[26:27]
	s_mov_b32 m0, s66
	v_readfirstlane_b32 s66, v143
	global_load_lds_dwordx4 v[168:169], off
	v_lshl_add_u64 v[168:169], v[236:237], 0, s[28:29]
	s_mov_b32 m0, s66
	s_nop 0
	global_load_lds_dwordx4 v[168:169], off
	s_waitcnt vmcnt(6)
	s_barrier
	v_mfma_f32_32x32x16_bf16 v[16:31], v[184:187], v[220:223], v[16:31]
	v_mfma_f32_32x32x16_bf16 v[0:15], v[192:195], v[220:223], v[0:15]
	v_mfma_f32_32x32x16_bf16 v[16:31], v[196:199], v[224:227], v[16:31]
	v_mfma_f32_32x32x16_bf16 v[0:15], v[200:203], v[224:227], v[0:15]
	v_mfma_f32_32x32x16_bf16 v[16:31], v[204:207], v[228:231], v[16:31]
	v_mfma_f32_32x32x16_bf16 v[0:15], v[208:211], v[228:231], v[0:15]
	v_mfma_f32_32x32x16_bf16 v[16:31], v[212:215], v[232:235], v[16:31]
	v_mfma_f32_32x32x16_bf16 v[0:15], v[216:219], v[232:235], v[0:15]
	s_barrier
	ds_read_b128 v[168:171], v155 offset:32768
	ds_read_b128 v[172:175], v156 offset:32768
	ds_read_b128 v[176:179], v157 offset:32768
	ds_read_b128 v[180:183], v158 offset:32768
	v_readfirstlane_b32 s66, v141
	v_lshl_add_u64 v[220:221], v[188:189], 0, s[30:31]
	s_mov_b32 m0, s66
	v_readfirstlane_b32 s66, v140
	ds_read_b128 v[184:187], v154 offset:32768
	ds_read_b128 v[192:195], v154 offset:36864
	ds_read_b128 v[196:199], v153 offset:32768
	ds_read_b128 v[200:203], v153 offset:36864
	ds_read_b128 v[204:207], v152 offset:32768
	ds_read_b128 v[208:211], v152 offset:36864
	ds_read_b128 v[212:215], v131 offset:32768
	ds_read_b128 v[216:219], v131 offset:36864
	global_load_lds_dwordx4 v[220:221], off
	v_lshl_add_u64 v[220:221], v[188:189], 0, s[36:37]
	s_mov_b32 m0, s66
	s_nop 0
	global_load_lds_dwordx4 v[220:221], off
	s_waitcnt lgkmcnt(8)
	s_barrier
; #define G8_STA(b, h, kt) G8_STAGE(G8_SA(b, h), Ag, lda, h, kt)
; #define G8_STB(b, h, kt) G8_STAGE(G8_SB(b, h), Bg, ldb, h, kt)
; #define G8_LDA(b, h) do { _Pragma("unroll") for (int m_ = 0; m_ < 2; ++m_) _Pragma("unroll") for (int k_ = 0; k_ < 4; ++k_) \
;     At[m_][k_] = *reinterpret_cast<const LAS bf16x8*>(la + ((b) * 2 + (h)) * 16384 + m_ * 4096 + (((k_ * 2 + hi) ^ swz) << 4)); } while (0)
; #define G8_LDB(dst, b, h) do { _Pragma("unroll") for (int k_ = 0; k_ < 4; ++k_) \
;     dst[k_] = *reinterpret_cast<const LAS bf16x8*>(lb + ((b) * 2 + (h)) * 16384 + (((k_ * 2 + hi) ^ swz) << 4)); } while (0)
; #define G8_MMA(ai, bj, Bx) do { __builtin_amdgcn_s_setprio(1); _Pragma("unroll") for (int k_ = 0; k_ < 4; ++k_) _Pragma("unroll") for (int m_ = 0; m_ < 2; ++m_) \
;     acc[ai][bj][m_] = __builtin_amdgcn_mfma_f32_32x32x16_bf16(At[m_][k_], Bx[k_], acc[ai][bj][m_], 0, 0, 0); __builtin_amdgcn_s_setprio(0); } while (0)
; #define G8_WV(n) asm volatile("s_waitcnt vmcnt(" #n ")" ::: "memory")
; #define G8_WL(n) asm volatile("s_waitcnt lgkmcnt(" #n ")" ::: "memory")
; #define G8_BAR __builtin_amdgcn_s_barrier()
; #define G8_SCHED __builtin_amdgcn_sched_barrier(0)
; template <class Epi>
; __device__ __forceinline__ void gemm8p(const bf16_t* __restrict__ A, int lda, const bf16_t* __restrict__ Bt, int ldb, int K,
;                                        LP lds, const Epi& epi, bool pre = false, const bf16_t* An = nullptr, const bf16_t* Bn = nullptr) {
;     ...
;     G8_WL(8); G8_BAR; G8_WL(0); G8_MMA(0, 0, B0); G8_BAR; G8_SCHED;
;     G8_LDB(B1, 1, 1); G8_STB(1, 0, t + 3);
;     G8_BAR; G8_WL(0); G8_MMA(0, 1, B1); G8_BAR; G8_SCHED;
;     G8_LDA(1, 1); G8_STA(1, 0, t + 3);
;     G8_BAR; G8_WL(0); G8_MMA(1, 0, B0); G8_BAR; G8_SCHED;
;     G8_STB(1, 1, t + 3);
;     G8_WV(6); G8_BAR; G8_MMA(1, 1, B1); G8_BAR; G8_SCHED;
;   }
;   { G8_LDB(B0, 0, 0); G8_LDA(0, 0); G8_STA(1, 1, nt - 1);
;     G8_BAR; G8_WL(0); G8_MMA(0, 0, B0); G8_BAR; G8_SCHED;
;     G8_LDB(B1, 0, 1); G8_BAR; G8_WL(0); G8_MMA(0, 1, B1); G8_BAR; G8_SCHED;
	s_waitcnt lgkmcnt(0)
	s_waitcnt lgkmcnt(0)
	v_mfma_f32_32x32x16_bf16 v[112:127], v[184:187], v[168:171], v[112:127]
	v_mfma_f32_32x32x16_bf16 v[96:111], v[192:195], v[168:171], v[96:111]
	v_mfma_f32_32x32x16_bf16 v[112:127], v[196:199], v[172:175], v[112:127]
	v_mfma_f32_32x32x16_bf16 v[96:111], v[200:203], v[172:175], v[96:111]
	v_mfma_f32_32x32x16_bf16 v[112:127], v[204:207], v[176:179], v[112:127]
	v_mfma_f32_32x32x16_bf16 v[96:111], v[208:211], v[176:179], v[96:111]
	v_mfma_f32_32x32x16_bf16 v[112:127], v[212:215], v[180:183], v[112:127]
	v_mfma_f32_32x32x16_bf16 v[96:111], v[216:219], v[180:183], v[96:111]
	s_barrier
	v_readfirstlane_b32 s66, v159
	v_lshl_add_u64 v[238:239], v[236:237], 0, s[38:39]
	s_mov_b32 m0, s66
	v_readfirstlane_b32 s66, v160
	ds_read_b128 v[220:223], v155 offset:49152
	ds_read_b128 v[224:227], v156 offset:49152
	ds_read_b128 v[228:231], v157 offset:49152
	ds_read_b128 v[232:235], v158 offset:49152
	global_load_lds_dwordx4 v[238:239], off
	v_lshl_add_u64 v[238:239], v[236:237], 0, s[40:41]
	s_mov_b32 m0, s66
	s_nop 0
	global_load_lds_dwordx4 v[238:239], off
	s_barrier
	s_waitcnt lgkmcnt(0)
	s_waitcnt lgkmcnt(0)
	v_mfma_f32_32x32x16_bf16 v[80:95], v[184:187], v[220:223], v[80:95]
	v_mfma_f32_32x32x16_bf16 v[64:79], v[192:195], v[220:223], v[64:79]
	v_mfma_f32_32x32x16_bf16 v[80:95], v[196:199], v[224:227], v[80:95]
	v_mfma_f32_32x32x16_bf16 v[64:79], v[200:203], v[224:227], v[64:79]
	v_mfma_f32_32x32x16_bf16 v[80:95], v[204:207], v[228:231], v[80:95]
	v_mfma_f32_32x32x16_bf16 v[64:79], v[208:211], v[228:231], v[64:79]
	v_mfma_f32_32x32x16_bf16 v[80:95], v[212:215], v[232:235], v[80:95]
	v_mfma_f32_32x32x16_bf16 v[64:79], v[216:219], v[232:235], v[64:79]
	s_barrier
	v_readfirstlane_b32 s66, v161
	v_lshl_add_u64 v[238:239], v[188:189], 0, s[42:43]
	s_mov_b32 m0, s66
	v_readfirstlane_b32 s66, v162
	ds_read_b128 v[184:187], v154 offset:49152
	ds_read_b128 v[192:195], v154 offset:53248
	ds_read_b128 v[196:199], v153 offset:49152
	ds_read_b128 v[200:203], v153 offset:53248
	ds_read_b128 v[204:207], v152 offset:49152
	ds_read_b128 v[208:211], v152 offset:53248
	ds_read_b128 v[212:215], v131 offset:49152
	ds_read_b128 v[216:219], v131 offset:53248
	global_load_lds_dwordx4 v[238:239], off
	v_lshl_add_u64 v[188:189], v[188:189], 0, s[44:45]
	s_mov_b32 m0, s66
	s_nop 0
	global_load_lds_dwordx4 v[188:189], off
	s_barrier
	s_waitcnt lgkmcnt(0)
	s_waitcnt lgkmcnt(0)
	v_mfma_f32_32x32x16_bf16 v[48:63], v[184:187], v[168:171], v[48:63]
	v_mfma_f32_32x32x16_bf16 v[32:47], v[192:195], v[168:171], v[32:47]
	v_mfma_f32_32x32x16_bf16 v[48:63], v[196:199], v[172:175], v[48:63]
	v_mfma_f32_32x32x16_bf16 v[32:47], v[200:203], v[172:175], v[32:47]
	v_mfma_f32_32x32x16_bf16 v[48:63], v[204:207], v[176:179], v[48:63]
	v_mfma_f32_32x32x16_bf16 v[32:47], v[208:211], v[176:179], v[32:47]
	v_mfma_f32_32x32x16_bf16 v[48:63], v[212:215], v[180:183], v[48:63]
	v_mfma_f32_32x32x16_bf16 v[32:47], v[216:219], v[180:183], v[32:47]
	s_barrier
	v_readfirstlane_b32 s66, v163
	v_lshl_add_u64 v[168:169], v[236:237], 0, s[46:47]
	s_mov_b32 m0, s66
	v_readfirstlane_b32 s66, v164
	global_load_lds_dwordx4 v[168:169], off
	v_lshl_add_u64 v[168:169], v[236:237], 0, s[48:49]
	s_mov_b32 m0, s66
	s_nop 0
	global_load_lds_dwordx4 v[168:169], off
	s_waitcnt vmcnt(6)
	s_barrier
	v_mfma_f32_32x32x16_bf16 v[16:31], v[184:187], v[220:223], v[16:31]
	v_mfma_f32_32x32x16_bf16 v[0:15], v[192:195], v[220:223], v[0:15]
	v_mfma_f32_32x32x16_bf16 v[16:31], v[196:199], v[224:227], v[16:31]
	v_mfma_f32_32x32x16_bf16 v[0:15], v[200:203], v[224:227], v[0:15]
	v_mfma_f32_32x32x16_bf16 v[16:31], v[204:207], v[228:231], v[16:31]
	v_mfma_f32_32x32x16_bf16 v[0:15], v[208:211], v[228:231], v[0:15]
	v_mfma_f32_32x32x16_bf16 v[16:31], v[212:215], v[232:235], v[16:31]
	v_mfma_f32_32x32x16_bf16 v[0:15], v[216:219], v[232:235], v[0:15]
	s_barrier
	s_add_i32 s59, s59, 2
	v_lshl_add_u64 v[136:137], v[136:137], 0, s[50:51]
	s_cmp_lt_u32 s59, 60
	v_lshl_add_u64 v[138:139], v[138:139], 0, s[50:51]
	s_cbranch_scc1 .LBB0_1826
	v_readfirstlane_b32 s59, v166
	v_lshl_add_u64 v[188:189], v[134:135], 0, s[52:53]
	s_mov_b32 m0, s59
	v_readfirstlane_b32 s59, v165
	ds_read_b128 v[136:139], v155
	ds_read_b128 v[160:163], v156
	ds_read_b128 v[168:171], v157
	ds_read_b128 v[172:175], v158
	ds_read_b128 v[176:179], v154
	ds_read_b128 v[180:183], v154 offset:4096
	ds_read_b128 v[184:187], v153
	ds_read_b128 v[192:195], v153 offset:4096
	ds_read_b128 v[196:199], v152
	ds_read_b128 v[200:203], v152 offset:4096
	ds_read_b128 v[204:207], v131
	ds_read_b128 v[208:211], v131 offset:4096
	global_load_lds_dwordx4 v[188:189], off
	v_lshl_add_u64 v[134:135], v[134:135], 0, s[54:55]
	s_mov_b32 m0, s59
	s_nop 0
	global_load_lds_dwordx4 v[134:135], off
	s_barrier
	s_waitcnt lgkmcnt(0)
	s_waitcnt lgkmcnt(0)
	v_mfma_f32_32x32x16_bf16 v[112:127], v[176:179], v[136:139], v[112:127]
	v_mfma_f32_32x32x16_bf16 v[96:111], v[180:183], v[136:139], v[96:111]
	v_mfma_f32_32x32x16_bf16 v[112:127], v[184:187], v[160:163], v[112:127]
	v_mfma_f32_32x32x16_bf16 v[96:111], v[192:195], v[160:163], v[96:111]
	v_mfma_f32_32x32x16_bf16 v[112:127], v[196:199], v[168:171], v[112:127]
	v_mfma_f32_32x32x16_bf16 v[96:111], v[200:203], v[168:171], v[96:111]
	v_mfma_f32_32x32x16_bf16 v[112:127], v[204:207], v[172:175], v[112:127]
	v_mfma_f32_32x32x16_bf16 v[96:111], v[208:211], v[172:175], v[96:111]
	s_barrier
	ds_read_b128 v[164:167], v155 offset:16384
	ds_read_b128 v[212:215], v156 offset:16384
	ds_read_b128 v[216:219], v157 offset:16384
	ds_read_b128 v[220:223], v158 offset:16384
	s_barrier
; #define G8_LDA(b, h) do { _Pragma("unroll") for (int m_ = 0; m_ < 2; ++m_) _Pragma("unroll") for (int k_ = 0; k_ < 4; ++k_) \
;     At[m_][k_] = *reinterpret_cast<const LAS bf16x8*>(la + ((b) * 2 + (h)) * 16384 + m_ * 4096 + (((k_ * 2 + hi) ^ swz) << 4)); } while (0)
; #define G8_LDB(dst, b, h) do { _Pragma("unroll") for (int k_ = 0; k_ < 4; ++k_) \
;     dst[k_] = *reinterpret_cast<const LAS bf16x8*>(lb + ((b) * 2 + (h)) * 16384 + (((k_ * 2 + hi) ^ swz) << 4)); } while (0)
; #define G8_MMA(ai, bj, Bx) do { __builtin_amdgcn_s_setprio(1); _Pragma("unroll") for (int k_ = 0; k_ < 4; ++k_) _Pragma("unroll") for (int m_ = 0; m_ < 2; ++m_) \
;     acc[ai][bj][m_] = __builtin_amdgcn_mfma_f32_32x32x16_bf16(At[m_][k_], Bx[k_], acc[ai][bj][m_], 0, 0, 0); __builtin_amdgcn_s_setprio(0); } while (0)
; #define G8_WV(n) asm volatile("s_waitcnt vmcnt(" #n ")" ::: "memory")
; #define G8_WL(n) asm volatile("s_waitcnt lgkmcnt(" #n ")" ::: "memory")
; #define G8_BAR __builtin_amdgcn_s_barrier()
; #define G8_SCHED __builtin_amdgcn_sched_barrier(0)
; template <class Epi>
; __device__ __forceinline__ void gemm8p(const bf16_t* __restrict__ A, int lda, const bf16_t* __restrict__ Bt, int ldb, int K,
;                                        LP lds, const Epi& epi, bool pre = false, const bf16_t* An = nullptr, const bf16_t* Bn = nullptr) {
;     ...
;     G8_LDB(B1, 0, 1); G8_BAR; G8_WL(0); G8_MMA(0, 1, B1); G8_BAR; G8_SCHED;
;     G8_LDA(0, 1); G8_WV(4); G8_BAR; G8_WL(0); G8_MMA(1, 0, B0); G8_MMA(1, 1, B1); G8_BAR; G8_SCHED; }
;   { G8_LDB(B0, 1, 0); G8_LDA(1, 0); G8_WV(2); G8_BAR; G8_WL(0); G8_MMA(0, 0, B0); G8_BAR; G8_SCHED;
;     G8_LDB(B1, 1, 1); G8_WV(0); G8_BAR; G8_WL(0); G8_MMA(0, 1, B1); G8_BAR; G8_SCHED;
;     G8_LDA(1, 1); G8_BAR; G8_WL(0); G8_MMA(1, 0, B0); G8_MMA(1, 1, B1); G8_BAR; G8_SCHED; }
;   if (wr == 0) G8_BAR;
	s_waitcnt lgkmcnt(0)
	s_waitcnt lgkmcnt(0)
	v_mfma_f32_32x32x16_bf16 v[80:95], v[176:179], v[164:167], v[80:95]
	v_mfma_f32_32x32x16_bf16 v[64:79], v[180:183], v[164:167], v[64:79]
	v_mfma_f32_32x32x16_bf16 v[80:95], v[184:187], v[212:215], v[80:95]
	v_mfma_f32_32x32x16_bf16 v[64:79], v[192:195], v[212:215], v[64:79]
	v_mfma_f32_32x32x16_bf16 v[80:95], v[196:199], v[216:219], v[80:95]
	v_mfma_f32_32x32x16_bf16 v[64:79], v[200:203], v[216:219], v[64:79]
	v_mfma_f32_32x32x16_bf16 v[80:95], v[204:207], v[220:223], v[80:95]
	v_mfma_f32_32x32x16_bf16 v[64:79], v[208:211], v[220:223], v[64:79]
	s_barrier
	ds_read_b128 v[176:179], v154 offset:16384
	ds_read_b128 v[180:183], v154 offset:20480
	ds_read_b128 v[184:187], v153 offset:16384
	ds_read_b128 v[192:195], v153 offset:20480
	ds_read_b128 v[196:199], v152 offset:16384
	ds_read_b128 v[200:203], v152 offset:20480
	ds_read_b128 v[204:207], v131 offset:16384
	ds_read_b128 v[208:211], v131 offset:20480
	s_waitcnt vmcnt(4)
	s_barrier
	s_waitcnt lgkmcnt(0)
	s_waitcnt lgkmcnt(0)
	v_mfma_f32_32x32x16_bf16 v[48:63], v[176:179], v[136:139], v[48:63]
	v_mfma_f32_32x32x16_bf16 v[32:47], v[180:183], v[136:139], v[32:47]
	v_mfma_f32_32x32x16_bf16 v[48:63], v[184:187], v[160:163], v[48:63]
	v_mfma_f32_32x32x16_bf16 v[32:47], v[192:195], v[160:163], v[32:47]
	v_mfma_f32_32x32x16_bf16 v[48:63], v[196:199], v[168:171], v[48:63]
	v_mfma_f32_32x32x16_bf16 v[32:47], v[200:203], v[168:171], v[32:47]
	v_mfma_f32_32x32x16_bf16 v[48:63], v[204:207], v[172:175], v[48:63]
	v_mfma_f32_32x32x16_bf16 v[32:47], v[208:211], v[172:175], v[32:47]
	v_mfma_f32_32x32x16_bf16 v[16:31], v[176:179], v[164:167], v[16:31]
	v_mfma_f32_32x32x16_bf16 v[0:15], v[180:183], v[164:167], v[0:15]
	v_mfma_f32_32x32x16_bf16 v[16:31], v[184:187], v[212:215], v[16:31]
	v_mfma_f32_32x32x16_bf16 v[0:15], v[192:195], v[212:215], v[0:15]
	v_mfma_f32_32x32x16_bf16 v[16:31], v[196:199], v[216:219], v[16:31]
	v_mfma_f32_32x32x16_bf16 v[0:15], v[200:203], v[216:219], v[0:15]
	v_mfma_f32_32x32x16_bf16 v[16:31], v[204:207], v[220:223], v[16:31]
	v_mfma_f32_32x32x16_bf16 v[0:15], v[208:211], v[220:223], v[0:15]
	s_barrier
	ds_read_b128 v[134:137], v155 offset:32768
	ds_read_b128 v[160:163], v156 offset:32768
	ds_read_b128 v[164:167], v157 offset:32768
	ds_read_b128 v[168:171], v158 offset:32768
	ds_read_b128 v[172:175], v154 offset:32768
	ds_read_b128 v[176:179], v154 offset:36864
	ds_read_b128 v[180:183], v153 offset:32768
	ds_read_b128 v[184:187], v153 offset:36864
	ds_read_b128 v[192:195], v152 offset:32768
	ds_read_b128 v[196:199], v152 offset:36864
	ds_read_b128 v[200:203], v131 offset:32768
	ds_read_b128 v[204:207], v131 offset:36864
	s_waitcnt vmcnt(2)
	s_barrier
	s_waitcnt lgkmcnt(0)
	s_waitcnt lgkmcnt(0)
	v_mfma_f32_32x32x16_bf16 v[112:127], v[172:175], v[134:137], v[112:127]
	v_mfma_f32_32x32x16_bf16 v[96:111], v[176:179], v[134:137], v[96:111]
	v_mfma_f32_32x32x16_bf16 v[112:127], v[180:183], v[160:163], v[112:127]
	v_mfma_f32_32x32x16_bf16 v[96:111], v[184:187], v[160:163], v[96:111]
	v_mfma_f32_32x32x16_bf16 v[112:127], v[192:195], v[164:167], v[112:127]
	v_mfma_f32_32x32x16_bf16 v[96:111], v[196:199], v[164:167], v[96:111]
	v_mfma_f32_32x32x16_bf16 v[112:127], v[200:203], v[168:171], v[112:127]
	v_mfma_f32_32x32x16_bf16 v[96:111], v[204:207], v[168:171], v[96:111]
	s_barrier
	ds_read_b128 v[208:211], v155 offset:49152
	ds_read_b128 v[212:215], v156 offset:49152
	ds_read_b128 v[216:219], v157 offset:49152
	ds_read_b128 v[156:159], v158 offset:49152
	s_waitcnt vmcnt(0)
	s_barrier
	s_waitcnt lgkmcnt(0)
	s_waitcnt lgkmcnt(0)
	v_mfma_f32_32x32x16_bf16 v[80:95], v[172:175], v[208:211], v[80:95]
	v_mfma_f32_32x32x16_bf16 v[64:79], v[176:179], v[208:211], v[64:79]
	v_mfma_f32_32x32x16_bf16 v[80:95], v[180:183], v[212:215], v[80:95]
	v_mfma_f32_32x32x16_bf16 v[64:79], v[184:187], v[212:215], v[64:79]
	v_mfma_f32_32x32x16_bf16 v[80:95], v[192:195], v[216:219], v[80:95]
	v_mfma_f32_32x32x16_bf16 v[64:79], v[196:199], v[216:219], v[64:79]
	v_mfma_f32_32x32x16_bf16 v[80:95], v[200:203], v[156:159], v[80:95]
	v_mfma_f32_32x32x16_bf16 v[64:79], v[204:207], v[156:159], v[64:79]
	s_barrier
	ds_read_b128 v[172:175], v154 offset:49152
	ds_read_b128 v[176:179], v154 offset:53248
	ds_read_b128 v[180:183], v153 offset:49152
	ds_read_b128 v[184:187], v153 offset:53248
	ds_read_b128 v[192:195], v152 offset:49152
	ds_read_b128 v[152:155], v152 offset:53248
	ds_read_b128 v[196:199], v131 offset:49152
	ds_read_b128 v[200:203], v131 offset:53248
	s_barrier
	s_waitcnt lgkmcnt(0)
	s_waitcnt lgkmcnt(0)
	v_mfma_f32_32x32x16_bf16 v[48:63], v[172:175], v[134:137], v[48:63]
	v_mfma_f32_32x32x16_bf16 v[32:47], v[176:179], v[134:137], v[32:47]
	v_mfma_f32_32x32x16_bf16 v[48:63], v[180:183], v[160:163], v[48:63]
	v_mfma_f32_32x32x16_bf16 v[32:47], v[184:187], v[160:163], v[32:47]
	v_mfma_f32_32x32x16_bf16 v[48:63], v[192:195], v[164:167], v[48:63]
	v_mfma_f32_32x32x16_bf16 v[32:47], v[152:155], v[164:167], v[32:47]
	v_mfma_f32_32x32x16_bf16 v[48:63], v[196:199], v[168:171], v[48:63]
	v_mfma_f32_32x32x16_bf16 v[32:47], v[200:203], v[168:171], v[32:47]
	v_mfma_f32_32x32x16_bf16 v[16:31], v[172:175], v[208:211], v[16:31]
	v_mfma_f32_32x32x16_bf16 v[0:15], v[176:179], v[208:211], v[0:15]
	v_mfma_f32_32x32x16_bf16 v[16:31], v[180:183], v[212:215], v[16:31]
	v_mfma_f32_32x32x16_bf16 v[0:15], v[184:187], v[212:215], v[0:15]
	v_mfma_f32_32x32x16_bf16 v[16:31], v[192:195], v[216:219], v[16:31]
	v_mfma_f32_32x32x16_bf16 v[0:15], v[152:155], v[216:219], v[0:15]
	v_mfma_f32_32x32x16_bf16 v[16:31], v[196:199], v[156:159], v[16:31]
	v_mfma_f32_32x32x16_bf16 v[0:15], v[200:203], v[156:159], v[0:15]
	s_barrier
	s_movk_i32 s59, 0x100
	v_cmp_gt_u32_e32 vcc, s59, v148
	s_and_saveexec_b64 s[66:67], vcc
	s_cbranch_execz .LBB0_1829
	s_barrier

; #define G8_STA(b, h, kt) G8_STAGE(G8_SA(b, h), Ag, lda, h, kt)
; #define G8_STB(b, h, kt) G8_STAGE(G8_SB(b, h), Bg, ldb, h, kt)
; #define G8_LDA(b, h) do { _Pragma("unroll") for (int m_ = 0; m_ < 2; ++m_) _Pragma("unroll") for (int k_ = 0; k_ < 4; ++k_) \
;     At[m_][k_] = *reinterpret_cast<const LAS bf16x8*>(la + ((b) * 2 + (h)) * 16384 + m_ * 4096 + (((k_ * 2 + hi) ^ swz) << 4)); } while (0)
; #define G8_LDB(dst, b, h) do { _Pragma("unroll") for (int k_ = 0; k_ < 4; ++k_) \
;     dst[k_] = *reinterpret_cast<const LAS bf16x8*>(lb + ((b) * 2 + (h)) * 16384 + (((k_ * 2 + hi) ^ swz) << 4)); } while (0)
; #define G8_MMA(ai, bj, Bx) do { __builtin_amdgcn_s_setprio(1); _Pragma("unroll") for (int k_ = 0; k_ < 4; ++k_) _Pragma("unroll") for (int m_ = 0; m_ < 2; ++m_) \
;     acc[ai][bj][m_] = __builtin_amdgcn_mfma_f32_32x32x16_bf16(At[m_][k_], Bx[k_], acc[ai][bj][m_], 0, 0, 0); __builtin_amdgcn_s_setprio(0); } while (0)
; #define G8_WV(n) asm volatile("s_waitcnt vmcnt(" #n ")" ::: "memory")
; #define G8_WL(n) asm volatile("s_waitcnt lgkmcnt(" #n ")" ::: "memory")
; #define G8_BAR __builtin_amdgcn_s_barrier()
; #define G8_SCHED __builtin_amdgcn_sched_barrier(0)
; template <class Epi>
; __device__ __forceinline__ void gemm8p(const bf16_t* __restrict__ A, int lda, const bf16_t* __restrict__ Bt, int ldb, int K,
;                                        LP lds, const Epi& epi, bool pre = false, const bf16_t* An = nullptr, const bf16_t* Bn = nullptr) {
;     ...
;   if (wr == 1) G8_BAR;
;   G8_WV(4); G8_BAR;
;   G8_STB(1, 0, 1); G8_STA(1, 0, 1); G8_STB(1, 1, 1);
;   G8_WV(6); G8_BAR;
;   G8_SCHED;
;   for (int t = 0; t < nt - 2; t += 2) {
;     G8_LDB(B0, 0, 0); G8_SCHED; G8_LDA(0, 0); G8_STA(1, 1, t + 1);
;     G8_WL(8); G8_BAR; G8_WL(0); G8_MMA(0, 0, B0); G8_BAR; G8_SCHED;
;     G8_LDB(B1, 0, 1); G8_STB(0, 0, t + 2);
;     G8_BAR; G8_WL(0); G8_MMA(0, 1, B1); G8_BAR; G8_SCHED;
;     G8_LDA(0, 1); G8_STA(0, 0, t + 2);
;     G8_BAR; G8_WL(0); G8_MMA(1, 0, B0); G8_BAR; G8_SCHED;
.LBB0_1836:
	s_or_b64 exec, exec, s[42:43]
	v_add_u32_e32 v10, 0x18000, v2
	v_lshl_add_u64 v[8:9], v[132:133], 0, s[12:13]
	v_readfirstlane_b32 s56, v10
	v_add_u32_e32 v10, 0x1a000, v2
	s_mov_b32 m0, s56
	v_readfirstlane_b32 s55, v10
	v_add_u32_e32 v10, 0x8000, v2
	s_waitcnt vmcnt(4)
	s_barrier
	global_load_lds_dwordx4 v[8:9], off
	v_lshl_add_u64 v[8:9], v[132:133], 0, s[14:15]
	s_mov_b32 m0, s55
	v_readfirstlane_b32 s54, v10
	v_add_u32_e32 v10, 0xa000, v2
	global_load_lds_dwordx4 v[8:9], off
	v_lshl_add_u64 v[8:9], v[130:131], 0, s[12:13]
	s_mov_b32 m0, s54
	v_readfirstlane_b32 s52, v10
	v_add_u32_e32 v10, 0x1c000, v2
	global_load_lds_dwordx4 v[8:9], off
	v_lshl_add_u64 v[8:9], v[130:131], 0, s[14:15]
	s_mov_b32 m0, s52
	v_readfirstlane_b32 s42, v10
	v_add_u32_e32 v10, 0x1e000, v2
	global_load_lds_dwordx4 v[8:9], off
	v_lshl_add_u64 v[8:9], v[132:133], 0, s[16:17]
	s_mov_b32 m0, s42
	v_readfirstlane_b32 s41, v10
	global_load_lds_dwordx4 v[8:9], off
	v_lshl_add_u64 v[8:9], v[132:133], 0, s[18:19]
	s_mov_b32 m0, s41
	v_lshlrev_b32_e32 v135, 6, v7
	global_load_lds_dwordx4 v[8:9], off
	v_and_b32_e32 v9, 31, v134
	v_lshlrev_b32_e32 v6, 5, v6
	s_waitcnt vmcnt(6)
	v_or_b32_e32 v7, v135, v9
	v_and_or_b32 v136, v6, s48, v9
	v_lshrrev_b32_e32 v8, 5, v134
	v_bfe_u32 v128, v134, 5, 1
	v_lshl_add_u32 v22, v7, 7, 0
	v_bfe_u32 v14, v134, 1, 3
	v_lshl_add_u32 v15, v136, 7, s74
	s_barrier
	v_bitop3_b32 v6, v8, v14, 1 bitop3:0x6c
	v_bitop3_b32 v16, v128, v14, 4 bitop3:0x36
	v_lshlrev_b32_e32 v23, 4, v6
	v_bitop3_b32 v6, v128, v14, 2 bitop3:0x36
	v_lshlrev_b32_e32 v25, 4, v16
	v_bitop3_b32 v14, v128, v14, 6 bitop3:0x36
	v_add_u32_e32 v191, v15, v23
	v_lshlrev_b32_e32 v24, 4, v6
	v_add_u32_e32 v209, v15, v25
	v_lshlrev_b32_e32 v26, 4, v14
	v_add_u32_e32 v208, v15, v24
	ds_read_b128 v[6:9], v191
	ds_read_b128 v[10:13], v208
	v_add_u32_e32 v210, v15, v26
	ds_read_b128 v[14:17], v209
	ds_read_b128 v[18:21], v210
	v_add_u32_e32 v56, 0xc000, v2
	s_nop 0
	v_readfirstlane_b32 s53, v56
	v_add_u32_e32 v56, 0xe000, v2
	v_add_u32_e32 v211, v22, v23
	v_lshl_add_u64 v[54:55], v[130:131], 0, s[16:17]
	s_mov_b32 m0, s53
	v_readfirstlane_b32 s43, v56
	v_add_u32_e32 v212, v22, v24
	v_add_u32_e32 v213, v22, v25
	v_add_u32_e32 v214, v22, v26
	ds_read_b128 v[22:25], v211
	ds_read_b128 v[26:29], v211 offset:4096
	ds_read_b128 v[30:33], v212
	ds_read_b128 v[34:37], v212 offset:4096
	ds_read_b128 v[38:41], v213
	ds_read_b128 v[42:45], v213 offset:4096
	ds_read_b128 v[46:49], v214
	ds_read_b128 v[50:53], v214 offset:4096
	global_load_lds_dwordx4 v[54:55], off
	v_lshl_add_u64 v[54:55], v[130:131], 0, s[18:19]
	s_mov_b32 m0, s43
	s_nop 0
	global_load_lds_dwordx4 v[54:55], off
	s_waitcnt lgkmcnt(8)
	s_barrier
	s_waitcnt lgkmcnt(0)
	s_waitcnt lgkmcnt(0)
	v_mfma_f32_32x32x16_bf16 v[112:127], v[22:25], v[6:9], 0
	v_mfma_f32_32x32x16_bf16 v[96:111], v[26:29], v[6:9], 0
	v_mfma_f32_32x32x16_bf16 v[112:127], v[30:33], v[10:13], v[112:127]
	v_mfma_f32_32x32x16_bf16 v[96:111], v[34:37], v[10:13], v[96:111]
	v_mfma_f32_32x32x16_bf16 v[112:127], v[38:41], v[14:17], v[112:127]
	v_mfma_f32_32x32x16_bf16 v[96:111], v[42:45], v[14:17], v[96:111]
	v_mfma_f32_32x32x16_bf16 v[112:127], v[46:49], v[18:21], v[112:127]
	v_mfma_f32_32x32x16_bf16 v[96:111], v[50:53], v[18:21], v[96:111]
	s_barrier
	v_readfirstlane_b32 s57, v4
	v_lshl_add_u64 v[54:55], v[132:133], 0, s[20:21]
	s_mov_b32 m0, s57
	v_readfirstlane_b32 s57, v5
	ds_read_b128 v[140:143], v191 offset:16384
	ds_read_b128 v[144:147], v208 offset:16384
	ds_read_b128 v[148:151], v209 offset:16384
	ds_read_b128 v[152:155], v210 offset:16384
	global_load_lds_dwordx4 v[54:55], off
	v_lshl_add_u64 v[54:55], v[132:133], 0, s[22:23]
	s_mov_b32 m0, s57
	s_nop 0
	global_load_lds_dwordx4 v[54:55], off
	s_barrier
	s_waitcnt lgkmcnt(0)
	s_waitcnt lgkmcnt(0)
	v_mfma_f32_32x32x16_bf16 v[80:95], v[22:25], v[140:143], 0
	v_mfma_f32_32x32x16_bf16 v[64:79], v[26:29], v[140:143], 0
	v_mfma_f32_32x32x16_bf16 v[80:95], v[30:33], v[144:147], v[80:95]
	v_mfma_f32_32x32x16_bf16 v[64:79], v[34:37], v[144:147], v[64:79]
	v_mfma_f32_32x32x16_bf16 v[80:95], v[38:41], v[148:151], v[80:95]
	v_mfma_f32_32x32x16_bf16 v[64:79], v[42:45], v[148:151], v[64:79]
	v_mfma_f32_32x32x16_bf16 v[80:95], v[46:49], v[152:155], v[80:95]
	v_mfma_f32_32x32x16_bf16 v[64:79], v[50:53], v[152:155], v[64:79]
	s_barrier
	v_readfirstlane_b32 s57, v2
	v_lshl_add_u64 v[4:5], v[130:131], 0, s[20:21]
	s_mov_b32 m0, s57
	v_readfirstlane_b32 s57, v3
	ds_read_b128 v[22:25], v211 offset:16384
	ds_read_b128 v[156:159], v211 offset:20480
	ds_read_b128 v[160:163], v212 offset:16384
	ds_read_b128 v[164:167], v212 offset:20480
	ds_read_b128 v[168:171], v213 offset:16384
	ds_read_b128 v[172:175], v213 offset:20480
	ds_read_b128 v[176:179], v214 offset:16384
	ds_read_b128 v[180:183], v214 offset:20480
	global_load_lds_dwordx4 v[4:5], off
	v_lshl_add_u64 v[4:5], v[130:131], 0, s[22:23]
	s_mov_b32 m0, s57
	s_nop 0
	global_load_lds_dwordx4 v[4:5], off
	s_barrier
	s_waitcnt lgkmcnt(0)
	s_waitcnt lgkmcnt(0)
	v_mfma_f32_32x32x16_bf16 v[48:63], v[22:25], v[6:9], 0
	v_mfma_f32_32x32x16_bf16 v[32:47], v[156:159], v[6:9], 0
	v_mfma_f32_32x32x16_bf16 v[48:63], v[160:163], v[10:13], v[48:63]
	v_mfma_f32_32x32x16_bf16 v[32:47], v[164:167], v[10:13], v[32:47]
	v_mfma_f32_32x32x16_bf16 v[48:63], v[168:171], v[14:17], v[48:63]
	v_mfma_f32_32x32x16_bf16 v[32:47], v[172:175], v[14:17], v[32:47]
	v_mfma_f32_32x32x16_bf16 v[48:63], v[176:179], v[18:21], v[48:63]
	v_mfma_f32_32x32x16_bf16 v[32:47], v[180:183], v[18:21], v[32:47]
	s_barrier
; #define G8_STA(b, h, kt) G8_STAGE(G8_SA(b, h), Ag, lda, h, kt)
; #define G8_STB(b, h, kt) G8_STAGE(G8_SB(b, h), Bg, ldb, h, kt)
; #define G8_LDA(b, h) do { _Pragma("unroll") for (int m_ = 0; m_ < 2; ++m_) _Pragma("unroll") for (int k_ = 0; k_ < 4; ++k_) \
;     At[m_][k_] = *reinterpret_cast<const LAS bf16x8*>(la + ((b) * 2 + (h)) * 16384 + m_ * 4096 + (((k_ * 2 + hi) ^ swz) << 4)); } while (0)
; #define G8_LDB(dst, b, h) do { _Pragma("unroll") for (int k_ = 0; k_ < 4; ++k_) \
;     dst[k_] = *reinterpret_cast<const LAS bf16x8*>(lb + ((b) * 2 + (h)) * 16384 + (((k_ * 2 + hi) ^ swz) << 4)); } while (0)
; #define G8_MMA(ai, bj, Bx) do { __builtin_amdgcn_s_setprio(1); _Pragma("unroll") for (int k_ = 0; k_ < 4; ++k_) _Pragma("unroll") for (int m_ = 0; m_ < 2; ++m_) \
;     acc[ai][bj][m_] = __builtin_amdgcn_mfma_f32_32x32x16_bf16(At[m_][k_], Bx[k_], acc[ai][bj][m_], 0, 0, 0); __builtin_amdgcn_s_setprio(0); } while (0)
; #define G8_WV(n) asm volatile("s_waitcnt vmcnt(" #n ")" ::: "memory")
; #define G8_WL(n) asm volatile("s_waitcnt lgkmcnt(" #n ")" ::: "memory")
; #define G8_BAR __builtin_amdgcn_s_barrier()
; #define G8_SCHED __builtin_amdgcn_sched_barrier(0)
; template <class Epi>
; __device__ __forceinline__ void gemm8p(const bf16_t* __restrict__ A, int lda, const bf16_t* __restrict__ Bt, int ldb, int K,
;                                        LP lds, const Epi& epi, bool pre = false, const bf16_t* An = nullptr, const bf16_t* Bn = nullptr) {
;     ...
;     G8_STB(0, 1, t + 2);
;     G8_WV(6); G8_BAR; G8_MMA(1, 1, B1); G8_BAR; G8_SCHED;
;     G8_LDB(B0, 1, 0); G8_SCHED; G8_LDA(1, 0); G8_STA(0, 1, t + 2);
;     G8_WL(8); G8_BAR; G8_WL(0); G8_MMA(0, 0, B0); G8_BAR; G8_SCHED;
;     G8_LDB(B1, 1, 1); G8_STB(1, 0, t + 3);
;     G8_BAR; G8_WL(0); G8_MMA(0, 1, B1); G8_BAR; G8_SCHED;
;     G8_LDA(1, 1); G8_STA(1, 0, t + 3);
;     G8_BAR; G8_WL(0); G8_MMA(1, 0, B0); G8_BAR; G8_SCHED;
;     G8_STB(1, 1, t + 3);
;     G8_WV(6); G8_BAR; G8_MMA(1, 1, B1); G8_BAR; G8_SCHED;
	v_readfirstlane_b32 s57, v0
	v_lshl_add_u64 v[2:3], v[132:133], 0, s[24:25]
	s_mov_b32 m0, s57
	v_readfirstlane_b32 s57, v1
	global_load_lds_dwordx4 v[2:3], off
	v_lshl_add_u64 v[2:3], v[132:133], 0, s[26:27]
	s_mov_b32 m0, s57
	s_nop 0
	global_load_lds_dwordx4 v[2:3], off
	s_waitcnt vmcnt(6)
	s_barrier
	v_mfma_f32_32x32x16_bf16 v[16:31], v[22:25], v[140:143], 0
	v_mfma_f32_32x32x16_bf16 v[0:15], v[156:159], v[140:143], 0
	v_mfma_f32_32x32x16_bf16 v[16:31], v[160:163], v[144:147], v[16:31]
	v_mfma_f32_32x32x16_bf16 v[0:15], v[164:167], v[144:147], v[0:15]
	v_mfma_f32_32x32x16_bf16 v[16:31], v[168:171], v[148:151], v[16:31]
	v_mfma_f32_32x32x16_bf16 v[0:15], v[172:175], v[148:151], v[0:15]
	v_mfma_f32_32x32x16_bf16 v[16:31], v[176:179], v[152:155], v[16:31]
	v_mfma_f32_32x32x16_bf16 v[0:15], v[180:183], v[152:155], v[0:15]
	s_barrier
	ds_read_b128 v[140:143], v191 offset:32768
	ds_read_b128 v[144:147], v208 offset:32768
	ds_read_b128 v[148:151], v209 offset:32768
	ds_read_b128 v[152:155], v210 offset:32768
	v_readfirstlane_b32 s57, v137
	v_lshl_add_u64 v[188:189], v[130:131], 0, s[24:25]
	s_mov_b32 m0, s57
	v_readfirstlane_b32 s57, v138
	ds_read_b128 v[156:159], v211 offset:32768
	ds_read_b128 v[160:163], v211 offset:36864
	ds_read_b128 v[164:167], v212 offset:32768
	ds_read_b128 v[168:171], v212 offset:36864
	ds_read_b128 v[172:175], v213 offset:32768
	ds_read_b128 v[176:179], v213 offset:36864
	ds_read_b128 v[180:183], v214 offset:32768
	ds_read_b128 v[184:187], v214 offset:36864
	global_load_lds_dwordx4 v[188:189], off
	v_lshl_add_u64 v[188:189], v[130:131], 0, s[26:27]
	s_mov_b32 m0, s57
	s_nop 0
	global_load_lds_dwordx4 v[188:189], off
	s_waitcnt lgkmcnt(8)
	s_barrier
	s_waitcnt lgkmcnt(0)
	s_waitcnt lgkmcnt(0)
	v_mfma_f32_32x32x16_bf16 v[112:127], v[156:159], v[140:143], v[112:127]
	v_mfma_f32_32x32x16_bf16 v[96:111], v[160:163], v[140:143], v[96:111]
	v_mfma_f32_32x32x16_bf16 v[112:127], v[164:167], v[144:147], v[112:127]
	v_mfma_f32_32x32x16_bf16 v[96:111], v[168:171], v[144:147], v[96:111]
	v_mfma_f32_32x32x16_bf16 v[112:127], v[172:175], v[148:151], v[112:127]
	v_mfma_f32_32x32x16_bf16 v[96:111], v[176:179], v[148:151], v[96:111]
	v_mfma_f32_32x32x16_bf16 v[112:127], v[180:183], v[152:155], v[112:127]
	v_mfma_f32_32x32x16_bf16 v[96:111], v[184:187], v[152:155], v[96:111]
	s_barrier
	s_mov_b32 m0, s56
	v_lshl_add_u64 v[138:139], v[132:133], 0, s[28:29]
	ds_read_b128 v[192:195], v191 offset:49152
	ds_read_b128 v[196:199], v208 offset:49152
	ds_read_b128 v[200:203], v209 offset:49152
	ds_read_b128 v[204:207], v210 offset:49152
	global_load_lds_dwordx4 v[138:139], off
	v_lshl_add_u64 v[138:139], v[132:133], 0, s[30:31]
	s_mov_b32 m0, s55
	s_nop 0
	global_load_lds_dwordx4 v[138:139], off
	s_barrier
	s_waitcnt lgkmcnt(0)
	s_waitcnt lgkmcnt(0)
	v_mfma_f32_32x32x16_bf16 v[80:95], v[156:159], v[192:195], v[80:95]
	v_mfma_f32_32x32x16_bf16 v[64:79], v[160:163], v[192:195], v[64:79]
	v_mfma_f32_32x32x16_bf16 v[80:95], v[164:167], v[196:199], v[80:95]
	v_mfma_f32_32x32x16_bf16 v[64:79], v[168:171], v[196:199], v[64:79]
	v_mfma_f32_32x32x16_bf16 v[80:95], v[172:175], v[200:203], v[80:95]
	v_mfma_f32_32x32x16_bf16 v[64:79], v[176:179], v[200:203], v[64:79]
	v_mfma_f32_32x32x16_bf16 v[80:95], v[180:183], v[204:207], v[80:95]
	v_mfma_f32_32x32x16_bf16 v[64:79], v[184:187], v[204:207], v[64:79]
	s_barrier
	s_mov_b32 m0, s54
	v_lshl_add_u64 v[138:139], v[130:131], 0, s[28:29]
	ds_read_b128 v[156:159], v211 offset:49152
	ds_read_b128 v[160:163], v211 offset:53248
	ds_read_b128 v[164:167], v212 offset:49152
	ds_read_b128 v[168:171], v212 offset:53248
	ds_read_b128 v[172:175], v213 offset:49152
	ds_read_b128 v[176:179], v213 offset:53248
	ds_read_b128 v[180:183], v214 offset:49152
	ds_read_b128 v[184:187], v214 offset:53248
	global_load_lds_dwordx4 v[138:139], off
	v_lshl_add_u64 v[138:139], v[130:131], 0, s[30:31]
	s_mov_b32 m0, s52
	s_nop 0
	global_load_lds_dwordx4 v[138:139], off
	s_barrier
	s_waitcnt lgkmcnt(0)
	s_waitcnt lgkmcnt(0)
	v_mfma_f32_32x32x16_bf16 v[48:63], v[156:159], v[140:143], v[48:63]
	v_mfma_f32_32x32x16_bf16 v[32:47], v[160:163], v[140:143], v[32:47]
	v_mfma_f32_32x32x16_bf16 v[48:63], v[164:167], v[144:147], v[48:63]
	v_mfma_f32_32x32x16_bf16 v[32:47], v[168:171], v[144:147], v[32:47]
	v_mfma_f32_32x32x16_bf16 v[48:63], v[172:175], v[148:151], v[48:63]
	v_mfma_f32_32x32x16_bf16 v[32:47], v[176:179], v[148:151], v[32:47]
	v_mfma_f32_32x32x16_bf16 v[48:63], v[180:183], v[152:155], v[48:63]
	v_mfma_f32_32x32x16_bf16 v[32:47], v[184:187], v[152:155], v[32:47]
	s_barrier
	s_mov_b32 m0, s42
	v_lshl_add_u64 v[138:139], v[132:133], 0, s[36:37]
	global_load_lds_dwordx4 v[138:139], off
	v_lshl_add_u64 v[132:133], v[132:133], 0, s[38:39]
	s_mov_b32 m0, s41
	s_nop 0
	global_load_lds_dwordx4 v[132:133], off
	s_waitcnt vmcnt(6)
	s_barrier
	v_mfma_f32_32x32x16_bf16 v[16:31], v[156:159], v[192:195], v[16:31]
	v_mfma_f32_32x32x16_bf16 v[0:15], v[160:163], v[192:195], v[0:15]
	v_mfma_f32_32x32x16_bf16 v[16:31], v[164:167], v[196:199], v[16:31]
	v_mfma_f32_32x32x16_bf16 v[0:15], v[168:171], v[196:199], v[0:15]
	v_mfma_f32_32x32x16_bf16 v[16:31], v[172:175], v[200:203], v[16:31]
	v_mfma_f32_32x32x16_bf16 v[0:15], v[176:179], v[200:203], v[0:15]
	v_mfma_f32_32x32x16_bf16 v[16:31], v[180:183], v[204:207], v[16:31]
	v_mfma_f32_32x32x16_bf16 v[0:15], v[184:187], v[204:207], v[0:15]
	s_barrier
; #define G8_STA(b, h, kt) G8_STAGE(G8_SA(b, h), Ag, lda, h, kt)
; #define G8_LDA(b, h) do { _Pragma("unroll") for (int m_ = 0; m_ < 2; ++m_) _Pragma("unroll") for (int k_ = 0; k_ < 4; ++k_) \
;     At[m_][k_] = *reinterpret_cast<const LAS bf16x8*>(la + ((b) * 2 + (h)) * 16384 + m_ * 4096 + (((k_ * 2 + hi) ^ swz) << 4)); } while (0)
; #define G8_LDB(dst, b, h) do { _Pragma("unroll") for (int k_ = 0; k_ < 4; ++k_) \
;     dst[k_] = *reinterpret_cast<const LAS bf16x8*>(lb + ((b) * 2 + (h)) * 16384 + (((k_ * 2 + hi) ^ swz) << 4)); } while (0)
; #define G8_MMA(ai, bj, Bx) do { __builtin_amdgcn_s_setprio(1); _Pragma("unroll") for (int k_ = 0; k_ < 4; ++k_) _Pragma("unroll") for (int m_ = 0; m_ < 2; ++m_) \
;     acc[ai][bj][m_] = __builtin_amdgcn_mfma_f32_32x32x16_bf16(At[m_][k_], Bx[k_], acc[ai][bj][m_], 0, 0, 0); __builtin_amdgcn_s_setprio(0); } while (0)
; #define G8_WV(n) asm volatile("s_waitcnt vmcnt(" #n ")" ::: "memory")
; #define G8_WL(n) asm volatile("s_waitcnt lgkmcnt(" #n ")" ::: "memory")
; #define G8_BAR __builtin_amdgcn_s_barrier()
; #define G8_SCHED __builtin_amdgcn_sched_barrier(0)
; template <class Epi>
; __device__ __forceinline__ void gemm8p(const bf16_t* __restrict__ A, int lda, const bf16_t* __restrict__ Bt, int ldb, int K,
;                                        LP lds, const Epi& epi, bool pre = false, const bf16_t* An = nullptr, const bf16_t* Bn = nullptr) {
;     ...
;   { G8_LDB(B0, 0, 0); G8_LDA(0, 0); G8_STA(1, 1, nt - 1);
;     G8_BAR; G8_WL(0); G8_MMA(0, 0, B0); G8_BAR; G8_SCHED;
;     G8_LDB(B1, 0, 1); G8_BAR; G8_WL(0); G8_MMA(0, 1, B1); G8_BAR; G8_SCHED;
;     G8_LDA(0, 1); G8_WV(4); G8_BAR; G8_WL(0); G8_MMA(1, 0, B0); G8_MMA(1, 1, B1); G8_BAR; G8_SCHED; }
	s_mov_b32 m0, s53
	v_lshl_add_u64 v[132:133], v[130:131], 0, s[36:37]
	ds_read_b128 v[138:141], v191
	ds_read_b128 v[142:145], v208
	ds_read_b128 v[146:149], v209
	ds_read_b128 v[150:153], v210
	ds_read_b128 v[154:157], v211
	ds_read_b128 v[158:161], v211 offset:4096
	ds_read_b128 v[162:165], v212
	ds_read_b128 v[166:169], v212 offset:4096
	ds_read_b128 v[170:173], v213
	ds_read_b128 v[174:177], v213 offset:4096
	ds_read_b128 v[178:181], v214
	ds_read_b128 v[182:185], v214 offset:4096
	global_load_lds_dwordx4 v[132:133], off
	v_lshl_add_u64 v[130:131], v[130:131], 0, s[38:39]
	s_mov_b32 m0, s43
	s_nop 0
	global_load_lds_dwordx4 v[130:131], off
	s_barrier
	s_waitcnt lgkmcnt(0)
	s_waitcnt lgkmcnt(0)
	v_mfma_f32_32x32x16_bf16 v[112:127], v[154:157], v[138:141], v[112:127]
	v_mfma_f32_32x32x16_bf16 v[96:111], v[158:161], v[138:141], v[96:111]
	v_mfma_f32_32x32x16_bf16 v[112:127], v[162:165], v[142:145], v[112:127]
	v_mfma_f32_32x32x16_bf16 v[96:111], v[166:169], v[142:145], v[96:111]
	v_mfma_f32_32x32x16_bf16 v[112:127], v[170:173], v[146:149], v[112:127]
	v_mfma_f32_32x32x16_bf16 v[96:111], v[174:177], v[146:149], v[96:111]
	v_mfma_f32_32x32x16_bf16 v[112:127], v[178:181], v[150:153], v[112:127]
	v_mfma_f32_32x32x16_bf16 v[96:111], v[182:185], v[150:153], v[96:111]
	s_barrier
	ds_read_b128 v[130:133], v191 offset:16384
	ds_read_b128 v[186:189], v208 offset:16384
	ds_read_b128 v[192:195], v209 offset:16384
	ds_read_b128 v[196:199], v210 offset:16384
	s_barrier
	s_waitcnt lgkmcnt(0)
	s_waitcnt lgkmcnt(0)
	v_mfma_f32_32x32x16_bf16 v[80:95], v[154:157], v[130:133], v[80:95]
	v_mfma_f32_32x32x16_bf16 v[64:79], v[158:161], v[130:133], v[64:79]
	v_mfma_f32_32x32x16_bf16 v[80:95], v[162:165], v[186:189], v[80:95]
	v_mfma_f32_32x32x16_bf16 v[64:79], v[166:169], v[186:189], v[64:79]
	v_mfma_f32_32x32x16_bf16 v[80:95], v[170:173], v[192:195], v[80:95]
	v_mfma_f32_32x32x16_bf16 v[64:79], v[174:177], v[192:195], v[64:79]
	v_mfma_f32_32x32x16_bf16 v[80:95], v[178:181], v[196:199], v[80:95]
	v_mfma_f32_32x32x16_bf16 v[64:79], v[182:185], v[196:199], v[64:79]
	s_barrier
	ds_read_b128 v[154:157], v211 offset:16384
	ds_read_b128 v[158:161], v211 offset:20480
	ds_read_b128 v[162:165], v212 offset:16384
	ds_read_b128 v[166:169], v212 offset:20480
	ds_read_b128 v[170:173], v213 offset:16384
	ds_read_b128 v[174:177], v213 offset:20480
	ds_read_b128 v[178:181], v214 offset:16384
	ds_read_b128 v[182:185], v214 offset:20480
	s_waitcnt vmcnt(4)
	s_barrier
	s_waitcnt lgkmcnt(0)
	s_waitcnt lgkmcnt(0)
	v_mfma_f32_32x32x16_bf16 v[48:63], v[154:157], v[138:141], v[48:63]
	v_mfma_f32_32x32x16_bf16 v[32:47], v[158:161], v[138:141], v[32:47]
	v_mfma_f32_32x32x16_bf16 v[48:63], v[162:165], v[142:145], v[48:63]
	v_mfma_f32_32x32x16_bf16 v[32:47], v[166:169], v[142:145], v[32:47]
	v_mfma_f32_32x32x16_bf16 v[48:63], v[170:173], v[146:149], v[48:63]
	v_mfma_f32_32x32x16_bf16 v[32:47], v[174:177], v[146:149], v[32:47]
	v_mfma_f32_32x32x16_bf16 v[48:63], v[178:181], v[150:153], v[48:63]
	v_mfma_f32_32x32x16_bf16 v[32:47], v[182:185], v[150:153], v[32:47]
	v_mfma_f32_32x32x16_bf16 v[16:31], v[154:157], v[130:133], v[16:31]
	v_mfma_f32_32x32x16_bf16 v[0:15], v[158:161], v[130:133], v[0:15]
	v_mfma_f32_32x32x16_bf16 v[16:31], v[162:165], v[186:189], v[16:31]
	v_mfma_f32_32x32x16_bf16 v[0:15], v[166:169], v[186:189], v[0:15]
	v_mfma_f32_32x32x16_bf16 v[16:31], v[170:173], v[192:195], v[16:31]
	v_mfma_f32_32x32x16_bf16 v[0:15], v[174:177], v[192:195], v[0:15]
	v_mfma_f32_32x32x16_bf16 v[16:31], v[178:181], v[196:199], v[16:31]
	v_mfma_f32_32x32x16_bf16 v[0:15], v[182:185], v[196:199], v[0:15]
	s_barrier
; #define G8_LDA(b, h) do { _Pragma("unroll") for (int m_ = 0; m_ < 2; ++m_) _Pragma("unroll") for (int k_ = 0; k_ < 4; ++k_) \
;     At[m_][k_] = *reinterpret_cast<const LAS bf16x8*>(la + ((b) * 2 + (h)) * 16384 + m_ * 4096 + (((k_ * 2 + hi) ^ swz) << 4)); } while (0)
; #define G8_LDB(dst, b, h) do { _Pragma("unroll") for (int k_ = 0; k_ < 4; ++k_) \
;     dst[k_] = *reinterpret_cast<const LAS bf16x8*>(lb + ((b) * 2 + (h)) * 16384 + (((k_ * 2 + hi) ^ swz) << 4)); } while (0)
; #define G8_MMA(ai, bj, Bx) do { __builtin_amdgcn_s_setprio(1); _Pragma("unroll") for (int k_ = 0; k_ < 4; ++k_) _Pragma("unroll") for (int m_ = 0; m_ < 2; ++m_) \
;     acc[ai][bj][m_] = __builtin_amdgcn_mfma_f32_32x32x16_bf16(At[m_][k_], Bx[k_], acc[ai][bj][m_], 0, 0, 0); __builtin_amdgcn_s_setprio(0); } while (0)
; #define G8_WV(n) asm volatile("s_waitcnt vmcnt(" #n ")" ::: "memory")
; #define G8_WL(n) asm volatile("s_waitcnt lgkmcnt(" #n ")" ::: "memory")
; #define G8_BAR __builtin_amdgcn_s_barrier()
; #define G8_SCHED __builtin_amdgcn_sched_barrier(0)
; template <class Epi>
; __device__ __forceinline__ void gemm8p(const bf16_t* __restrict__ A, int lda, const bf16_t* __restrict__ Bt, int ldb, int K,
;                                        LP lds, const Epi& epi, bool pre = false, const bf16_t* An = nullptr, const bf16_t* Bn = nullptr) {
;     ...
;   { G8_LDB(B0, 1, 0); G8_LDA(1, 0); G8_WV(2); G8_BAR; G8_WL(0); G8_MMA(0, 0, B0); G8_BAR; G8_SCHED;
;     G8_LDB(B1, 1, 1); G8_WV(0); G8_BAR; G8_WL(0); G8_MMA(0, 1, B1); G8_BAR; G8_SCHED;
;     G8_LDA(1, 1); G8_BAR; G8_WL(0); G8_MMA(1, 0, B0); G8_MMA(1, 1, B1); G8_BAR; G8_SCHED; }
;   if (wr == 0) G8_BAR;
	ds_read_b128 v[130:133], v191 offset:32768
	ds_read_b128 v[138:141], v208 offset:32768
	ds_read_b128 v[142:145], v209 offset:32768
	ds_read_b128 v[146:149], v210 offset:32768
	ds_read_b128 v[150:153], v211 offset:32768
	ds_read_b128 v[154:157], v211 offset:36864
	ds_read_b128 v[158:161], v212 offset:32768
	ds_read_b128 v[162:165], v212 offset:36864
	ds_read_b128 v[166:169], v213 offset:32768
	ds_read_b128 v[170:173], v213 offset:36864
	ds_read_b128 v[174:177], v214 offset:32768
	ds_read_b128 v[178:181], v214 offset:36864
	s_waitcnt vmcnt(2)
	s_barrier
	s_waitcnt lgkmcnt(0)
	s_waitcnt lgkmcnt(0)
	v_mfma_f32_32x32x16_bf16 v[112:127], v[150:153], v[130:133], v[112:127]
	v_mfma_f32_32x32x16_bf16 v[96:111], v[154:157], v[130:133], v[96:111]
	v_mfma_f32_32x32x16_bf16 v[112:127], v[158:161], v[138:141], v[112:127]
	v_mfma_f32_32x32x16_bf16 v[96:111], v[162:165], v[138:141], v[96:111]
	v_mfma_f32_32x32x16_bf16 v[112:127], v[166:169], v[142:145], v[112:127]
	v_mfma_f32_32x32x16_bf16 v[96:111], v[170:173], v[142:145], v[96:111]
	v_mfma_f32_32x32x16_bf16 v[112:127], v[174:177], v[146:149], v[112:127]
	v_mfma_f32_32x32x16_bf16 v[96:111], v[178:181], v[146:149], v[96:111]
	s_barrier
	ds_read_b128 v[182:185], v191 offset:49152
	ds_read_b128 v[186:189], v208 offset:49152
	ds_read_b128 v[192:195], v209 offset:49152
	ds_read_b128 v[196:199], v210 offset:49152
	s_waitcnt vmcnt(0)
	s_barrier
	s_waitcnt lgkmcnt(0)
	s_waitcnt lgkmcnt(0)
	v_mfma_f32_32x32x16_bf16 v[80:95], v[150:153], v[182:185], v[80:95]
	v_mfma_f32_32x32x16_bf16 v[64:79], v[154:157], v[182:185], v[64:79]
	v_mfma_f32_32x32x16_bf16 v[80:95], v[158:161], v[186:189], v[80:95]
	v_mfma_f32_32x32x16_bf16 v[64:79], v[162:165], v[186:189], v[64:79]
	v_mfma_f32_32x32x16_bf16 v[80:95], v[166:169], v[192:195], v[80:95]
	v_mfma_f32_32x32x16_bf16 v[64:79], v[170:173], v[192:195], v[64:79]
	v_mfma_f32_32x32x16_bf16 v[80:95], v[174:177], v[196:199], v[80:95]
	v_mfma_f32_32x32x16_bf16 v[64:79], v[178:181], v[196:199], v[64:79]
	s_barrier
	ds_read_b128 v[150:153], v211 offset:49152
	ds_read_b128 v[154:157], v211 offset:53248
	ds_read_b128 v[158:161], v212 offset:49152
	ds_read_b128 v[162:165], v212 offset:53248
	ds_read_b128 v[166:169], v213 offset:49152
	ds_read_b128 v[170:173], v213 offset:53248
	ds_read_b128 v[174:177], v214 offset:49152
	ds_read_b128 v[178:181], v214 offset:53248
	s_barrier
	s_waitcnt lgkmcnt(0)
	s_waitcnt lgkmcnt(0)
	v_mfma_f32_32x32x16_bf16 v[48:63], v[150:153], v[130:133], v[48:63]
	v_mfma_f32_32x32x16_bf16 v[32:47], v[154:157], v[130:133], v[32:47]
	v_mfma_f32_32x32x16_bf16 v[48:63], v[158:161], v[138:141], v[48:63]
	v_mfma_f32_32x32x16_bf16 v[32:47], v[162:165], v[138:141], v[32:47]
	v_mfma_f32_32x32x16_bf16 v[48:63], v[166:169], v[142:145], v[48:63]
	v_mfma_f32_32x32x16_bf16 v[32:47], v[170:173], v[142:145], v[32:47]
	v_mfma_f32_32x32x16_bf16 v[48:63], v[174:177], v[146:149], v[48:63]
	v_mfma_f32_32x32x16_bf16 v[32:47], v[178:181], v[146:149], v[32:47]
	v_mfma_f32_32x32x16_bf16 v[16:31], v[150:153], v[182:185], v[16:31]
	v_mfma_f32_32x32x16_bf16 v[0:15], v[154:157], v[182:185], v[0:15]
	v_mfma_f32_32x32x16_bf16 v[16:31], v[158:161], v[186:189], v[16:31]
	v_mfma_f32_32x32x16_bf16 v[0:15], v[162:165], v[186:189], v[0:15]
	v_mfma_f32_32x32x16_bf16 v[16:31], v[166:169], v[192:195], v[16:31]
	v_mfma_f32_32x32x16_bf16 v[0:15], v[170:173], v[192:195], v[0:15]
	v_mfma_f32_32x32x16_bf16 v[16:31], v[174:177], v[196:199], v[16:31]
	v_mfma_f32_32x32x16_bf16 v[0:15], v[178:181], v[196:199], v[0:15]
	s_barrier
	v_cmp_gt_u32_e32 vcc, s49, v134
	s_and_saveexec_b64 s[42:43], vcc
	s_cbranch_execz .LBB0_1833
	s_barrier
	s_branch .LBB0_1833

; #define G8_STA(b, h, kt) G8_STAGE(G8_SA(b, h), Ag, lda, h, kt)
; #define G8_STB(b, h, kt) G8_STAGE(G8_SB(b, h), Bg, ldb, h, kt)
; #define G8_LDA(b, h) do { _Pragma("unroll") for (int m_ = 0; m_ < 2; ++m_) _Pragma("unroll") for (int k_ = 0; k_ < 4; ++k_) \
;     At[m_][k_] = *reinterpret_cast<const LAS bf16x8*>(la + ((b) * 2 + (h)) * 16384 + m_ * 4096 + (((k_ * 2 + hi) ^ swz) << 4)); } while (0)
; #define G8_LDB(dst, b, h) do { _Pragma("unroll") for (int k_ = 0; k_ < 4; ++k_) \
;     dst[k_] = *reinterpret_cast<const LAS bf16x8*>(lb + ((b) * 2 + (h)) * 16384 + (((k_ * 2 + hi) ^ swz) << 4)); } while (0)
; #define G8_MMA(ai, bj, Bx) do { __builtin_amdgcn_s_setprio(1); _Pragma("unroll") for (int k_ = 0; k_ < 4; ++k_) _Pragma("unroll") for (int m_ = 0; m_ < 2; ++m_) \
;     acc[ai][bj][m_] = __builtin_amdgcn_mfma_f32_32x32x16_bf16(At[m_][k_], Bx[k_], acc[ai][bj][m_], 0, 0, 0); __builtin_amdgcn_s_setprio(0); } while (0)
; #define G8_WV(n) asm volatile("s_waitcnt vmcnt(" #n ")" ::: "memory")
; #define G8_WL(n) asm volatile("s_waitcnt lgkmcnt(" #n ")" ::: "memory")
; #define G8_BAR __builtin_amdgcn_s_barrier()
; #define G8_SCHED __builtin_amdgcn_sched_barrier(0)
; template <class Epi>
; __device__ __forceinline__ void gemm8p(const bf16_t* __restrict__ A, int lda, const bf16_t* __restrict__ Bt, int ldb, int K,
;                                        LP lds, const Epi& epi, bool pre = false, const bf16_t* An = nullptr, const bf16_t* Bn = nullptr) {
;     ...
;     G8_LDB(B0, 0, 0); G8_SCHED; G8_LDA(0, 0); G8_STA(1, 1, t + 1);
;     G8_WL(8); G8_BAR; G8_WL(0); G8_MMA(0, 0, B0); G8_BAR; G8_SCHED;
;     G8_LDB(B1, 0, 1); G8_STB(0, 0, t + 2);
;     G8_BAR; G8_WL(0); G8_MMA(0, 1, B1); G8_BAR; G8_SCHED;
;     G8_LDA(0, 1); G8_STA(0, 0, t + 2);
;     G8_BAR; G8_WL(0); G8_MMA(1, 0, B0); G8_BAR; G8_SCHED;
;     G8_STB(0, 1, t + 2);
;     G8_WV(6); G8_BAR; G8_MMA(1, 1, B1); G8_BAR; G8_SCHED;
;     G8_LDB(B0, 1, 0); G8_SCHED; G8_LDA(1, 0); G8_STA(0, 1, t + 2);
.LBB0_1953:
	ds_read_b128 v[168:171], v155
	ds_read_b128 v[172:175], v156
	ds_read_b128 v[176:179], v157
	ds_read_b128 v[180:183], v158
	v_lshl_add_u64 v[188:189], v[136:137], 0, v[128:129]
	v_readfirstlane_b32 s67, v166
	v_lshl_add_u64 v[220:221], v[188:189], 0, s[22:23]
	s_mov_b32 m0, s67
	v_readfirstlane_b32 s67, v165
	ds_read_b128 v[184:187], v154
	ds_read_b128 v[192:195], v154 offset:4096
	ds_read_b128 v[196:199], v153
	ds_read_b128 v[200:203], v153 offset:4096
	ds_read_b128 v[204:207], v152
	ds_read_b128 v[208:211], v152 offset:4096
	ds_read_b128 v[212:215], v131
	ds_read_b128 v[216:219], v131 offset:4096
	global_load_lds_dwordx4 v[220:221], off
	v_lshl_add_u64 v[220:221], v[188:189], 0, s[24:25]
	s_mov_b32 m0, s67
	s_nop 0
	global_load_lds_dwordx4 v[220:221], off
	s_waitcnt lgkmcnt(8)
	s_barrier
	s_waitcnt lgkmcnt(0)
	s_waitcnt lgkmcnt(0)
	v_mfma_f32_32x32x16_bf16 v[112:127], v[184:187], v[168:171], v[112:127]
	v_mfma_f32_32x32x16_bf16 v[96:111], v[192:195], v[168:171], v[96:111]
	v_mfma_f32_32x32x16_bf16 v[112:127], v[196:199], v[172:175], v[112:127]
	v_mfma_f32_32x32x16_bf16 v[96:111], v[200:203], v[172:175], v[96:111]
	v_mfma_f32_32x32x16_bf16 v[112:127], v[204:207], v[176:179], v[112:127]
	v_mfma_f32_32x32x16_bf16 v[96:111], v[208:211], v[176:179], v[96:111]
	v_mfma_f32_32x32x16_bf16 v[112:127], v[212:215], v[180:183], v[112:127]
	v_mfma_f32_32x32x16_bf16 v[96:111], v[216:219], v[180:183], v[96:111]
	s_barrier
	v_lshl_add_u64 v[236:237], v[138:139], 0, v[128:129]
	v_readfirstlane_b32 s67, v147
	v_lshl_add_u64 v[238:239], v[236:237], 0, s[26:27]
	s_mov_b32 m0, s67
	v_readfirstlane_b32 s67, v146
	ds_read_b128 v[220:223], v155 offset:16384
	ds_read_b128 v[224:227], v156 offset:16384
	ds_read_b128 v[228:231], v157 offset:16384
	ds_read_b128 v[232:235], v158 offset:16384
	global_load_lds_dwordx4 v[238:239], off
	v_lshl_add_u64 v[238:239], v[236:237], 0, s[28:29]
	s_mov_b32 m0, s67
	s_nop 0
	global_load_lds_dwordx4 v[238:239], off
	s_barrier
	s_waitcnt lgkmcnt(0)
	s_waitcnt lgkmcnt(0)
	v_mfma_f32_32x32x16_bf16 v[80:95], v[184:187], v[220:223], v[80:95]
	v_mfma_f32_32x32x16_bf16 v[64:79], v[192:195], v[220:223], v[64:79]
	v_mfma_f32_32x32x16_bf16 v[80:95], v[196:199], v[224:227], v[80:95]
	v_mfma_f32_32x32x16_bf16 v[64:79], v[200:203], v[224:227], v[64:79]
	v_mfma_f32_32x32x16_bf16 v[80:95], v[204:207], v[228:231], v[80:95]
	v_mfma_f32_32x32x16_bf16 v[64:79], v[208:211], v[228:231], v[64:79]
	v_mfma_f32_32x32x16_bf16 v[80:95], v[212:215], v[232:235], v[80:95]
	v_mfma_f32_32x32x16_bf16 v[64:79], v[216:219], v[232:235], v[64:79]
	s_barrier
	v_readfirstlane_b32 s67, v143
	v_lshl_add_u64 v[238:239], v[188:189], 0, s[30:31]
	s_mov_b32 m0, s67
	v_readfirstlane_b32 s67, v145
	ds_read_b128 v[184:187], v154 offset:16384
	ds_read_b128 v[192:195], v154 offset:20480
	ds_read_b128 v[196:199], v153 offset:16384
	ds_read_b128 v[200:203], v153 offset:20480
	ds_read_b128 v[204:207], v152 offset:16384
	ds_read_b128 v[208:211], v152 offset:20480
	ds_read_b128 v[212:215], v131 offset:16384
	ds_read_b128 v[216:219], v131 offset:20480
	global_load_lds_dwordx4 v[238:239], off
	v_lshl_add_u64 v[238:239], v[188:189], 0, s[36:37]
	s_mov_b32 m0, s67
	s_nop 0
	global_load_lds_dwordx4 v[238:239], off
	s_barrier
	s_waitcnt lgkmcnt(0)
	s_waitcnt lgkmcnt(0)
	v_mfma_f32_32x32x16_bf16 v[48:63], v[184:187], v[168:171], v[48:63]
	v_mfma_f32_32x32x16_bf16 v[32:47], v[192:195], v[168:171], v[32:47]
	v_mfma_f32_32x32x16_bf16 v[48:63], v[196:199], v[172:175], v[48:63]
	v_mfma_f32_32x32x16_bf16 v[32:47], v[200:203], v[172:175], v[32:47]
	v_mfma_f32_32x32x16_bf16 v[48:63], v[204:207], v[176:179], v[48:63]
	v_mfma_f32_32x32x16_bf16 v[32:47], v[208:211], v[176:179], v[32:47]
	v_mfma_f32_32x32x16_bf16 v[48:63], v[212:215], v[180:183], v[48:63]
	v_mfma_f32_32x32x16_bf16 v[32:47], v[216:219], v[180:183], v[32:47]
	s_barrier
	v_readfirstlane_b32 s67, v144
	v_lshl_add_u64 v[168:169], v[236:237], 0, s[38:39]
	s_mov_b32 m0, s67
	v_readfirstlane_b32 s67, v142
	global_load_lds_dwordx4 v[168:169], off
	v_lshl_add_u64 v[168:169], v[236:237], 0, s[40:41]
	s_mov_b32 m0, s67
	s_nop 0
	global_load_lds_dwordx4 v[168:169], off
	s_waitcnt vmcnt(6)
	s_barrier
	v_mfma_f32_32x32x16_bf16 v[16:31], v[184:187], v[220:223], v[16:31]
	v_mfma_f32_32x32x16_bf16 v[0:15], v[192:195], v[220:223], v[0:15]
	v_mfma_f32_32x32x16_bf16 v[16:31], v[196:199], v[224:227], v[16:31]
	v_mfma_f32_32x32x16_bf16 v[0:15], v[200:203], v[224:227], v[0:15]
	v_mfma_f32_32x32x16_bf16 v[16:31], v[204:207], v[228:231], v[16:31]
	v_mfma_f32_32x32x16_bf16 v[0:15], v[208:211], v[228:231], v[0:15]
	v_mfma_f32_32x32x16_bf16 v[16:31], v[212:215], v[232:235], v[16:31]
	v_mfma_f32_32x32x16_bf16 v[0:15], v[216:219], v[232:235], v[0:15]
	s_barrier
	ds_read_b128 v[168:171], v155 offset:32768
	ds_read_b128 v[172:175], v156 offset:32768
	ds_read_b128 v[176:179], v157 offset:32768
	ds_read_b128 v[180:183], v158 offset:32768
	v_readfirstlane_b32 s67, v141
	v_lshl_add_u64 v[220:221], v[188:189], 0, s[42:43]
	s_mov_b32 m0, s67
	v_readfirstlane_b32 s67, v140
	ds_read_b128 v[184:187], v154 offset:32768
	ds_read_b128 v[192:195], v154 offset:36864
	ds_read_b128 v[196:199], v153 offset:32768
	ds_read_b128 v[200:203], v153 offset:36864
	ds_read_b128 v[204:207], v152 offset:32768
	ds_read_b128 v[208:211], v152 offset:36864
	ds_read_b128 v[212:215], v131 offset:32768
	ds_read_b128 v[216:219], v131 offset:36864
	global_load_lds_dwordx4 v[220:221], off
	v_lshl_add_u64 v[220:221], v[188:189], 0, s[44:45]
	s_mov_b32 m0, s67
	s_nop 0
	global_load_lds_dwordx4 v[220:221], off
	s_waitcnt lgkmcnt(8)
	s_barrier
; #define G8_STA(b, h, kt) G8_STAGE(G8_SA(b, h), Ag, lda, h, kt)
; #define G8_STB(b, h, kt) G8_STAGE(G8_SB(b, h), Bg, ldb, h, kt)
; #define G8_LDA(b, h) do { _Pragma("unroll") for (int m_ = 0; m_ < 2; ++m_) _Pragma("unroll") for (int k_ = 0; k_ < 4; ++k_) \
;     At[m_][k_] = *reinterpret_cast<const LAS bf16x8*>(la + ((b) * 2 + (h)) * 16384 + m_ * 4096 + (((k_ * 2 + hi) ^ swz) << 4)); } while (0)
; #define G8_LDB(dst, b, h) do { _Pragma("unroll") for (int k_ = 0; k_ < 4; ++k_) \
;     dst[k_] = *reinterpret_cast<const LAS bf16x8*>(lb + ((b) * 2 + (h)) * 16384 + (((k_ * 2 + hi) ^ swz) << 4)); } while (0)
; #define G8_MMA(ai, bj, Bx) do { __builtin_amdgcn_s_setprio(1); _Pragma("unroll") for (int k_ = 0; k_ < 4; ++k_) _Pragma("unroll") for (int m_ = 0; m_ < 2; ++m_) \
;     acc[ai][bj][m_] = __builtin_amdgcn_mfma_f32_32x32x16_bf16(At[m_][k_], Bx[k_], acc[ai][bj][m_], 0, 0, 0); __builtin_amdgcn_s_setprio(0); } while (0)
; #define G8_WV(n) asm volatile("s_waitcnt vmcnt(" #n ")" ::: "memory")
; #define G8_WL(n) asm volatile("s_waitcnt lgkmcnt(" #n ")" ::: "memory")
; #define G8_BAR __builtin_amdgcn_s_barrier()
; #define G8_SCHED __builtin_amdgcn_sched_barrier(0)
; template <class Epi>
; __device__ __forceinline__ void gemm8p(const bf16_t* __restrict__ A, int lda, const bf16_t* __restrict__ Bt, int ldb, int K,
;                                        LP lds, const Epi& epi, bool pre = false, const bf16_t* An = nullptr, const bf16_t* Bn = nullptr) {
;     ...
;     G8_WL(8); G8_BAR; G8_WL(0); G8_MMA(0, 0, B0); G8_BAR; G8_SCHED;
;     G8_LDB(B1, 1, 1); G8_STB(1, 0, t + 3);
;     G8_BAR; G8_WL(0); G8_MMA(0, 1, B1); G8_BAR; G8_SCHED;
;     G8_LDA(1, 1); G8_STA(1, 0, t + 3);
;     G8_BAR; G8_WL(0); G8_MMA(1, 0, B0); G8_BAR; G8_SCHED;
;     G8_STB(1, 1, t + 3);
;     G8_WV(6); G8_BAR; G8_MMA(1, 1, B1); G8_BAR; G8_SCHED;
;   }
;   { G8_LDB(B0, 0, 0); G8_LDA(0, 0); G8_STA(1, 1, nt - 1);
;     G8_BAR; G8_WL(0); G8_MMA(0, 0, B0); G8_BAR; G8_SCHED;
;     G8_LDB(B1, 0, 1); G8_BAR; G8_WL(0); G8_MMA(0, 1, B1); G8_BAR; G8_SCHED;
	s_waitcnt lgkmcnt(0)
	s_waitcnt lgkmcnt(0)
	v_mfma_f32_32x32x16_bf16 v[112:127], v[184:187], v[168:171], v[112:127]
	v_mfma_f32_32x32x16_bf16 v[96:111], v[192:195], v[168:171], v[96:111]
	v_mfma_f32_32x32x16_bf16 v[112:127], v[196:199], v[172:175], v[112:127]
	v_mfma_f32_32x32x16_bf16 v[96:111], v[200:203], v[172:175], v[96:111]
	v_mfma_f32_32x32x16_bf16 v[112:127], v[204:207], v[176:179], v[112:127]
	v_mfma_f32_32x32x16_bf16 v[96:111], v[208:211], v[176:179], v[96:111]
	v_mfma_f32_32x32x16_bf16 v[112:127], v[212:215], v[180:183], v[112:127]
	v_mfma_f32_32x32x16_bf16 v[96:111], v[216:219], v[180:183], v[96:111]
	s_barrier
	v_readfirstlane_b32 s67, v159
	v_lshl_add_u64 v[238:239], v[236:237], 0, s[46:47]
	s_mov_b32 m0, s67
	v_readfirstlane_b32 s67, v160
	ds_read_b128 v[220:223], v155 offset:49152
	ds_read_b128 v[224:227], v156 offset:49152
	ds_read_b128 v[228:231], v157 offset:49152
	ds_read_b128 v[232:235], v158 offset:49152
	global_load_lds_dwordx4 v[238:239], off
	v_lshl_add_u64 v[238:239], v[236:237], 0, s[48:49]
	s_mov_b32 m0, s67
	s_nop 0
	global_load_lds_dwordx4 v[238:239], off
	s_barrier
	s_waitcnt lgkmcnt(0)
	s_waitcnt lgkmcnt(0)
	v_mfma_f32_32x32x16_bf16 v[80:95], v[184:187], v[220:223], v[80:95]
	v_mfma_f32_32x32x16_bf16 v[64:79], v[192:195], v[220:223], v[64:79]
	v_mfma_f32_32x32x16_bf16 v[80:95], v[196:199], v[224:227], v[80:95]
	v_mfma_f32_32x32x16_bf16 v[64:79], v[200:203], v[224:227], v[64:79]
	v_mfma_f32_32x32x16_bf16 v[80:95], v[204:207], v[228:231], v[80:95]
	v_mfma_f32_32x32x16_bf16 v[64:79], v[208:211], v[228:231], v[64:79]
	v_mfma_f32_32x32x16_bf16 v[80:95], v[212:215], v[232:235], v[80:95]
	v_mfma_f32_32x32x16_bf16 v[64:79], v[216:219], v[232:235], v[64:79]
	s_barrier
	v_readfirstlane_b32 s67, v161
	v_lshl_add_u64 v[238:239], v[188:189], 0, s[50:51]
	s_mov_b32 m0, s67
	v_readfirstlane_b32 s67, v162
	ds_read_b128 v[184:187], v154 offset:49152
	ds_read_b128 v[192:195], v154 offset:53248
	ds_read_b128 v[196:199], v153 offset:49152
	ds_read_b128 v[200:203], v153 offset:53248
	ds_read_b128 v[204:207], v152 offset:49152
	ds_read_b128 v[208:211], v152 offset:53248
	ds_read_b128 v[212:215], v131 offset:49152
	ds_read_b128 v[216:219], v131 offset:53248
	global_load_lds_dwordx4 v[238:239], off
	v_lshl_add_u64 v[188:189], v[188:189], 0, s[52:53]
	s_mov_b32 m0, s67
	s_nop 0
	global_load_lds_dwordx4 v[188:189], off
	s_barrier
	s_waitcnt lgkmcnt(0)
	s_waitcnt lgkmcnt(0)
	v_mfma_f32_32x32x16_bf16 v[48:63], v[184:187], v[168:171], v[48:63]
	v_mfma_f32_32x32x16_bf16 v[32:47], v[192:195], v[168:171], v[32:47]
	v_mfma_f32_32x32x16_bf16 v[48:63], v[196:199], v[172:175], v[48:63]
	v_mfma_f32_32x32x16_bf16 v[32:47], v[200:203], v[172:175], v[32:47]
	v_mfma_f32_32x32x16_bf16 v[48:63], v[204:207], v[176:179], v[48:63]
	v_mfma_f32_32x32x16_bf16 v[32:47], v[208:211], v[176:179], v[32:47]
	v_mfma_f32_32x32x16_bf16 v[48:63], v[212:215], v[180:183], v[48:63]
	v_mfma_f32_32x32x16_bf16 v[32:47], v[216:219], v[180:183], v[32:47]
	s_barrier
	v_readfirstlane_b32 s67, v163
	v_lshl_add_u64 v[168:169], v[236:237], 0, s[54:55]
	s_mov_b32 m0, s67
	v_readfirstlane_b32 s67, v164
	global_load_lds_dwordx4 v[168:169], off
	v_lshl_add_u64 v[168:169], v[236:237], 0, s[56:57]
	s_mov_b32 m0, s67
	s_nop 0
	global_load_lds_dwordx4 v[168:169], off
	s_waitcnt vmcnt(6)
	s_barrier
	v_mfma_f32_32x32x16_bf16 v[16:31], v[184:187], v[220:223], v[16:31]
	v_mfma_f32_32x32x16_bf16 v[0:15], v[192:195], v[220:223], v[0:15]
	v_mfma_f32_32x32x16_bf16 v[16:31], v[196:199], v[224:227], v[16:31]
	v_mfma_f32_32x32x16_bf16 v[0:15], v[200:203], v[224:227], v[0:15]
	v_mfma_f32_32x32x16_bf16 v[16:31], v[204:207], v[228:231], v[16:31]
	v_mfma_f32_32x32x16_bf16 v[0:15], v[208:211], v[228:231], v[0:15]
	v_mfma_f32_32x32x16_bf16 v[16:31], v[212:215], v[232:235], v[16:31]
	v_mfma_f32_32x32x16_bf16 v[0:15], v[216:219], v[232:235], v[0:15]
	s_barrier
	s_add_i32 s65, s65, 2
	v_lshl_add_u64 v[136:137], v[136:137], 0, s[58:59]
	s_cmp_lt_u32 s65, 12
	v_lshl_add_u64 v[138:139], v[138:139], 0, s[58:59]
	s_cbranch_scc1 .LBB0_1953
	v_readfirstlane_b32 s65, v166
	v_lshl_add_u64 v[188:189], v[134:135], 0, s[60:61]
	s_mov_b32 m0, s65
	v_readfirstlane_b32 s65, v165
	ds_read_b128 v[136:139], v155
	ds_read_b128 v[160:163], v156
	ds_read_b128 v[168:171], v157
	ds_read_b128 v[172:175], v158
	ds_read_b128 v[176:179], v154
	ds_read_b128 v[180:183], v154 offset:4096
	ds_read_b128 v[184:187], v153
	ds_read_b128 v[192:195], v153 offset:4096
	ds_read_b128 v[196:199], v152
	ds_read_b128 v[200:203], v152 offset:4096
	ds_read_b128 v[204:207], v131
	ds_read_b128 v[208:211], v131 offset:4096
	global_load_lds_dwordx4 v[188:189], off
	v_lshl_add_u64 v[134:135], v[134:135], 0, s[62:63]
	s_mov_b32 m0, s65
	s_nop 0
	global_load_lds_dwordx4 v[134:135], off
	s_barrier
	s_waitcnt lgkmcnt(0)
	s_waitcnt lgkmcnt(0)
	v_mfma_f32_32x32x16_bf16 v[112:127], v[176:179], v[136:139], v[112:127]
	v_mfma_f32_32x32x16_bf16 v[96:111], v[180:183], v[136:139], v[96:111]
	v_mfma_f32_32x32x16_bf16 v[112:127], v[184:187], v[160:163], v[112:127]
	v_mfma_f32_32x32x16_bf16 v[96:111], v[192:195], v[160:163], v[96:111]
	v_mfma_f32_32x32x16_bf16 v[112:127], v[196:199], v[168:171], v[112:127]
	v_mfma_f32_32x32x16_bf16 v[96:111], v[200:203], v[168:171], v[96:111]
	v_mfma_f32_32x32x16_bf16 v[112:127], v[204:207], v[172:175], v[112:127]
	v_mfma_f32_32x32x16_bf16 v[96:111], v[208:211], v[172:175], v[96:111]
	s_barrier
	ds_read_b128 v[164:167], v155 offset:16384
	ds_read_b128 v[212:215], v156 offset:16384
	ds_read_b128 v[216:219], v157 offset:16384
	ds_read_b128 v[220:223], v158 offset:16384
	s_barrier
; #define G8_LDA(b, h) do { _Pragma("unroll") for (int m_ = 0; m_ < 2; ++m_) _Pragma("unroll") for (int k_ = 0; k_ < 4; ++k_) \
;     At[m_][k_] = *reinterpret_cast<const LAS bf16x8*>(la + ((b) * 2 + (h)) * 16384 + m_ * 4096 + (((k_ * 2 + hi) ^ swz) << 4)); } while (0)
; #define G8_LDB(dst, b, h) do { _Pragma("unroll") for (int k_ = 0; k_ < 4; ++k_) \
;     dst[k_] = *reinterpret_cast<const LAS bf16x8*>(lb + ((b) * 2 + (h)) * 16384 + (((k_ * 2 + hi) ^ swz) << 4)); } while (0)
; #define G8_MMA(ai, bj, Bx) do { __builtin_amdgcn_s_setprio(1); _Pragma("unroll") for (int k_ = 0; k_ < 4; ++k_) _Pragma("unroll") for (int m_ = 0; m_ < 2; ++m_) \
;     acc[ai][bj][m_] = __builtin_amdgcn_mfma_f32_32x32x16_bf16(At[m_][k_], Bx[k_], acc[ai][bj][m_], 0, 0, 0); __builtin_amdgcn_s_setprio(0); } while (0)
; #define G8_WV(n) asm volatile("s_waitcnt vmcnt(" #n ")" ::: "memory")
; #define G8_WL(n) asm volatile("s_waitcnt lgkmcnt(" #n ")" ::: "memory")
; #define G8_BAR __builtin_amdgcn_s_barrier()
; #define G8_SCHED __builtin_amdgcn_sched_barrier(0)
; template <class Epi>
; __device__ __forceinline__ void gemm8p(const bf16_t* __restrict__ A, int lda, const bf16_t* __restrict__ Bt, int ldb, int K,
;                                        LP lds, const Epi& epi, bool pre = false, const bf16_t* An = nullptr, const bf16_t* Bn = nullptr) {
;     ...
;     G8_LDB(B1, 0, 1); G8_BAR; G8_WL(0); G8_MMA(0, 1, B1); G8_BAR; G8_SCHED;
;     G8_LDA(0, 1); G8_WV(4); G8_BAR; G8_WL(0); G8_MMA(1, 0, B0); G8_MMA(1, 1, B1); G8_BAR; G8_SCHED; }
;   { G8_LDB(B0, 1, 0); G8_LDA(1, 0); G8_WV(2); G8_BAR; G8_WL(0); G8_MMA(0, 0, B0); G8_BAR; G8_SCHED;
;     G8_LDB(B1, 1, 1); G8_WV(0); G8_BAR; G8_WL(0); G8_MMA(0, 1, B1); G8_BAR; G8_SCHED;
;     G8_LDA(1, 1); G8_BAR; G8_WL(0); G8_MMA(1, 0, B0); G8_MMA(1, 1, B1); G8_BAR; G8_SCHED; }
;   if (wr == 0) G8_BAR;
	s_waitcnt lgkmcnt(0)
	s_waitcnt lgkmcnt(0)
	v_mfma_f32_32x32x16_bf16 v[80:95], v[176:179], v[164:167], v[80:95]
	v_mfma_f32_32x32x16_bf16 v[64:79], v[180:183], v[164:167], v[64:79]
	v_mfma_f32_32x32x16_bf16 v[80:95], v[184:187], v[212:215], v[80:95]
	v_mfma_f32_32x32x16_bf16 v[64:79], v[192:195], v[212:215], v[64:79]
	v_mfma_f32_32x32x16_bf16 v[80:95], v[196:199], v[216:219], v[80:95]
	v_mfma_f32_32x32x16_bf16 v[64:79], v[200:203], v[216:219], v[64:79]
	v_mfma_f32_32x32x16_bf16 v[80:95], v[204:207], v[220:223], v[80:95]
	v_mfma_f32_32x32x16_bf16 v[64:79], v[208:211], v[220:223], v[64:79]
	s_barrier
	ds_read_b128 v[176:179], v154 offset:16384
	ds_read_b128 v[180:183], v154 offset:20480
	ds_read_b128 v[184:187], v153 offset:16384
	ds_read_b128 v[192:195], v153 offset:20480
	ds_read_b128 v[196:199], v152 offset:16384
	ds_read_b128 v[200:203], v152 offset:20480
	ds_read_b128 v[204:207], v131 offset:16384
	ds_read_b128 v[208:211], v131 offset:20480
	s_waitcnt vmcnt(4)
	s_barrier
	s_waitcnt lgkmcnt(0)
	s_waitcnt lgkmcnt(0)
	v_mfma_f32_32x32x16_bf16 v[48:63], v[176:179], v[136:139], v[48:63]
	v_mfma_f32_32x32x16_bf16 v[32:47], v[180:183], v[136:139], v[32:47]
	v_mfma_f32_32x32x16_bf16 v[48:63], v[184:187], v[160:163], v[48:63]
	v_mfma_f32_32x32x16_bf16 v[32:47], v[192:195], v[160:163], v[32:47]
	v_mfma_f32_32x32x16_bf16 v[48:63], v[196:199], v[168:171], v[48:63]
	v_mfma_f32_32x32x16_bf16 v[32:47], v[200:203], v[168:171], v[32:47]
	v_mfma_f32_32x32x16_bf16 v[48:63], v[204:207], v[172:175], v[48:63]
	v_mfma_f32_32x32x16_bf16 v[32:47], v[208:211], v[172:175], v[32:47]
	v_mfma_f32_32x32x16_bf16 v[16:31], v[176:179], v[164:167], v[16:31]
	v_mfma_f32_32x32x16_bf16 v[0:15], v[180:183], v[164:167], v[0:15]
	v_mfma_f32_32x32x16_bf16 v[16:31], v[184:187], v[212:215], v[16:31]
	v_mfma_f32_32x32x16_bf16 v[0:15], v[192:195], v[212:215], v[0:15]
	v_mfma_f32_32x32x16_bf16 v[16:31], v[196:199], v[216:219], v[16:31]
	v_mfma_f32_32x32x16_bf16 v[0:15], v[200:203], v[216:219], v[0:15]
	v_mfma_f32_32x32x16_bf16 v[16:31], v[204:207], v[220:223], v[16:31]
	v_mfma_f32_32x32x16_bf16 v[0:15], v[208:211], v[220:223], v[0:15]
	s_barrier
	ds_read_b128 v[134:137], v155 offset:32768
	ds_read_b128 v[160:163], v156 offset:32768
	ds_read_b128 v[164:167], v157 offset:32768
	ds_read_b128 v[168:171], v158 offset:32768
	ds_read_b128 v[172:175], v154 offset:32768
	ds_read_b128 v[176:179], v154 offset:36864
	ds_read_b128 v[180:183], v153 offset:32768
	ds_read_b128 v[184:187], v153 offset:36864
	ds_read_b128 v[192:195], v152 offset:32768
	ds_read_b128 v[196:199], v152 offset:36864
	ds_read_b128 v[200:203], v131 offset:32768
	ds_read_b128 v[204:207], v131 offset:36864
	s_waitcnt vmcnt(2)
	s_barrier
	s_waitcnt lgkmcnt(0)
	s_waitcnt lgkmcnt(0)
	v_mfma_f32_32x32x16_bf16 v[112:127], v[172:175], v[134:137], v[112:127]
	v_mfma_f32_32x32x16_bf16 v[96:111], v[176:179], v[134:137], v[96:111]
	v_mfma_f32_32x32x16_bf16 v[112:127], v[180:183], v[160:163], v[112:127]
	v_mfma_f32_32x32x16_bf16 v[96:111], v[184:187], v[160:163], v[96:111]
	v_mfma_f32_32x32x16_bf16 v[112:127], v[192:195], v[164:167], v[112:127]
	v_mfma_f32_32x32x16_bf16 v[96:111], v[196:199], v[164:167], v[96:111]
	v_mfma_f32_32x32x16_bf16 v[112:127], v[200:203], v[168:171], v[112:127]
	v_mfma_f32_32x32x16_bf16 v[96:111], v[204:207], v[168:171], v[96:111]
	s_barrier
	ds_read_b128 v[208:211], v155 offset:49152
	ds_read_b128 v[212:215], v156 offset:49152
	ds_read_b128 v[216:219], v157 offset:49152
	ds_read_b128 v[156:159], v158 offset:49152
	s_waitcnt vmcnt(0)
	s_barrier
	s_waitcnt lgkmcnt(0)
	s_waitcnt lgkmcnt(0)
	v_mfma_f32_32x32x16_bf16 v[80:95], v[172:175], v[208:211], v[80:95]
	v_mfma_f32_32x32x16_bf16 v[64:79], v[176:179], v[208:211], v[64:79]
	v_mfma_f32_32x32x16_bf16 v[80:95], v[180:183], v[212:215], v[80:95]
	v_mfma_f32_32x32x16_bf16 v[64:79], v[184:187], v[212:215], v[64:79]
	v_mfma_f32_32x32x16_bf16 v[80:95], v[192:195], v[216:219], v[80:95]
	v_mfma_f32_32x32x16_bf16 v[64:79], v[196:199], v[216:219], v[64:79]
	v_mfma_f32_32x32x16_bf16 v[80:95], v[200:203], v[156:159], v[80:95]
	v_mfma_f32_32x32x16_bf16 v[64:79], v[204:207], v[156:159], v[64:79]
	s_barrier
	ds_read_b128 v[172:175], v154 offset:49152
	ds_read_b128 v[176:179], v154 offset:53248
	ds_read_b128 v[180:183], v153 offset:49152
	ds_read_b128 v[184:187], v153 offset:53248
	ds_read_b128 v[192:195], v152 offset:49152
	ds_read_b128 v[152:155], v152 offset:53248
	ds_read_b128 v[196:199], v131 offset:49152
	ds_read_b128 v[200:203], v131 offset:53248
	s_barrier
	s_waitcnt lgkmcnt(0)
	s_waitcnt lgkmcnt(0)
	v_mfma_f32_32x32x16_bf16 v[48:63], v[172:175], v[134:137], v[48:63]
	v_mfma_f32_32x32x16_bf16 v[32:47], v[176:179], v[134:137], v[32:47]
	v_mfma_f32_32x32x16_bf16 v[48:63], v[180:183], v[160:163], v[48:63]
	v_mfma_f32_32x32x16_bf16 v[32:47], v[184:187], v[160:163], v[32:47]
	v_mfma_f32_32x32x16_bf16 v[48:63], v[192:195], v[164:167], v[48:63]
	v_mfma_f32_32x32x16_bf16 v[32:47], v[152:155], v[164:167], v[32:47]
	v_mfma_f32_32x32x16_bf16 v[48:63], v[196:199], v[168:171], v[48:63]
	v_mfma_f32_32x32x16_bf16 v[32:47], v[200:203], v[168:171], v[32:47]
	v_mfma_f32_32x32x16_bf16 v[16:31], v[172:175], v[208:211], v[16:31]
	v_mfma_f32_32x32x16_bf16 v[0:15], v[176:179], v[208:211], v[0:15]
	v_mfma_f32_32x32x16_bf16 v[16:31], v[180:183], v[212:215], v[16:31]
	v_mfma_f32_32x32x16_bf16 v[0:15], v[184:187], v[212:215], v[0:15]
	v_mfma_f32_32x32x16_bf16 v[16:31], v[192:195], v[216:219], v[16:31]
	v_mfma_f32_32x32x16_bf16 v[0:15], v[152:155], v[216:219], v[0:15]
	v_mfma_f32_32x32x16_bf16 v[16:31], v[196:199], v[156:159], v[16:31]
	v_mfma_f32_32x32x16_bf16 v[0:15], v[200:203], v[156:159], v[0:15]
	s_barrier
	v_cmp_gt_u32_e32 vcc, s80, v148
	s_and_saveexec_b64 s[68:69], vcc
	s_cbranch_execz .LBB0_1956
	s_barrier

; #define G8_STA(b, h, kt) G8_STAGE(G8_SA(b, h), Ag, lda, h, kt)
; #define G8_STB(b, h, kt) G8_STAGE(G8_SB(b, h), Bg, ldb, h, kt)
; #define G8_LDA(b, h) do { _Pragma("unroll") for (int m_ = 0; m_ < 2; ++m_) _Pragma("unroll") for (int k_ = 0; k_ < 4; ++k_) \
;     At[m_][k_] = *reinterpret_cast<const LAS bf16x8*>(la + ((b) * 2 + (h)) * 16384 + m_ * 4096 + (((k_ * 2 + hi) ^ swz) << 4)); } while (0)
; #define G8_LDB(dst, b, h) do { _Pragma("unroll") for (int k_ = 0; k_ < 4; ++k_) \
;     dst[k_] = *reinterpret_cast<const LAS bf16x8*>(lb + ((b) * 2 + (h)) * 16384 + (((k_ * 2 + hi) ^ swz) << 4)); } while (0)
; #define G8_MMA(ai, bj, Bx) do { __builtin_amdgcn_s_setprio(1); _Pragma("unroll") for (int k_ = 0; k_ < 4; ++k_) _Pragma("unroll") for (int m_ = 0; m_ < 2; ++m_) \
;     acc[ai][bj][m_] = __builtin_amdgcn_mfma_f32_32x32x16_bf16(At[m_][k_], Bx[k_], acc[ai][bj][m_], 0, 0, 0); __builtin_amdgcn_s_setprio(0); } while (0)
; #define G8_WV(n) asm volatile("s_waitcnt vmcnt(" #n ")" ::: "memory")
; #define G8_WL(n) asm volatile("s_waitcnt lgkmcnt(" #n ")" ::: "memory")
; #define G8_BAR __builtin_amdgcn_s_barrier()
; #define G8_SCHED __builtin_amdgcn_sched_barrier(0)
; template <class Epi>
; __device__ __forceinline__ void gemm8p(const bf16_t* __restrict__ A, int lda, const bf16_t* __restrict__ Bt, int ldb, int K,
;                                        LP lds, const Epi& epi, bool pre = false, const bf16_t* An = nullptr, const bf16_t* Bn = nullptr) {
;     ...
;     G8_LDB(B0, 0, 0); G8_SCHED; G8_LDA(0, 0); G8_STA(1, 1, t + 1);
;     G8_WL(8); G8_BAR; G8_WL(0); G8_MMA(0, 0, B0); G8_BAR; G8_SCHED;
;     G8_LDB(B1, 0, 1); G8_STB(0, 0, t + 2);
;     G8_BAR; G8_WL(0); G8_MMA(0, 1, B1); G8_BAR; G8_SCHED;
;     G8_LDA(0, 1); G8_STA(0, 0, t + 2);
;     G8_BAR; G8_WL(0); G8_MMA(1, 0, B0); G8_BAR; G8_SCHED;
;     G8_STB(0, 1, t + 2);
;     G8_WV(6); G8_BAR; G8_MMA(1, 1, B1); G8_BAR; G8_SCHED;
;     G8_LDB(B0, 1, 0); G8_SCHED; G8_LDA(1, 0); G8_STA(0, 1, t + 2);
.LBB0_2203:
	ds_read_b128 v[168:171], v155
	ds_read_b128 v[172:175], v156
	ds_read_b128 v[176:179], v157
	ds_read_b128 v[180:183], v158
	v_lshl_add_u64 v[188:189], v[138:139], 0, v[128:129]
	v_readfirstlane_b32 s70, v166
	v_lshl_add_u64 v[220:221], v[188:189], 0, s[18:19]
	s_mov_b32 m0, s70
	v_readfirstlane_b32 s70, v165
	ds_read_b128 v[184:187], v154
	ds_read_b128 v[192:195], v154 offset:4096
	ds_read_b128 v[196:199], v153
	ds_read_b128 v[200:203], v153 offset:4096
	ds_read_b128 v[204:207], v152
	ds_read_b128 v[208:211], v152 offset:4096
	ds_read_b128 v[212:215], v131
	ds_read_b128 v[216:219], v131 offset:4096
	global_load_lds_dwordx4 v[220:221], off
	v_lshl_add_u64 v[220:221], v[188:189], 0, s[20:21]
	s_mov_b32 m0, s70
	s_nop 0
	global_load_lds_dwordx4 v[220:221], off
	s_waitcnt lgkmcnt(8)
	s_barrier
	s_waitcnt lgkmcnt(0)
	s_waitcnt lgkmcnt(0)
	v_mfma_f32_32x32x16_bf16 v[112:127], v[184:187], v[168:171], v[112:127]
	v_mfma_f32_32x32x16_bf16 v[96:111], v[192:195], v[168:171], v[96:111]
	v_mfma_f32_32x32x16_bf16 v[112:127], v[196:199], v[172:175], v[112:127]
	v_mfma_f32_32x32x16_bf16 v[96:111], v[200:203], v[172:175], v[96:111]
	v_mfma_f32_32x32x16_bf16 v[112:127], v[204:207], v[176:179], v[112:127]
	v_mfma_f32_32x32x16_bf16 v[96:111], v[208:211], v[176:179], v[96:111]
	v_mfma_f32_32x32x16_bf16 v[112:127], v[212:215], v[180:183], v[112:127]
	v_mfma_f32_32x32x16_bf16 v[96:111], v[216:219], v[180:183], v[96:111]
	s_barrier
	v_lshl_add_u64 v[236:237], v[136:137], 0, v[128:129]
	v_readfirstlane_b32 s70, v147
	v_lshl_add_u64 v[238:239], v[236:237], 0, s[22:23]
	s_mov_b32 m0, s70
	v_readfirstlane_b32 s70, v146
	ds_read_b128 v[220:223], v155 offset:16384
	ds_read_b128 v[224:227], v156 offset:16384
	ds_read_b128 v[228:231], v157 offset:16384
	ds_read_b128 v[232:235], v158 offset:16384
	global_load_lds_dwordx4 v[238:239], off
	v_lshl_add_u64 v[238:239], v[236:237], 0, s[24:25]
	s_mov_b32 m0, s70
	s_nop 0
	global_load_lds_dwordx4 v[238:239], off
	s_barrier
	s_waitcnt lgkmcnt(0)
	s_waitcnt lgkmcnt(0)
	v_mfma_f32_32x32x16_bf16 v[80:95], v[184:187], v[220:223], v[80:95]
	v_mfma_f32_32x32x16_bf16 v[64:79], v[192:195], v[220:223], v[64:79]
	v_mfma_f32_32x32x16_bf16 v[80:95], v[196:199], v[224:227], v[80:95]
	v_mfma_f32_32x32x16_bf16 v[64:79], v[200:203], v[224:227], v[64:79]
	v_mfma_f32_32x32x16_bf16 v[80:95], v[204:207], v[228:231], v[80:95]
	v_mfma_f32_32x32x16_bf16 v[64:79], v[208:211], v[228:231], v[64:79]
	v_mfma_f32_32x32x16_bf16 v[80:95], v[212:215], v[232:235], v[80:95]
	v_mfma_f32_32x32x16_bf16 v[64:79], v[216:219], v[232:235], v[64:79]
	s_barrier
	v_readfirstlane_b32 s70, v142
	v_lshl_add_u64 v[238:239], v[188:189], 0, s[26:27]
	s_mov_b32 m0, s70
	v_readfirstlane_b32 s70, v145
	ds_read_b128 v[184:187], v154 offset:16384
	ds_read_b128 v[192:195], v154 offset:20480
	ds_read_b128 v[196:199], v153 offset:16384
	ds_read_b128 v[200:203], v153 offset:20480
	ds_read_b128 v[204:207], v152 offset:16384
	ds_read_b128 v[208:211], v152 offset:20480
	ds_read_b128 v[212:215], v131 offset:16384
	ds_read_b128 v[216:219], v131 offset:20480
	global_load_lds_dwordx4 v[238:239], off
	v_lshl_add_u64 v[238:239], v[188:189], 0, s[28:29]
	s_mov_b32 m0, s70
	s_nop 0
	global_load_lds_dwordx4 v[238:239], off
	s_barrier
	s_waitcnt lgkmcnt(0)
	s_waitcnt lgkmcnt(0)
	v_mfma_f32_32x32x16_bf16 v[48:63], v[184:187], v[168:171], v[48:63]
	v_mfma_f32_32x32x16_bf16 v[32:47], v[192:195], v[168:171], v[32:47]
	v_mfma_f32_32x32x16_bf16 v[48:63], v[196:199], v[172:175], v[48:63]
	v_mfma_f32_32x32x16_bf16 v[32:47], v[200:203], v[172:175], v[32:47]
	v_mfma_f32_32x32x16_bf16 v[48:63], v[204:207], v[176:179], v[48:63]
	v_mfma_f32_32x32x16_bf16 v[32:47], v[208:211], v[176:179], v[32:47]
	v_mfma_f32_32x32x16_bf16 v[48:63], v[212:215], v[180:183], v[48:63]
	v_mfma_f32_32x32x16_bf16 v[32:47], v[216:219], v[180:183], v[32:47]
	s_barrier
	v_readfirstlane_b32 s70, v144
	v_lshl_add_u64 v[168:169], v[236:237], 0, s[30:31]
	s_mov_b32 m0, s70
	v_readfirstlane_b32 s70, v143
	global_load_lds_dwordx4 v[168:169], off
	v_lshl_add_u64 v[168:169], v[236:237], 0, s[36:37]
	s_mov_b32 m0, s70
	s_nop 0
	global_load_lds_dwordx4 v[168:169], off
	s_waitcnt vmcnt(6)
	s_barrier
	v_mfma_f32_32x32x16_bf16 v[16:31], v[184:187], v[220:223], v[16:31]
	v_mfma_f32_32x32x16_bf16 v[0:15], v[192:195], v[220:223], v[0:15]
	v_mfma_f32_32x32x16_bf16 v[16:31], v[196:199], v[224:227], v[16:31]
	v_mfma_f32_32x32x16_bf16 v[0:15], v[200:203], v[224:227], v[0:15]
	v_mfma_f32_32x32x16_bf16 v[16:31], v[204:207], v[228:231], v[16:31]
	v_mfma_f32_32x32x16_bf16 v[0:15], v[208:211], v[228:231], v[0:15]
	v_mfma_f32_32x32x16_bf16 v[16:31], v[212:215], v[232:235], v[16:31]
	v_mfma_f32_32x32x16_bf16 v[0:15], v[216:219], v[232:235], v[0:15]
	s_barrier
	ds_read_b128 v[168:171], v155 offset:32768
	ds_read_b128 v[172:175], v156 offset:32768
	ds_read_b128 v[176:179], v157 offset:32768
	ds_read_b128 v[180:183], v158 offset:32768
	v_readfirstlane_b32 s70, v141
	v_lshl_add_u64 v[220:221], v[188:189], 0, s[38:39]
	s_mov_b32 m0, s70
	v_readfirstlane_b32 s70, v140
	ds_read_b128 v[184:187], v154 offset:32768
	ds_read_b128 v[192:195], v154 offset:36864
	ds_read_b128 v[196:199], v153 offset:32768
	ds_read_b128 v[200:203], v153 offset:36864
	ds_read_b128 v[204:207], v152 offset:32768
	ds_read_b128 v[208:211], v152 offset:36864
	ds_read_b128 v[212:215], v131 offset:32768
	ds_read_b128 v[216:219], v131 offset:36864
	global_load_lds_dwordx4 v[220:221], off
	v_lshl_add_u64 v[220:221], v[188:189], 0, s[40:41]
	s_mov_b32 m0, s70
	s_nop 0
	global_load_lds_dwordx4 v[220:221], off
	s_waitcnt lgkmcnt(8)
	s_barrier
; #define G8_STA(b, h, kt) G8_STAGE(G8_SA(b, h), Ag, lda, h, kt)
; #define G8_STB(b, h, kt) G8_STAGE(G8_SB(b, h), Bg, ldb, h, kt)
; #define G8_LDA(b, h) do { _Pragma("unroll") for (int m_ = 0; m_ < 2; ++m_) _Pragma("unroll") for (int k_ = 0; k_ < 4; ++k_) \
;     At[m_][k_] = *reinterpret_cast<const LAS bf16x8*>(la + ((b) * 2 + (h)) * 16384 + m_ * 4096 + (((k_ * 2 + hi) ^ swz) << 4)); } while (0)
; #define G8_LDB(dst, b, h) do { _Pragma("unroll") for (int k_ = 0; k_ < 4; ++k_) \
;     dst[k_] = *reinterpret_cast<const LAS bf16x8*>(lb + ((b) * 2 + (h)) * 16384 + (((k_ * 2 + hi) ^ swz) << 4)); } while (0)
; #define G8_MMA(ai, bj, Bx) do { __builtin_amdgcn_s_setprio(1); _Pragma("unroll") for (int k_ = 0; k_ < 4; ++k_) _Pragma("unroll") for (int m_ = 0; m_ < 2; ++m_) \
;     acc[ai][bj][m_] = __builtin_amdgcn_mfma_f32_32x32x16_bf16(At[m_][k_], Bx[k_], acc[ai][bj][m_], 0, 0, 0); __builtin_amdgcn_s_setprio(0); } while (0)
; #define G8_WV(n) asm volatile("s_waitcnt vmcnt(" #n ")" ::: "memory")
; #define G8_WL(n) asm volatile("s_waitcnt lgkmcnt(" #n ")" ::: "memory")
; #define G8_BAR __builtin_amdgcn_s_barrier()
; #define G8_SCHED __builtin_amdgcn_sched_barrier(0)
; template <class Epi>
; __device__ __forceinline__ void gemm8p(const bf16_t* __restrict__ A, int lda, const bf16_t* __restrict__ Bt, int ldb, int K,
;                                        LP lds, const Epi& epi, bool pre = false, const bf16_t* An = nullptr, const bf16_t* Bn = nullptr) {
;     ...
;     G8_WL(8); G8_BAR; G8_WL(0); G8_MMA(0, 0, B0); G8_BAR; G8_SCHED;
;     G8_LDB(B1, 1, 1); G8_STB(1, 0, t + 3);
;     G8_BAR; G8_WL(0); G8_MMA(0, 1, B1); G8_BAR; G8_SCHED;
;     G8_LDA(1, 1); G8_STA(1, 0, t + 3);
;     G8_BAR; G8_WL(0); G8_MMA(1, 0, B0); G8_BAR; G8_SCHED;
;     G8_STB(1, 1, t + 3);
;     G8_WV(6); G8_BAR; G8_MMA(1, 1, B1); G8_BAR; G8_SCHED;
;   }
;   { G8_LDB(B0, 0, 0); G8_LDA(0, 0); G8_STA(1, 1, nt - 1);
;     G8_BAR; G8_WL(0); G8_MMA(0, 0, B0); G8_BAR; G8_SCHED;
;     G8_LDB(B1, 0, 1); G8_BAR; G8_WL(0); G8_MMA(0, 1, B1); G8_BAR; G8_SCHED;
	s_waitcnt lgkmcnt(0)
	s_waitcnt lgkmcnt(0)
	v_mfma_f32_32x32x16_bf16 v[112:127], v[184:187], v[168:171], v[112:127]
	v_mfma_f32_32x32x16_bf16 v[96:111], v[192:195], v[168:171], v[96:111]
	v_mfma_f32_32x32x16_bf16 v[112:127], v[196:199], v[172:175], v[112:127]
	v_mfma_f32_32x32x16_bf16 v[96:111], v[200:203], v[172:175], v[96:111]
	v_mfma_f32_32x32x16_bf16 v[112:127], v[204:207], v[176:179], v[112:127]
	v_mfma_f32_32x32x16_bf16 v[96:111], v[208:211], v[176:179], v[96:111]
	v_mfma_f32_32x32x16_bf16 v[112:127], v[212:215], v[180:183], v[112:127]
	v_mfma_f32_32x32x16_bf16 v[96:111], v[216:219], v[180:183], v[96:111]
	s_barrier
	v_readfirstlane_b32 s70, v159
	v_lshl_add_u64 v[238:239], v[236:237], 0, s[42:43]
	s_mov_b32 m0, s70
	v_readfirstlane_b32 s70, v160
	ds_read_b128 v[220:223], v155 offset:49152
	ds_read_b128 v[224:227], v156 offset:49152
	ds_read_b128 v[228:231], v157 offset:49152
	ds_read_b128 v[232:235], v158 offset:49152
	global_load_lds_dwordx4 v[238:239], off
	v_lshl_add_u64 v[238:239], v[236:237], 0, s[44:45]
	s_mov_b32 m0, s70
	s_nop 0
	global_load_lds_dwordx4 v[238:239], off
	s_barrier
	s_waitcnt lgkmcnt(0)
	s_waitcnt lgkmcnt(0)
	v_mfma_f32_32x32x16_bf16 v[80:95], v[184:187], v[220:223], v[80:95]
	v_mfma_f32_32x32x16_bf16 v[64:79], v[192:195], v[220:223], v[64:79]
	v_mfma_f32_32x32x16_bf16 v[80:95], v[196:199], v[224:227], v[80:95]
	v_mfma_f32_32x32x16_bf16 v[64:79], v[200:203], v[224:227], v[64:79]
	v_mfma_f32_32x32x16_bf16 v[80:95], v[204:207], v[228:231], v[80:95]
	v_mfma_f32_32x32x16_bf16 v[64:79], v[208:211], v[228:231], v[64:79]
	v_mfma_f32_32x32x16_bf16 v[80:95], v[212:215], v[232:235], v[80:95]
	v_mfma_f32_32x32x16_bf16 v[64:79], v[216:219], v[232:235], v[64:79]
	s_barrier
	v_readfirstlane_b32 s70, v161
	v_lshl_add_u64 v[238:239], v[188:189], 0, s[46:47]
	s_mov_b32 m0, s70
	v_readfirstlane_b32 s70, v162
	ds_read_b128 v[184:187], v154 offset:49152
	ds_read_b128 v[192:195], v154 offset:53248
	ds_read_b128 v[196:199], v153 offset:49152
	ds_read_b128 v[200:203], v153 offset:53248
	ds_read_b128 v[204:207], v152 offset:49152
	ds_read_b128 v[208:211], v152 offset:53248
	ds_read_b128 v[212:215], v131 offset:49152
	ds_read_b128 v[216:219], v131 offset:53248
	global_load_lds_dwordx4 v[238:239], off
	v_lshl_add_u64 v[188:189], v[188:189], 0, s[48:49]
	s_mov_b32 m0, s70
	s_nop 0
	global_load_lds_dwordx4 v[188:189], off
	s_barrier
	s_waitcnt lgkmcnt(0)
	s_waitcnt lgkmcnt(0)
	v_mfma_f32_32x32x16_bf16 v[48:63], v[184:187], v[168:171], v[48:63]
	v_mfma_f32_32x32x16_bf16 v[32:47], v[192:195], v[168:171], v[32:47]
	v_mfma_f32_32x32x16_bf16 v[48:63], v[196:199], v[172:175], v[48:63]
	v_mfma_f32_32x32x16_bf16 v[32:47], v[200:203], v[172:175], v[32:47]
	v_mfma_f32_32x32x16_bf16 v[48:63], v[204:207], v[176:179], v[48:63]
	v_mfma_f32_32x32x16_bf16 v[32:47], v[208:211], v[176:179], v[32:47]
	v_mfma_f32_32x32x16_bf16 v[48:63], v[212:215], v[180:183], v[48:63]
	v_mfma_f32_32x32x16_bf16 v[32:47], v[216:219], v[180:183], v[32:47]
	s_barrier
	v_readfirstlane_b32 s70, v163
	v_lshl_add_u64 v[168:169], v[236:237], 0, s[50:51]
	s_mov_b32 m0, s70
	v_readfirstlane_b32 s70, v164
	global_load_lds_dwordx4 v[168:169], off
	v_lshl_add_u64 v[168:169], v[236:237], 0, s[52:53]
	s_mov_b32 m0, s70
	s_nop 0
	global_load_lds_dwordx4 v[168:169], off
	s_waitcnt vmcnt(6)
	s_barrier
	v_mfma_f32_32x32x16_bf16 v[16:31], v[184:187], v[220:223], v[16:31]
	v_mfma_f32_32x32x16_bf16 v[0:15], v[192:195], v[220:223], v[0:15]
	v_mfma_f32_32x32x16_bf16 v[16:31], v[196:199], v[224:227], v[16:31]
	v_mfma_f32_32x32x16_bf16 v[0:15], v[200:203], v[224:227], v[0:15]
	v_mfma_f32_32x32x16_bf16 v[16:31], v[204:207], v[228:231], v[16:31]
	v_mfma_f32_32x32x16_bf16 v[0:15], v[208:211], v[228:231], v[0:15]
	v_mfma_f32_32x32x16_bf16 v[16:31], v[212:215], v[232:235], v[16:31]
	v_mfma_f32_32x32x16_bf16 v[0:15], v[216:219], v[232:235], v[0:15]
	s_barrier
	s_add_i32 s63, s63, 2
	v_lshl_add_u64 v[136:137], v[136:137], 0, s[54:55]
	s_cmp_lt_u32 s63, 12
	v_lshl_add_u64 v[138:139], v[138:139], 0, s[54:55]
	s_cbranch_scc1 .LBB0_2203
	v_readfirstlane_b32 s63, v166
	v_lshl_add_u64 v[188:189], v[134:135], 0, s[56:57]
	s_mov_b32 m0, s63
	v_readfirstlane_b32 s63, v165
	ds_read_b128 v[136:139], v155
	ds_read_b128 v[160:163], v156
	ds_read_b128 v[168:171], v157
	ds_read_b128 v[172:175], v158
	ds_read_b128 v[176:179], v154
	ds_read_b128 v[180:183], v154 offset:4096
	ds_read_b128 v[184:187], v153
	ds_read_b128 v[192:195], v153 offset:4096
	ds_read_b128 v[196:199], v152
	ds_read_b128 v[200:203], v152 offset:4096
	ds_read_b128 v[204:207], v131
	ds_read_b128 v[208:211], v131 offset:4096
	global_load_lds_dwordx4 v[188:189], off
	v_lshl_add_u64 v[134:135], v[134:135], 0, s[58:59]
	s_mov_b32 m0, s63
	s_nop 0
	global_load_lds_dwordx4 v[134:135], off
	s_barrier
	s_waitcnt lgkmcnt(0)
	s_waitcnt lgkmcnt(0)
	v_mfma_f32_32x32x16_bf16 v[112:127], v[176:179], v[136:139], v[112:127]
	v_mfma_f32_32x32x16_bf16 v[96:111], v[180:183], v[136:139], v[96:111]
	v_mfma_f32_32x32x16_bf16 v[112:127], v[184:187], v[160:163], v[112:127]
	v_mfma_f32_32x32x16_bf16 v[96:111], v[192:195], v[160:163], v[96:111]
	v_mfma_f32_32x32x16_bf16 v[112:127], v[196:199], v[168:171], v[112:127]
	v_mfma_f32_32x32x16_bf16 v[96:111], v[200:203], v[168:171], v[96:111]
	v_mfma_f32_32x32x16_bf16 v[112:127], v[204:207], v[172:175], v[112:127]
	v_mfma_f32_32x32x16_bf16 v[96:111], v[208:211], v[172:175], v[96:111]
	s_barrier
	ds_read_b128 v[164:167], v155 offset:16384
	ds_read_b128 v[212:215], v156 offset:16384
	ds_read_b128 v[216:219], v157 offset:16384
	ds_read_b128 v[220:223], v158 offset:16384
	s_barrier
; #define G8_LDA(b, h) do { _Pragma("unroll") for (int m_ = 0; m_ < 2; ++m_) _Pragma("unroll") for (int k_ = 0; k_ < 4; ++k_) \
;     At[m_][k_] = *reinterpret_cast<const LAS bf16x8*>(la + ((b) * 2 + (h)) * 16384 + m_ * 4096 + (((k_ * 2 + hi) ^ swz) << 4)); } while (0)
; #define G8_LDB(dst, b, h) do { _Pragma("unroll") for (int k_ = 0; k_ < 4; ++k_) \
;     dst[k_] = *reinterpret_cast<const LAS bf16x8*>(lb + ((b) * 2 + (h)) * 16384 + (((k_ * 2 + hi) ^ swz) << 4)); } while (0)
; #define G8_MMA(ai, bj, Bx) do { __builtin_amdgcn_s_setprio(1); _Pragma("unroll") for (int k_ = 0; k_ < 4; ++k_) _Pragma("unroll") for (int m_ = 0; m_ < 2; ++m_) \
;     acc[ai][bj][m_] = __builtin_amdgcn_mfma_f32_32x32x16_bf16(At[m_][k_], Bx[k_], acc[ai][bj][m_], 0, 0, 0); __builtin_amdgcn_s_setprio(0); } while (0)
; #define G8_WV(n) asm volatile("s_waitcnt vmcnt(" #n ")" ::: "memory")
; #define G8_WL(n) asm volatile("s_waitcnt lgkmcnt(" #n ")" ::: "memory")
; #define G8_BAR __builtin_amdgcn_s_barrier()
; #define G8_SCHED __builtin_amdgcn_sched_barrier(0)
; template <class Epi>
; __device__ __forceinline__ void gemm8p(const bf16_t* __restrict__ A, int lda, const bf16_t* __restrict__ Bt, int ldb, int K,
;                                        LP lds, const Epi& epi, bool pre = false, const bf16_t* An = nullptr, const bf16_t* Bn = nullptr) {
;     ...
;     G8_LDB(B1, 0, 1); G8_BAR; G8_WL(0); G8_MMA(0, 1, B1); G8_BAR; G8_SCHED;
;     G8_LDA(0, 1); G8_WV(4); G8_BAR; G8_WL(0); G8_MMA(1, 0, B0); G8_MMA(1, 1, B1); G8_BAR; G8_SCHED; }
;   { G8_LDB(B0, 1, 0); G8_LDA(1, 0); G8_WV(2); G8_BAR; G8_WL(0); G8_MMA(0, 0, B0); G8_BAR; G8_SCHED;
;     G8_LDB(B1, 1, 1); G8_WV(0); G8_BAR; G8_WL(0); G8_MMA(0, 1, B1); G8_BAR; G8_SCHED;
;     G8_LDA(1, 1); G8_BAR; G8_WL(0); G8_MMA(1, 0, B0); G8_MMA(1, 1, B1); G8_BAR; G8_SCHED; }
;   if (wr == 0) G8_BAR;
	s_waitcnt lgkmcnt(0)
	s_waitcnt lgkmcnt(0)
	v_mfma_f32_32x32x16_bf16 v[80:95], v[176:179], v[164:167], v[80:95]
	v_mfma_f32_32x32x16_bf16 v[64:79], v[180:183], v[164:167], v[64:79]
	v_mfma_f32_32x32x16_bf16 v[80:95], v[184:187], v[212:215], v[80:95]
	v_mfma_f32_32x32x16_bf16 v[64:79], v[192:195], v[212:215], v[64:79]
	v_mfma_f32_32x32x16_bf16 v[80:95], v[196:199], v[216:219], v[80:95]
	v_mfma_f32_32x32x16_bf16 v[64:79], v[200:203], v[216:219], v[64:79]
	v_mfma_f32_32x32x16_bf16 v[80:95], v[204:207], v[220:223], v[80:95]
	v_mfma_f32_32x32x16_bf16 v[64:79], v[208:211], v[220:223], v[64:79]
	s_barrier
	ds_read_b128 v[176:179], v154 offset:16384
	ds_read_b128 v[180:183], v154 offset:20480
	ds_read_b128 v[184:187], v153 offset:16384
	ds_read_b128 v[192:195], v153 offset:20480
	ds_read_b128 v[196:199], v152 offset:16384
	ds_read_b128 v[200:203], v152 offset:20480
	ds_read_b128 v[204:207], v131 offset:16384
	ds_read_b128 v[208:211], v131 offset:20480
	s_waitcnt vmcnt(4)
	s_barrier
	s_waitcnt lgkmcnt(0)
	s_waitcnt lgkmcnt(0)
	v_mfma_f32_32x32x16_bf16 v[48:63], v[176:179], v[136:139], v[48:63]
	v_mfma_f32_32x32x16_bf16 v[32:47], v[180:183], v[136:139], v[32:47]
	v_mfma_f32_32x32x16_bf16 v[48:63], v[184:187], v[160:163], v[48:63]
	v_mfma_f32_32x32x16_bf16 v[32:47], v[192:195], v[160:163], v[32:47]
	v_mfma_f32_32x32x16_bf16 v[48:63], v[196:199], v[168:171], v[48:63]
	v_mfma_f32_32x32x16_bf16 v[32:47], v[200:203], v[168:171], v[32:47]
	v_mfma_f32_32x32x16_bf16 v[48:63], v[204:207], v[172:175], v[48:63]
	v_mfma_f32_32x32x16_bf16 v[32:47], v[208:211], v[172:175], v[32:47]
	v_mfma_f32_32x32x16_bf16 v[16:31], v[176:179], v[164:167], v[16:31]
	v_mfma_f32_32x32x16_bf16 v[0:15], v[180:183], v[164:167], v[0:15]
	v_mfma_f32_32x32x16_bf16 v[16:31], v[184:187], v[212:215], v[16:31]
	v_mfma_f32_32x32x16_bf16 v[0:15], v[192:195], v[212:215], v[0:15]
	v_mfma_f32_32x32x16_bf16 v[16:31], v[196:199], v[216:219], v[16:31]
	v_mfma_f32_32x32x16_bf16 v[0:15], v[200:203], v[216:219], v[0:15]
	v_mfma_f32_32x32x16_bf16 v[16:31], v[204:207], v[220:223], v[16:31]
	v_mfma_f32_32x32x16_bf16 v[0:15], v[208:211], v[220:223], v[0:15]
	s_barrier
	ds_read_b128 v[134:137], v155 offset:32768
	ds_read_b128 v[160:163], v156 offset:32768
	ds_read_b128 v[164:167], v157 offset:32768
	ds_read_b128 v[168:171], v158 offset:32768
	ds_read_b128 v[172:175], v154 offset:32768
	ds_read_b128 v[176:179], v154 offset:36864
	ds_read_b128 v[180:183], v153 offset:32768
	ds_read_b128 v[184:187], v153 offset:36864
	ds_read_b128 v[192:195], v152 offset:32768
	ds_read_b128 v[196:199], v152 offset:36864
	ds_read_b128 v[200:203], v131 offset:32768
	ds_read_b128 v[204:207], v131 offset:36864
	s_waitcnt vmcnt(2)
	s_barrier
	s_waitcnt lgkmcnt(0)
	s_waitcnt lgkmcnt(0)
	v_mfma_f32_32x32x16_bf16 v[112:127], v[172:175], v[134:137], v[112:127]
	v_mfma_f32_32x32x16_bf16 v[96:111], v[176:179], v[134:137], v[96:111]
	v_mfma_f32_32x32x16_bf16 v[112:127], v[180:183], v[160:163], v[112:127]
	v_mfma_f32_32x32x16_bf16 v[96:111], v[184:187], v[160:163], v[96:111]
	v_mfma_f32_32x32x16_bf16 v[112:127], v[192:195], v[164:167], v[112:127]
	v_mfma_f32_32x32x16_bf16 v[96:111], v[196:199], v[164:167], v[96:111]
	v_mfma_f32_32x32x16_bf16 v[112:127], v[200:203], v[168:171], v[112:127]
	v_mfma_f32_32x32x16_bf16 v[96:111], v[204:207], v[168:171], v[96:111]
	s_barrier
	ds_read_b128 v[208:211], v155 offset:49152
	ds_read_b128 v[212:215], v156 offset:49152
	ds_read_b128 v[216:219], v157 offset:49152
	ds_read_b128 v[156:159], v158 offset:49152
	s_waitcnt vmcnt(0)
	s_barrier
	s_waitcnt lgkmcnt(0)
	s_waitcnt lgkmcnt(0)
	v_mfma_f32_32x32x16_bf16 v[80:95], v[172:175], v[208:211], v[80:95]
	v_mfma_f32_32x32x16_bf16 v[64:79], v[176:179], v[208:211], v[64:79]
	v_mfma_f32_32x32x16_bf16 v[80:95], v[180:183], v[212:215], v[80:95]
	v_mfma_f32_32x32x16_bf16 v[64:79], v[184:187], v[212:215], v[64:79]
	v_mfma_f32_32x32x16_bf16 v[80:95], v[192:195], v[216:219], v[80:95]
	v_mfma_f32_32x32x16_bf16 v[64:79], v[196:199], v[216:219], v[64:79]
	v_mfma_f32_32x32x16_bf16 v[80:95], v[200:203], v[156:159], v[80:95]
	v_mfma_f32_32x32x16_bf16 v[64:79], v[204:207], v[156:159], v[64:79]
	s_barrier
	ds_read_b128 v[172:175], v154 offset:49152
	ds_read_b128 v[176:179], v154 offset:53248
	ds_read_b128 v[180:183], v153 offset:49152
	ds_read_b128 v[184:187], v153 offset:53248
	ds_read_b128 v[192:195], v152 offset:49152
	ds_read_b128 v[152:155], v152 offset:53248
	ds_read_b128 v[196:199], v131 offset:49152
	ds_read_b128 v[200:203], v131 offset:53248
	s_barrier
	s_waitcnt lgkmcnt(0)
	s_waitcnt lgkmcnt(0)
	v_mfma_f32_32x32x16_bf16 v[48:63], v[172:175], v[134:137], v[48:63]
	v_mfma_f32_32x32x16_bf16 v[32:47], v[176:179], v[134:137], v[32:47]
	v_mfma_f32_32x32x16_bf16 v[48:63], v[180:183], v[160:163], v[48:63]
	v_mfma_f32_32x32x16_bf16 v[32:47], v[184:187], v[160:163], v[32:47]
	v_mfma_f32_32x32x16_bf16 v[48:63], v[192:195], v[164:167], v[48:63]
	v_mfma_f32_32x32x16_bf16 v[32:47], v[152:155], v[164:167], v[32:47]
	v_mfma_f32_32x32x16_bf16 v[48:63], v[196:199], v[168:171], v[48:63]
	v_mfma_f32_32x32x16_bf16 v[32:47], v[200:203], v[168:171], v[32:47]
	v_mfma_f32_32x32x16_bf16 v[16:31], v[172:175], v[208:211], v[16:31]
	v_mfma_f32_32x32x16_bf16 v[0:15], v[176:179], v[208:211], v[0:15]
	v_mfma_f32_32x32x16_bf16 v[16:31], v[180:183], v[212:215], v[16:31]
	v_mfma_f32_32x32x16_bf16 v[0:15], v[184:187], v[212:215], v[0:15]
	v_mfma_f32_32x32x16_bf16 v[16:31], v[192:195], v[216:219], v[16:31]
	v_mfma_f32_32x32x16_bf16 v[0:15], v[152:155], v[216:219], v[0:15]
	v_mfma_f32_32x32x16_bf16 v[16:31], v[196:199], v[156:159], v[16:31]
	v_mfma_f32_32x32x16_bf16 v[0:15], v[200:203], v[156:159], v[0:15]
	s_barrier
	s_movk_i32 s63, 0x100
	v_cmp_gt_u32_e32 vcc, s63, v148
	s_and_saveexec_b64 s[70:71], vcc
	s_cbranch_execz .LBB0_2206
	s_barrier

; #define G8_STA(b, h, kt) G8_STAGE(G8_SA(b, h), Ag, lda, h, kt)
; #define G8_STB(b, h, kt) G8_STAGE(G8_SB(b, h), Bg, ldb, h, kt)
; #define G8_LDA(b, h) do { _Pragma("unroll") for (int m_ = 0; m_ < 2; ++m_) _Pragma("unroll") for (int k_ = 0; k_ < 4; ++k_) \
;     At[m_][k_] = *reinterpret_cast<const LAS bf16x8*>(la + ((b) * 2 + (h)) * 16384 + m_ * 4096 + (((k_ * 2 + hi) ^ swz) << 4)); } while (0)
; #define G8_LDB(dst, b, h) do { _Pragma("unroll") for (int k_ = 0; k_ < 4; ++k_) \
;     dst[k_] = *reinterpret_cast<const LAS bf16x8*>(lb + ((b) * 2 + (h)) * 16384 + (((k_ * 2 + hi) ^ swz) << 4)); } while (0)
; #define G8_MMA(ai, bj, Bx) do { __builtin_amdgcn_s_setprio(1); _Pragma("unroll") for (int k_ = 0; k_ < 4; ++k_) _Pragma("unroll") for (int m_ = 0; m_ < 2; ++m_) \
;     acc[ai][bj][m_] = __builtin_amdgcn_mfma_f32_32x32x16_bf16(At[m_][k_], Bx[k_], acc[ai][bj][m_], 0, 0, 0); __builtin_amdgcn_s_setprio(0); } while (0)
; #define G8_WV(n) asm volatile("s_waitcnt vmcnt(" #n ")" ::: "memory")
; #define G8_WL(n) asm volatile("s_waitcnt lgkmcnt(" #n ")" ::: "memory")
; #define G8_BAR __builtin_amdgcn_s_barrier()
; #define G8_SCHED __builtin_amdgcn_sched_barrier(0)
; template <class Epi>
; __device__ __forceinline__ void gemm8p(const bf16_t* __restrict__ A, int lda, const bf16_t* __restrict__ Bt, int ldb, int K,
;                                        LP lds, const Epi& epi, bool pre = false, const bf16_t* An = nullptr, const bf16_t* Bn = nullptr) {
;     ...
;   for (int t = 0; t < nt - 2; t += 2) {
;     G8_LDB(B0, 0, 0); G8_SCHED; G8_LDA(0, 0); G8_STA(1, 1, t + 1);
;     G8_WL(8); G8_BAR; G8_WL(0); G8_MMA(0, 0, B0); G8_BAR; G8_SCHED;
;     G8_LDB(B1, 0, 1); G8_STB(0, 0, t + 2);
;     G8_BAR; G8_WL(0); G8_MMA(0, 1, B1); G8_BAR; G8_SCHED;
;     G8_LDA(0, 1); G8_STA(0, 0, t + 2);
;     G8_BAR; G8_WL(0); G8_MMA(1, 0, B0); G8_BAR; G8_SCHED;
;     G8_STB(0, 1, t + 2);
;     G8_WV(6); G8_BAR; G8_MMA(1, 1, B1); G8_BAR; G8_SCHED;
.LBB0_2334:
	ds_read_b128 v[168:171], v155
	ds_read_b128 v[172:175], v156
	ds_read_b128 v[176:179], v157
	ds_read_b128 v[180:183], v158
	v_lshl_add_u64 v[188:189], v[136:137], 0, v[128:129]
	v_readfirstlane_b32 s72, v166
	v_lshl_add_u64 v[220:221], v[188:189], 0, s[22:23]
	s_mov_b32 m0, s72
	v_readfirstlane_b32 s72, v165
	ds_read_b128 v[184:187], v154
	ds_read_b128 v[192:195], v154 offset:4096
	ds_read_b128 v[196:199], v153
	ds_read_b128 v[200:203], v153 offset:4096
	ds_read_b128 v[204:207], v152
	ds_read_b128 v[208:211], v152 offset:4096
	ds_read_b128 v[212:215], v131
	ds_read_b128 v[216:219], v131 offset:4096
	global_load_lds_dwordx4 v[220:221], off
	v_lshl_add_u64 v[220:221], v[188:189], 0, s[24:25]
	s_mov_b32 m0, s72
	s_nop 0
	global_load_lds_dwordx4 v[220:221], off
	s_waitcnt lgkmcnt(8)
	s_barrier
	s_waitcnt lgkmcnt(0)
	s_waitcnt lgkmcnt(0)
	v_mfma_f32_32x32x16_bf16 v[112:127], v[184:187], v[168:171], v[112:127]
	v_mfma_f32_32x32x16_bf16 v[96:111], v[192:195], v[168:171], v[96:111]
	v_mfma_f32_32x32x16_bf16 v[112:127], v[196:199], v[172:175], v[112:127]
	v_mfma_f32_32x32x16_bf16 v[96:111], v[200:203], v[172:175], v[96:111]
	v_mfma_f32_32x32x16_bf16 v[112:127], v[204:207], v[176:179], v[112:127]
	v_mfma_f32_32x32x16_bf16 v[96:111], v[208:211], v[176:179], v[96:111]
	v_mfma_f32_32x32x16_bf16 v[112:127], v[212:215], v[180:183], v[112:127]
	v_mfma_f32_32x32x16_bf16 v[96:111], v[216:219], v[180:183], v[96:111]
	s_barrier
	v_lshl_add_u64 v[236:237], v[138:139], 0, v[128:129]
	v_readfirstlane_b32 s72, v147
	v_lshl_add_u64 v[238:239], v[236:237], 0, s[26:27]
	s_mov_b32 m0, s72
	v_readfirstlane_b32 s72, v146
	ds_read_b128 v[220:223], v155 offset:16384
	ds_read_b128 v[224:227], v156 offset:16384
	ds_read_b128 v[228:231], v157 offset:16384
	ds_read_b128 v[232:235], v158 offset:16384
	global_load_lds_dwordx4 v[238:239], off
	v_lshl_add_u64 v[238:239], v[236:237], 0, s[28:29]
	s_mov_b32 m0, s72
	s_nop 0
	global_load_lds_dwordx4 v[238:239], off
	s_barrier
	s_waitcnt lgkmcnt(0)
	s_waitcnt lgkmcnt(0)
	v_mfma_f32_32x32x16_bf16 v[80:95], v[184:187], v[220:223], v[80:95]
	v_mfma_f32_32x32x16_bf16 v[64:79], v[192:195], v[220:223], v[64:79]
	v_mfma_f32_32x32x16_bf16 v[80:95], v[196:199], v[224:227], v[80:95]
	v_mfma_f32_32x32x16_bf16 v[64:79], v[200:203], v[224:227], v[64:79]
	v_mfma_f32_32x32x16_bf16 v[80:95], v[204:207], v[228:231], v[80:95]
	v_mfma_f32_32x32x16_bf16 v[64:79], v[208:211], v[228:231], v[64:79]
	v_mfma_f32_32x32x16_bf16 v[80:95], v[212:215], v[232:235], v[80:95]
	v_mfma_f32_32x32x16_bf16 v[64:79], v[216:219], v[232:235], v[64:79]
	s_barrier
	v_readfirstlane_b32 s72, v142
	v_lshl_add_u64 v[238:239], v[188:189], 0, s[30:31]
	s_mov_b32 m0, s72
	v_readfirstlane_b32 s72, v145
	ds_read_b128 v[184:187], v154 offset:16384
	ds_read_b128 v[192:195], v154 offset:20480
	ds_read_b128 v[196:199], v153 offset:16384
	ds_read_b128 v[200:203], v153 offset:20480
	ds_read_b128 v[204:207], v152 offset:16384
	ds_read_b128 v[208:211], v152 offset:20480
	ds_read_b128 v[212:215], v131 offset:16384
	ds_read_b128 v[216:219], v131 offset:20480
	global_load_lds_dwordx4 v[238:239], off
	v_lshl_add_u64 v[238:239], v[188:189], 0, s[36:37]
	s_mov_b32 m0, s72
	s_nop 0
	global_load_lds_dwordx4 v[238:239], off
	s_barrier
	s_waitcnt lgkmcnt(0)
	s_waitcnt lgkmcnt(0)
	v_mfma_f32_32x32x16_bf16 v[48:63], v[184:187], v[168:171], v[48:63]
	v_mfma_f32_32x32x16_bf16 v[32:47], v[192:195], v[168:171], v[32:47]
	v_mfma_f32_32x32x16_bf16 v[48:63], v[196:199], v[172:175], v[48:63]
	v_mfma_f32_32x32x16_bf16 v[32:47], v[200:203], v[172:175], v[32:47]
	v_mfma_f32_32x32x16_bf16 v[48:63], v[204:207], v[176:179], v[48:63]
	v_mfma_f32_32x32x16_bf16 v[32:47], v[208:211], v[176:179], v[32:47]
	v_mfma_f32_32x32x16_bf16 v[48:63], v[212:215], v[180:183], v[48:63]
	v_mfma_f32_32x32x16_bf16 v[32:47], v[216:219], v[180:183], v[32:47]
	s_barrier
	v_readfirstlane_b32 s72, v144
	v_lshl_add_u64 v[168:169], v[236:237], 0, s[38:39]
	s_mov_b32 m0, s72
	v_readfirstlane_b32 s72, v143
	global_load_lds_dwordx4 v[168:169], off
	v_lshl_add_u64 v[168:169], v[236:237], 0, s[40:41]
	s_mov_b32 m0, s72
	s_nop 0
	global_load_lds_dwordx4 v[168:169], off
	s_waitcnt vmcnt(6)
	s_barrier
	v_mfma_f32_32x32x16_bf16 v[16:31], v[184:187], v[220:223], v[16:31]
	v_mfma_f32_32x32x16_bf16 v[0:15], v[192:195], v[220:223], v[0:15]
	v_mfma_f32_32x32x16_bf16 v[16:31], v[196:199], v[224:227], v[16:31]
	v_mfma_f32_32x32x16_bf16 v[0:15], v[200:203], v[224:227], v[0:15]
	v_mfma_f32_32x32x16_bf16 v[16:31], v[204:207], v[228:231], v[16:31]
	v_mfma_f32_32x32x16_bf16 v[0:15], v[208:211], v[228:231], v[0:15]
	v_mfma_f32_32x32x16_bf16 v[16:31], v[212:215], v[232:235], v[16:31]
	v_mfma_f32_32x32x16_bf16 v[0:15], v[216:219], v[232:235], v[0:15]
	s_barrier
	ds_read_b128 v[168:171], v155 offset:32768
	ds_read_b128 v[172:175], v156 offset:32768
	ds_read_b128 v[176:179], v157 offset:32768
	ds_read_b128 v[180:183], v158 offset:32768
	v_readfirstlane_b32 s72, v141
	v_lshl_add_u64 v[220:221], v[188:189], 0, s[42:43]
	s_mov_b32 m0, s72
	v_readfirstlane_b32 s72, v140
	ds_read_b128 v[184:187], v154 offset:32768
	ds_read_b128 v[192:195], v154 offset:36864
	ds_read_b128 v[196:199], v153 offset:32768
	ds_read_b128 v[200:203], v153 offset:36864
	ds_read_b128 v[204:207], v152 offset:32768
	ds_read_b128 v[208:211], v152 offset:36864
	ds_read_b128 v[212:215], v131 offset:32768
	ds_read_b128 v[216:219], v131 offset:36864
	global_load_lds_dwordx4 v[220:221], off
	v_lshl_add_u64 v[220:221], v[188:189], 0, s[44:45]
	s_mov_b32 m0, s72
	s_nop 0
	global_load_lds_dwordx4 v[220:221], off
	s_waitcnt lgkmcnt(8)
	s_barrier
; #define G8_STA(b, h, kt) G8_STAGE(G8_SA(b, h), Ag, lda, h, kt)
; #define G8_STB(b, h, kt) G8_STAGE(G8_SB(b, h), Bg, ldb, h, kt)
; #define G8_LDA(b, h) do { _Pragma("unroll") for (int m_ = 0; m_ < 2; ++m_) _Pragma("unroll") for (int k_ = 0; k_ < 4; ++k_) \
;     At[m_][k_] = *reinterpret_cast<const LAS bf16x8*>(la + ((b) * 2 + (h)) * 16384 + m_ * 4096 + (((k_ * 2 + hi) ^ swz) << 4)); } while (0)
; #define G8_LDB(dst, b, h) do { _Pragma("unroll") for (int k_ = 0; k_ < 4; ++k_) \
;     dst[k_] = *reinterpret_cast<const LAS bf16x8*>(lb + ((b) * 2 + (h)) * 16384 + (((k_ * 2 + hi) ^ swz) << 4)); } while (0)
; #define G8_MMA(ai, bj, Bx) do { __builtin_amdgcn_s_setprio(1); _Pragma("unroll") for (int k_ = 0; k_ < 4; ++k_) _Pragma("unroll") for (int m_ = 0; m_ < 2; ++m_) \
;     acc[ai][bj][m_] = __builtin_amdgcn_mfma_f32_32x32x16_bf16(At[m_][k_], Bx[k_], acc[ai][bj][m_], 0, 0, 0); __builtin_amdgcn_s_setprio(0); } while (0)
; #define G8_WV(n) asm volatile("s_waitcnt vmcnt(" #n ")" ::: "memory")
; #define G8_WL(n) asm volatile("s_waitcnt lgkmcnt(" #n ")" ::: "memory")
; #define G8_BAR __builtin_amdgcn_s_barrier()
; #define G8_SCHED __builtin_amdgcn_sched_barrier(0)
; template <class Epi>
; __device__ __forceinline__ void gemm8p(const bf16_t* __restrict__ A, int lda, const bf16_t* __restrict__ Bt, int ldb, int K,
;                                        LP lds, const Epi& epi, bool pre = false, const bf16_t* An = nullptr, const bf16_t* Bn = nullptr) {
;     ...
;     G8_LDB(B0, 1, 0); G8_SCHED; G8_LDA(1, 0); G8_STA(0, 1, t + 2);
;     G8_WL(8); G8_BAR; G8_WL(0); G8_MMA(0, 0, B0); G8_BAR; G8_SCHED;
;     G8_LDB(B1, 1, 1); G8_STB(1, 0, t + 3);
;     G8_BAR; G8_WL(0); G8_MMA(0, 1, B1); G8_BAR; G8_SCHED;
;     G8_LDA(1, 1); G8_STA(1, 0, t + 3);
;     G8_BAR; G8_WL(0); G8_MMA(1, 0, B0); G8_BAR; G8_SCHED;
;     G8_STB(1, 1, t + 3);
;     G8_WV(6); G8_BAR; G8_MMA(1, 1, B1); G8_BAR; G8_SCHED;
;   }
;   { G8_LDB(B0, 0, 0); G8_LDA(0, 0); G8_STA(1, 1, nt - 1);
;     G8_BAR; G8_WL(0); G8_MMA(0, 0, B0); G8_BAR; G8_SCHED;
	s_waitcnt lgkmcnt(0)
	s_waitcnt lgkmcnt(0)
	v_mfma_f32_32x32x16_bf16 v[112:127], v[184:187], v[168:171], v[112:127]
	v_mfma_f32_32x32x16_bf16 v[96:111], v[192:195], v[168:171], v[96:111]
	v_mfma_f32_32x32x16_bf16 v[112:127], v[196:199], v[172:175], v[112:127]
	v_mfma_f32_32x32x16_bf16 v[96:111], v[200:203], v[172:175], v[96:111]
	v_mfma_f32_32x32x16_bf16 v[112:127], v[204:207], v[176:179], v[112:127]
	v_mfma_f32_32x32x16_bf16 v[96:111], v[208:211], v[176:179], v[96:111]
	v_mfma_f32_32x32x16_bf16 v[112:127], v[212:215], v[180:183], v[112:127]
	v_mfma_f32_32x32x16_bf16 v[96:111], v[216:219], v[180:183], v[96:111]
	s_barrier
	v_readfirstlane_b32 s72, v159
	v_lshl_add_u64 v[238:239], v[236:237], 0, s[46:47]
	s_mov_b32 m0, s72
	v_readfirstlane_b32 s72, v160
	ds_read_b128 v[220:223], v155 offset:49152
	ds_read_b128 v[224:227], v156 offset:49152
	ds_read_b128 v[228:231], v157 offset:49152
	ds_read_b128 v[232:235], v158 offset:49152
	global_load_lds_dwordx4 v[238:239], off
	v_lshl_add_u64 v[238:239], v[236:237], 0, s[48:49]
	s_mov_b32 m0, s72
	s_nop 0
	global_load_lds_dwordx4 v[238:239], off
	s_barrier
	s_waitcnt lgkmcnt(0)
	s_waitcnt lgkmcnt(0)
	v_mfma_f32_32x32x16_bf16 v[80:95], v[184:187], v[220:223], v[80:95]
	v_mfma_f32_32x32x16_bf16 v[64:79], v[192:195], v[220:223], v[64:79]
	v_mfma_f32_32x32x16_bf16 v[80:95], v[196:199], v[224:227], v[80:95]
	v_mfma_f32_32x32x16_bf16 v[64:79], v[200:203], v[224:227], v[64:79]
	v_mfma_f32_32x32x16_bf16 v[80:95], v[204:207], v[228:231], v[80:95]
	v_mfma_f32_32x32x16_bf16 v[64:79], v[208:211], v[228:231], v[64:79]
	v_mfma_f32_32x32x16_bf16 v[80:95], v[212:215], v[232:235], v[80:95]
	v_mfma_f32_32x32x16_bf16 v[64:79], v[216:219], v[232:235], v[64:79]
	s_barrier
	v_readfirstlane_b32 s72, v161
	v_lshl_add_u64 v[238:239], v[188:189], 0, s[50:51]
	s_mov_b32 m0, s72
	v_readfirstlane_b32 s72, v162
	ds_read_b128 v[184:187], v154 offset:49152
	ds_read_b128 v[192:195], v154 offset:53248
	ds_read_b128 v[196:199], v153 offset:49152
	ds_read_b128 v[200:203], v153 offset:53248
	ds_read_b128 v[204:207], v152 offset:49152
	ds_read_b128 v[208:211], v152 offset:53248
	ds_read_b128 v[212:215], v131 offset:49152
	ds_read_b128 v[216:219], v131 offset:53248
	global_load_lds_dwordx4 v[238:239], off
	v_lshl_add_u64 v[188:189], v[188:189], 0, s[52:53]
	s_mov_b32 m0, s72
	s_nop 0
	global_load_lds_dwordx4 v[188:189], off
	s_barrier
	s_waitcnt lgkmcnt(0)
	s_waitcnt lgkmcnt(0)
	v_mfma_f32_32x32x16_bf16 v[48:63], v[184:187], v[168:171], v[48:63]
	v_mfma_f32_32x32x16_bf16 v[32:47], v[192:195], v[168:171], v[32:47]
	v_mfma_f32_32x32x16_bf16 v[48:63], v[196:199], v[172:175], v[48:63]
	v_mfma_f32_32x32x16_bf16 v[32:47], v[200:203], v[172:175], v[32:47]
	v_mfma_f32_32x32x16_bf16 v[48:63], v[204:207], v[176:179], v[48:63]
	v_mfma_f32_32x32x16_bf16 v[32:47], v[208:211], v[176:179], v[32:47]
	v_mfma_f32_32x32x16_bf16 v[48:63], v[212:215], v[180:183], v[48:63]
	v_mfma_f32_32x32x16_bf16 v[32:47], v[216:219], v[180:183], v[32:47]
	s_barrier
	v_readfirstlane_b32 s72, v163
	v_lshl_add_u64 v[168:169], v[236:237], 0, s[54:55]
	s_mov_b32 m0, s72
	v_readfirstlane_b32 s72, v164
	global_load_lds_dwordx4 v[168:169], off
	v_lshl_add_u64 v[168:169], v[236:237], 0, s[56:57]
	s_mov_b32 m0, s72
	s_nop 0
	global_load_lds_dwordx4 v[168:169], off
	s_waitcnt vmcnt(6)
	s_barrier
	v_mfma_f32_32x32x16_bf16 v[16:31], v[184:187], v[220:223], v[16:31]
	v_mfma_f32_32x32x16_bf16 v[0:15], v[192:195], v[220:223], v[0:15]
	v_mfma_f32_32x32x16_bf16 v[16:31], v[196:199], v[224:227], v[16:31]
	v_mfma_f32_32x32x16_bf16 v[0:15], v[200:203], v[224:227], v[0:15]
	v_mfma_f32_32x32x16_bf16 v[16:31], v[204:207], v[228:231], v[16:31]
	v_mfma_f32_32x32x16_bf16 v[0:15], v[208:211], v[228:231], v[0:15]
	v_mfma_f32_32x32x16_bf16 v[16:31], v[212:215], v[232:235], v[16:31]
	v_mfma_f32_32x32x16_bf16 v[0:15], v[216:219], v[232:235], v[0:15]
	s_barrier
	s_add_i32 s67, s67, 2
	v_lshl_add_u64 v[136:137], v[136:137], 0, s[58:59]
	s_cmp_lt_u32 s67, 12
	v_lshl_add_u64 v[138:139], v[138:139], 0, s[58:59]
	s_cbranch_scc1 .LBB0_2334
	v_readfirstlane_b32 s67, v166
	v_lshl_add_u64 v[188:189], v[134:135], 0, s[60:61]
	s_mov_b32 m0, s67
	v_readfirstlane_b32 s67, v165
	ds_read_b128 v[136:139], v155
	ds_read_b128 v[160:163], v156
	ds_read_b128 v[168:171], v157
	ds_read_b128 v[172:175], v158
	ds_read_b128 v[176:179], v154
	ds_read_b128 v[180:183], v154 offset:4096
	ds_read_b128 v[184:187], v153
	ds_read_b128 v[192:195], v153 offset:4096
	ds_read_b128 v[196:199], v152
	ds_read_b128 v[200:203], v152 offset:4096
	ds_read_b128 v[204:207], v131
	ds_read_b128 v[208:211], v131 offset:4096
	global_load_lds_dwordx4 v[188:189], off
	v_lshl_add_u64 v[134:135], v[134:135], 0, s[62:63]
	s_mov_b32 m0, s67
	s_nop 0
	global_load_lds_dwordx4 v[134:135], off
	s_barrier
	s_waitcnt lgkmcnt(0)
	s_waitcnt lgkmcnt(0)
	v_mfma_f32_32x32x16_bf16 v[112:127], v[176:179], v[136:139], v[112:127]
	v_mfma_f32_32x32x16_bf16 v[96:111], v[180:183], v[136:139], v[96:111]
	v_mfma_f32_32x32x16_bf16 v[112:127], v[184:187], v[160:163], v[112:127]
	v_mfma_f32_32x32x16_bf16 v[96:111], v[192:195], v[160:163], v[96:111]
	v_mfma_f32_32x32x16_bf16 v[112:127], v[196:199], v[168:171], v[112:127]
	v_mfma_f32_32x32x16_bf16 v[96:111], v[200:203], v[168:171], v[96:111]
	v_mfma_f32_32x32x16_bf16 v[112:127], v[204:207], v[172:175], v[112:127]
	v_mfma_f32_32x32x16_bf16 v[96:111], v[208:211], v[172:175], v[96:111]
	s_barrier
	ds_read_b128 v[164:167], v155 offset:16384
	ds_read_b128 v[212:215], v156 offset:16384
	ds_read_b128 v[216:219], v157 offset:16384
	ds_read_b128 v[220:223], v158 offset:16384
	s_barrier
; #define G8_LDA(b, h) do { _Pragma("unroll") for (int m_ = 0; m_ < 2; ++m_) _Pragma("unroll") for (int k_ = 0; k_ < 4; ++k_) \
;     At[m_][k_] = *reinterpret_cast<const LAS bf16x8*>(la + ((b) * 2 + (h)) * 16384 + m_ * 4096 + (((k_ * 2 + hi) ^ swz) << 4)); } while (0)
; #define G8_LDB(dst, b, h) do { _Pragma("unroll") for (int k_ = 0; k_ < 4; ++k_) \
;     dst[k_] = *reinterpret_cast<const LAS bf16x8*>(lb + ((b) * 2 + (h)) * 16384 + (((k_ * 2 + hi) ^ swz) << 4)); } while (0)
; #define G8_MMA(ai, bj, Bx) do { __builtin_amdgcn_s_setprio(1); _Pragma("unroll") for (int k_ = 0; k_ < 4; ++k_) _Pragma("unroll") for (int m_ = 0; m_ < 2; ++m_) \
;     acc[ai][bj][m_] = __builtin_amdgcn_mfma_f32_32x32x16_bf16(At[m_][k_], Bx[k_], acc[ai][bj][m_], 0, 0, 0); __builtin_amdgcn_s_setprio(0); } while (0)
; #define G8_WV(n) asm volatile("s_waitcnt vmcnt(" #n ")" ::: "memory")
; #define G8_WL(n) asm volatile("s_waitcnt lgkmcnt(" #n ")" ::: "memory")
; #define G8_BAR __builtin_amdgcn_s_barrier()
; #define G8_SCHED __builtin_amdgcn_sched_barrier(0)
; template <class Epi>
; __device__ __forceinline__ void gemm8p(const bf16_t* __restrict__ A, int lda, const bf16_t* __restrict__ Bt, int ldb, int K,
;                                        LP lds, const Epi& epi, bool pre = false, const bf16_t* An = nullptr, const bf16_t* Bn = nullptr) {
;     ...
;     G8_BAR; G8_WL(0); G8_MMA(0, 0, B0); G8_BAR; G8_SCHED;
;     G8_LDB(B1, 0, 1); G8_BAR; G8_WL(0); G8_MMA(0, 1, B1); G8_BAR; G8_SCHED;
;     G8_LDA(0, 1); G8_WV(4); G8_BAR; G8_WL(0); G8_MMA(1, 0, B0); G8_MMA(1, 1, B1); G8_BAR; G8_SCHED; }
;   { G8_LDB(B0, 1, 0); G8_LDA(1, 0); G8_WV(2); G8_BAR; G8_WL(0); G8_MMA(0, 0, B0); G8_BAR; G8_SCHED;
;     G8_LDB(B1, 1, 1); G8_WV(0); G8_BAR; G8_WL(0); G8_MMA(0, 1, B1); G8_BAR; G8_SCHED;
;     G8_LDA(1, 1); G8_BAR; G8_WL(0); G8_MMA(1, 0, B0); G8_MMA(1, 1, B1); G8_BAR; G8_SCHED; }
;   if (wr == 0) G8_BAR;
;   G8_SCHED;
;   if (An != nullptr) {
	s_waitcnt lgkmcnt(0)
	s_waitcnt lgkmcnt(0)
	v_mfma_f32_32x32x16_bf16 v[80:95], v[176:179], v[164:167], v[80:95]
	v_mfma_f32_32x32x16_bf16 v[64:79], v[180:183], v[164:167], v[64:79]
	v_mfma_f32_32x32x16_bf16 v[80:95], v[184:187], v[212:215], v[80:95]
	v_mfma_f32_32x32x16_bf16 v[64:79], v[192:195], v[212:215], v[64:79]
	v_mfma_f32_32x32x16_bf16 v[80:95], v[196:199], v[216:219], v[80:95]
	v_mfma_f32_32x32x16_bf16 v[64:79], v[200:203], v[216:219], v[64:79]
	v_mfma_f32_32x32x16_bf16 v[80:95], v[204:207], v[220:223], v[80:95]
	v_mfma_f32_32x32x16_bf16 v[64:79], v[208:211], v[220:223], v[64:79]
	s_barrier
	ds_read_b128 v[176:179], v154 offset:16384
	ds_read_b128 v[180:183], v154 offset:20480
	ds_read_b128 v[184:187], v153 offset:16384
	ds_read_b128 v[192:195], v153 offset:20480
	ds_read_b128 v[196:199], v152 offset:16384
	ds_read_b128 v[200:203], v152 offset:20480
	ds_read_b128 v[204:207], v131 offset:16384
	ds_read_b128 v[208:211], v131 offset:20480
	s_waitcnt vmcnt(4)
	s_barrier
	s_waitcnt lgkmcnt(0)
	s_waitcnt lgkmcnt(0)
	v_mfma_f32_32x32x16_bf16 v[48:63], v[176:179], v[136:139], v[48:63]
	v_mfma_f32_32x32x16_bf16 v[32:47], v[180:183], v[136:139], v[32:47]
	v_mfma_f32_32x32x16_bf16 v[48:63], v[184:187], v[160:163], v[48:63]
	v_mfma_f32_32x32x16_bf16 v[32:47], v[192:195], v[160:163], v[32:47]
	v_mfma_f32_32x32x16_bf16 v[48:63], v[196:199], v[168:171], v[48:63]
	v_mfma_f32_32x32x16_bf16 v[32:47], v[200:203], v[168:171], v[32:47]
	v_mfma_f32_32x32x16_bf16 v[48:63], v[204:207], v[172:175], v[48:63]
	v_mfma_f32_32x32x16_bf16 v[32:47], v[208:211], v[172:175], v[32:47]
	v_mfma_f32_32x32x16_bf16 v[16:31], v[176:179], v[164:167], v[16:31]
	v_mfma_f32_32x32x16_bf16 v[0:15], v[180:183], v[164:167], v[0:15]
	v_mfma_f32_32x32x16_bf16 v[16:31], v[184:187], v[212:215], v[16:31]
	v_mfma_f32_32x32x16_bf16 v[0:15], v[192:195], v[212:215], v[0:15]
	v_mfma_f32_32x32x16_bf16 v[16:31], v[196:199], v[216:219], v[16:31]
	v_mfma_f32_32x32x16_bf16 v[0:15], v[200:203], v[216:219], v[0:15]
	v_mfma_f32_32x32x16_bf16 v[16:31], v[204:207], v[220:223], v[16:31]
	v_mfma_f32_32x32x16_bf16 v[0:15], v[208:211], v[220:223], v[0:15]
	s_barrier
	ds_read_b128 v[134:137], v155 offset:32768
	ds_read_b128 v[160:163], v156 offset:32768
	ds_read_b128 v[164:167], v157 offset:32768
	ds_read_b128 v[168:171], v158 offset:32768
	ds_read_b128 v[172:175], v154 offset:32768
	ds_read_b128 v[176:179], v154 offset:36864
	ds_read_b128 v[180:183], v153 offset:32768
	ds_read_b128 v[184:187], v153 offset:36864
	ds_read_b128 v[192:195], v152 offset:32768
	ds_read_b128 v[196:199], v152 offset:36864
	ds_read_b128 v[200:203], v131 offset:32768
	ds_read_b128 v[204:207], v131 offset:36864
	s_waitcnt vmcnt(2)
	s_barrier
	s_waitcnt lgkmcnt(0)
	s_waitcnt lgkmcnt(0)
	v_mfma_f32_32x32x16_bf16 v[112:127], v[172:175], v[134:137], v[112:127]
	v_mfma_f32_32x32x16_bf16 v[96:111], v[176:179], v[134:137], v[96:111]
	v_mfma_f32_32x32x16_bf16 v[112:127], v[180:183], v[160:163], v[112:127]
	v_mfma_f32_32x32x16_bf16 v[96:111], v[184:187], v[160:163], v[96:111]
	v_mfma_f32_32x32x16_bf16 v[112:127], v[192:195], v[164:167], v[112:127]
	v_mfma_f32_32x32x16_bf16 v[96:111], v[196:199], v[164:167], v[96:111]
	v_mfma_f32_32x32x16_bf16 v[112:127], v[200:203], v[168:171], v[112:127]
	v_mfma_f32_32x32x16_bf16 v[96:111], v[204:207], v[168:171], v[96:111]
	s_barrier
	ds_read_b128 v[208:211], v155 offset:49152
	ds_read_b128 v[212:215], v156 offset:49152
	ds_read_b128 v[216:219], v157 offset:49152
	ds_read_b128 v[156:159], v158 offset:49152
	s_waitcnt vmcnt(0)
	s_barrier
	s_waitcnt lgkmcnt(0)
	s_waitcnt lgkmcnt(0)
	v_mfma_f32_32x32x16_bf16 v[80:95], v[172:175], v[208:211], v[80:95]
	v_mfma_f32_32x32x16_bf16 v[64:79], v[176:179], v[208:211], v[64:79]
	v_mfma_f32_32x32x16_bf16 v[80:95], v[180:183], v[212:215], v[80:95]
	v_mfma_f32_32x32x16_bf16 v[64:79], v[184:187], v[212:215], v[64:79]
	v_mfma_f32_32x32x16_bf16 v[80:95], v[192:195], v[216:219], v[80:95]
	v_mfma_f32_32x32x16_bf16 v[64:79], v[196:199], v[216:219], v[64:79]
	v_mfma_f32_32x32x16_bf16 v[80:95], v[200:203], v[156:159], v[80:95]
	v_mfma_f32_32x32x16_bf16 v[64:79], v[204:207], v[156:159], v[64:79]
	s_barrier
	ds_read_b128 v[172:175], v154 offset:49152
	ds_read_b128 v[176:179], v154 offset:53248
	ds_read_b128 v[180:183], v153 offset:49152
	ds_read_b128 v[184:187], v153 offset:53248
	ds_read_b128 v[192:195], v152 offset:49152
	ds_read_b128 v[152:155], v152 offset:53248
	ds_read_b128 v[196:199], v131 offset:49152
	ds_read_b128 v[200:203], v131 offset:53248
	s_barrier
	s_waitcnt lgkmcnt(0)
	s_waitcnt lgkmcnt(0)
	v_mfma_f32_32x32x16_bf16 v[48:63], v[172:175], v[134:137], v[48:63]
	v_mfma_f32_32x32x16_bf16 v[32:47], v[176:179], v[134:137], v[32:47]
	v_mfma_f32_32x32x16_bf16 v[48:63], v[180:183], v[160:163], v[48:63]
	v_mfma_f32_32x32x16_bf16 v[32:47], v[184:187], v[160:163], v[32:47]
	v_mfma_f32_32x32x16_bf16 v[48:63], v[192:195], v[164:167], v[48:63]
	v_mfma_f32_32x32x16_bf16 v[32:47], v[152:155], v[164:167], v[32:47]
	v_mfma_f32_32x32x16_bf16 v[48:63], v[196:199], v[168:171], v[48:63]
	v_mfma_f32_32x32x16_bf16 v[32:47], v[200:203], v[168:171], v[32:47]
	v_mfma_f32_32x32x16_bf16 v[16:31], v[172:175], v[208:211], v[16:31]
	v_mfma_f32_32x32x16_bf16 v[0:15], v[176:179], v[208:211], v[0:15]
	v_mfma_f32_32x32x16_bf16 v[16:31], v[180:183], v[212:215], v[16:31]
	v_mfma_f32_32x32x16_bf16 v[0:15], v[184:187], v[212:215], v[0:15]
	v_mfma_f32_32x32x16_bf16 v[16:31], v[192:195], v[216:219], v[16:31]
	v_mfma_f32_32x32x16_bf16 v[0:15], v[152:155], v[216:219], v[0:15]
	v_mfma_f32_32x32x16_bf16 v[16:31], v[196:199], v[156:159], v[16:31]
	v_mfma_f32_32x32x16_bf16 v[0:15], v[200:203], v[156:159], v[0:15]
	s_barrier
	v_cmp_gt_u32_e32 vcc, s82, v148
	s_and_saveexec_b64 s[72:73], vcc
	s_cbranch_execz .LBB0_2337
	s_barrier

; #define G8_STA(b, h, kt) G8_STAGE(G8_SA(b, h), Ag, lda, h, kt)
; #define G8_STB(b, h, kt) G8_STAGE(G8_SB(b, h), Bg, ldb, h, kt)
; #define G8_LDA(b, h) do { _Pragma("unroll") for (int m_ = 0; m_ < 2; ++m_) _Pragma("unroll") for (int k_ = 0; k_ < 4; ++k_) \
;     At[m_][k_] = *reinterpret_cast<const LAS bf16x8*>(la + ((b) * 2 + (h)) * 16384 + m_ * 4096 + (((k_ * 2 + hi) ^ swz) << 4)); } while (0)
; #define G8_LDB(dst, b, h) do { _Pragma("unroll") for (int k_ = 0; k_ < 4; ++k_) \
;     dst[k_] = *reinterpret_cast<const LAS bf16x8*>(lb + ((b) * 2 + (h)) * 16384 + (((k_ * 2 + hi) ^ swz) << 4)); } while (0)
; #define G8_MMA(ai, bj, Bx) do { __builtin_amdgcn_s_setprio(1); _Pragma("unroll") for (int k_ = 0; k_ < 4; ++k_) _Pragma("unroll") for (int m_ = 0; m_ < 2; ++m_) \
;     acc[ai][bj][m_] = __builtin_amdgcn_mfma_f32_32x32x16_bf16(At[m_][k_], Bx[k_], acc[ai][bj][m_], 0, 0, 0); __builtin_amdgcn_s_setprio(0); } while (0)
; #define G8_WV(n) asm volatile("s_waitcnt vmcnt(" #n ")" ::: "memory")
; #define G8_WL(n) asm volatile("s_waitcnt lgkmcnt(" #n ")" ::: "memory")
; #define G8_BAR __builtin_amdgcn_s_barrier()
; #define G8_SCHED __builtin_amdgcn_sched_barrier(0)
; template <class Epi>
; __device__ __forceinline__ void gemm8p(const bf16_t* __restrict__ A, int lda, const bf16_t* __restrict__ Bt, int ldb, int K,
;                                        LP lds, const Epi& epi, bool pre = false, const bf16_t* An = nullptr, const bf16_t* Bn = nullptr) {
;     ...
;   for (int t = 0; t < nt - 2; t += 2) {
;     G8_LDB(B0, 0, 0); G8_SCHED; G8_LDA(0, 0); G8_STA(1, 1, t + 1);
;     G8_WL(8); G8_BAR; G8_WL(0); G8_MMA(0, 0, B0); G8_BAR; G8_SCHED;
;     G8_LDB(B1, 0, 1); G8_STB(0, 0, t + 2);
;     G8_BAR; G8_WL(0); G8_MMA(0, 1, B1); G8_BAR; G8_SCHED;
;     G8_LDA(0, 1); G8_STA(0, 0, t + 2);
;     G8_BAR; G8_WL(0); G8_MMA(1, 0, B0); G8_BAR; G8_SCHED;
;     G8_STB(0, 1, t + 2);
;     G8_WV(6); G8_BAR; G8_MMA(1, 1, B1); G8_BAR; G8_SCHED;
.LBB0_2401:
	ds_read_b128 v[168:171], v155
	ds_read_b128 v[172:175], v156
	ds_read_b128 v[176:179], v157
	ds_read_b128 v[180:183], v158
	v_lshl_add_u64 v[188:189], v[138:139], 0, v[128:129]
	v_readfirstlane_b32 s63, v166
	v_lshl_add_u64 v[220:221], v[188:189], 0, s[18:19]
	s_mov_b32 m0, s63
	v_readfirstlane_b32 s63, v165
	ds_read_b128 v[184:187], v154
	ds_read_b128 v[192:195], v154 offset:4096
	ds_read_b128 v[196:199], v153
	ds_read_b128 v[200:203], v153 offset:4096
	ds_read_b128 v[204:207], v152
	ds_read_b128 v[208:211], v152 offset:4096
	ds_read_b128 v[212:215], v131
	ds_read_b128 v[216:219], v131 offset:4096
	global_load_lds_dwordx4 v[220:221], off
	v_lshl_add_u64 v[220:221], v[188:189], 0, s[20:21]
	s_mov_b32 m0, s63
	s_nop 0
	global_load_lds_dwordx4 v[220:221], off
	s_waitcnt lgkmcnt(8)
	s_barrier
	s_waitcnt lgkmcnt(0)
	s_waitcnt lgkmcnt(0)
	v_mfma_f32_32x32x16_bf16 v[112:127], v[184:187], v[168:171], v[112:127]
	v_mfma_f32_32x32x16_bf16 v[96:111], v[192:195], v[168:171], v[96:111]
	v_mfma_f32_32x32x16_bf16 v[112:127], v[196:199], v[172:175], v[112:127]
	v_mfma_f32_32x32x16_bf16 v[96:111], v[200:203], v[172:175], v[96:111]
	v_mfma_f32_32x32x16_bf16 v[112:127], v[204:207], v[176:179], v[112:127]
	v_mfma_f32_32x32x16_bf16 v[96:111], v[208:211], v[176:179], v[96:111]
	v_mfma_f32_32x32x16_bf16 v[112:127], v[212:215], v[180:183], v[112:127]
	v_mfma_f32_32x32x16_bf16 v[96:111], v[216:219], v[180:183], v[96:111]
	s_barrier
	v_lshl_add_u64 v[236:237], v[136:137], 0, v[128:129]
	v_readfirstlane_b32 s63, v147
	v_lshl_add_u64 v[238:239], v[236:237], 0, s[22:23]
	s_mov_b32 m0, s63
	v_readfirstlane_b32 s63, v146
	ds_read_b128 v[220:223], v155 offset:16384
	ds_read_b128 v[224:227], v156 offset:16384
	ds_read_b128 v[228:231], v157 offset:16384
	ds_read_b128 v[232:235], v158 offset:16384
	global_load_lds_dwordx4 v[238:239], off
	v_lshl_add_u64 v[238:239], v[236:237], 0, s[24:25]
	s_mov_b32 m0, s63
	s_nop 0
	global_load_lds_dwordx4 v[238:239], off
	s_barrier
	s_waitcnt lgkmcnt(0)
	s_waitcnt lgkmcnt(0)
	v_mfma_f32_32x32x16_bf16 v[80:95], v[184:187], v[220:223], v[80:95]
	v_mfma_f32_32x32x16_bf16 v[64:79], v[192:195], v[220:223], v[64:79]
	v_mfma_f32_32x32x16_bf16 v[80:95], v[196:199], v[224:227], v[80:95]
	v_mfma_f32_32x32x16_bf16 v[64:79], v[200:203], v[224:227], v[64:79]
	v_mfma_f32_32x32x16_bf16 v[80:95], v[204:207], v[228:231], v[80:95]
	v_mfma_f32_32x32x16_bf16 v[64:79], v[208:211], v[228:231], v[64:79]
	v_mfma_f32_32x32x16_bf16 v[80:95], v[212:215], v[232:235], v[80:95]
	v_mfma_f32_32x32x16_bf16 v[64:79], v[216:219], v[232:235], v[64:79]
	s_barrier
	v_readfirstlane_b32 s63, v142
	v_lshl_add_u64 v[238:239], v[188:189], 0, s[26:27]
	s_mov_b32 m0, s63
	v_readfirstlane_b32 s63, v145
	ds_read_b128 v[184:187], v154 offset:16384
	ds_read_b128 v[192:195], v154 offset:20480
	ds_read_b128 v[196:199], v153 offset:16384
	ds_read_b128 v[200:203], v153 offset:20480
	ds_read_b128 v[204:207], v152 offset:16384
	ds_read_b128 v[208:211], v152 offset:20480
	ds_read_b128 v[212:215], v131 offset:16384
	ds_read_b128 v[216:219], v131 offset:20480
	global_load_lds_dwordx4 v[238:239], off
	v_lshl_add_u64 v[238:239], v[188:189], 0, s[28:29]
	s_mov_b32 m0, s63
	s_nop 0
	global_load_lds_dwordx4 v[238:239], off
	s_barrier
	s_waitcnt lgkmcnt(0)
	s_waitcnt lgkmcnt(0)
	v_mfma_f32_32x32x16_bf16 v[48:63], v[184:187], v[168:171], v[48:63]
	v_mfma_f32_32x32x16_bf16 v[32:47], v[192:195], v[168:171], v[32:47]
	v_mfma_f32_32x32x16_bf16 v[48:63], v[196:199], v[172:175], v[48:63]
	v_mfma_f32_32x32x16_bf16 v[32:47], v[200:203], v[172:175], v[32:47]
	v_mfma_f32_32x32x16_bf16 v[48:63], v[204:207], v[176:179], v[48:63]
	v_mfma_f32_32x32x16_bf16 v[32:47], v[208:211], v[176:179], v[32:47]
	v_mfma_f32_32x32x16_bf16 v[48:63], v[212:215], v[180:183], v[48:63]
	v_mfma_f32_32x32x16_bf16 v[32:47], v[216:219], v[180:183], v[32:47]
	s_barrier
	v_readfirstlane_b32 s63, v144
	v_lshl_add_u64 v[168:169], v[236:237], 0, s[30:31]
	s_mov_b32 m0, s63
	v_readfirstlane_b32 s63, v143
	global_load_lds_dwordx4 v[168:169], off
	v_lshl_add_u64 v[168:169], v[236:237], 0, s[36:37]
	s_mov_b32 m0, s63
	s_nop 0
	global_load_lds_dwordx4 v[168:169], off
	s_waitcnt vmcnt(6)
	s_barrier
	v_mfma_f32_32x32x16_bf16 v[16:31], v[184:187], v[220:223], v[16:31]
	v_mfma_f32_32x32x16_bf16 v[0:15], v[192:195], v[220:223], v[0:15]
	v_mfma_f32_32x32x16_bf16 v[16:31], v[196:199], v[224:227], v[16:31]
	v_mfma_f32_32x32x16_bf16 v[0:15], v[200:203], v[224:227], v[0:15]
	v_mfma_f32_32x32x16_bf16 v[16:31], v[204:207], v[228:231], v[16:31]
	v_mfma_f32_32x32x16_bf16 v[0:15], v[208:211], v[228:231], v[0:15]
	v_mfma_f32_32x32x16_bf16 v[16:31], v[212:215], v[232:235], v[16:31]
	v_mfma_f32_32x32x16_bf16 v[0:15], v[216:219], v[232:235], v[0:15]
	s_barrier
	ds_read_b128 v[168:171], v155 offset:32768
	ds_read_b128 v[172:175], v156 offset:32768
	ds_read_b128 v[176:179], v157 offset:32768
	ds_read_b128 v[180:183], v158 offset:32768
	v_readfirstlane_b32 s63, v141
	v_lshl_add_u64 v[220:221], v[188:189], 0, s[38:39]
	s_mov_b32 m0, s63
	v_readfirstlane_b32 s63, v140
	ds_read_b128 v[184:187], v154 offset:32768
	ds_read_b128 v[192:195], v154 offset:36864
	ds_read_b128 v[196:199], v153 offset:32768
	ds_read_b128 v[200:203], v153 offset:36864
	ds_read_b128 v[204:207], v152 offset:32768
	ds_read_b128 v[208:211], v152 offset:36864
	ds_read_b128 v[212:215], v131 offset:32768
	ds_read_b128 v[216:219], v131 offset:36864
	global_load_lds_dwordx4 v[220:221], off
	v_lshl_add_u64 v[220:221], v[188:189], 0, s[40:41]
	s_mov_b32 m0, s63
	s_nop 0
	global_load_lds_dwordx4 v[220:221], off
	s_waitcnt lgkmcnt(8)
	s_barrier
; #define G8_STA(b, h, kt) G8_STAGE(G8_SA(b, h), Ag, lda, h, kt)
; #define G8_STB(b, h, kt) G8_STAGE(G8_SB(b, h), Bg, ldb, h, kt)
; #define G8_LDA(b, h) do { _Pragma("unroll") for (int m_ = 0; m_ < 2; ++m_) _Pragma("unroll") for (int k_ = 0; k_ < 4; ++k_) \
;     At[m_][k_] = *reinterpret_cast<const LAS bf16x8*>(la + ((b) * 2 + (h)) * 16384 + m_ * 4096 + (((k_ * 2 + hi) ^ swz) << 4)); } while (0)
; #define G8_LDB(dst, b, h) do { _Pragma("unroll") for (int k_ = 0; k_ < 4; ++k_) \
;     dst[k_] = *reinterpret_cast<const LAS bf16x8*>(lb + ((b) * 2 + (h)) * 16384 + (((k_ * 2 + hi) ^ swz) << 4)); } while (0)
; #define G8_MMA(ai, bj, Bx) do { __builtin_amdgcn_s_setprio(1); _Pragma("unroll") for (int k_ = 0; k_ < 4; ++k_) _Pragma("unroll") for (int m_ = 0; m_ < 2; ++m_) \
;     acc[ai][bj][m_] = __builtin_amdgcn_mfma_f32_32x32x16_bf16(At[m_][k_], Bx[k_], acc[ai][bj][m_], 0, 0, 0); __builtin_amdgcn_s_setprio(0); } while (0)
; #define G8_WV(n) asm volatile("s_waitcnt vmcnt(" #n ")" ::: "memory")
; #define G8_WL(n) asm volatile("s_waitcnt lgkmcnt(" #n ")" ::: "memory")
; #define G8_BAR __builtin_amdgcn_s_barrier()
; #define G8_SCHED __builtin_amdgcn_sched_barrier(0)
; template <class Epi>
; __device__ __forceinline__ void gemm8p(const bf16_t* __restrict__ A, int lda, const bf16_t* __restrict__ Bt, int ldb, int K,
;                                        LP lds, const Epi& epi, bool pre = false, const bf16_t* An = nullptr, const bf16_t* Bn = nullptr) {
;     ...
;     G8_LDB(B0, 1, 0); G8_SCHED; G8_LDA(1, 0); G8_STA(0, 1, t + 2);
;     G8_WL(8); G8_BAR; G8_WL(0); G8_MMA(0, 0, B0); G8_BAR; G8_SCHED;
;     G8_LDB(B1, 1, 1); G8_STB(1, 0, t + 3);
;     G8_BAR; G8_WL(0); G8_MMA(0, 1, B1); G8_BAR; G8_SCHED;
;     G8_LDA(1, 1); G8_STA(1, 0, t + 3);
;     G8_BAR; G8_WL(0); G8_MMA(1, 0, B0); G8_BAR; G8_SCHED;
;     G8_STB(1, 1, t + 3);
;     G8_WV(6); G8_BAR; G8_MMA(1, 1, B1); G8_BAR; G8_SCHED;
;   }
;   { G8_LDB(B0, 0, 0); G8_LDA(0, 0); G8_STA(1, 1, nt - 1);
;     G8_BAR; G8_WL(0); G8_MMA(0, 0, B0); G8_BAR; G8_SCHED;
	s_waitcnt lgkmcnt(0)
	s_waitcnt lgkmcnt(0)
	v_mfma_f32_32x32x16_bf16 v[112:127], v[184:187], v[168:171], v[112:127]
	v_mfma_f32_32x32x16_bf16 v[96:111], v[192:195], v[168:171], v[96:111]
	v_mfma_f32_32x32x16_bf16 v[112:127], v[196:199], v[172:175], v[112:127]
	v_mfma_f32_32x32x16_bf16 v[96:111], v[200:203], v[172:175], v[96:111]
	v_mfma_f32_32x32x16_bf16 v[112:127], v[204:207], v[176:179], v[112:127]
	v_mfma_f32_32x32x16_bf16 v[96:111], v[208:211], v[176:179], v[96:111]
	v_mfma_f32_32x32x16_bf16 v[112:127], v[212:215], v[180:183], v[112:127]
	v_mfma_f32_32x32x16_bf16 v[96:111], v[216:219], v[180:183], v[96:111]
	s_barrier
	v_readfirstlane_b32 s63, v159
	v_lshl_add_u64 v[238:239], v[236:237], 0, s[42:43]
	s_mov_b32 m0, s63
	v_readfirstlane_b32 s63, v160
	ds_read_b128 v[220:223], v155 offset:49152
	ds_read_b128 v[224:227], v156 offset:49152
	ds_read_b128 v[228:231], v157 offset:49152
	ds_read_b128 v[232:235], v158 offset:49152
	global_load_lds_dwordx4 v[238:239], off
	v_lshl_add_u64 v[238:239], v[236:237], 0, s[44:45]
	s_mov_b32 m0, s63
	s_nop 0
	global_load_lds_dwordx4 v[238:239], off
	s_barrier
	s_waitcnt lgkmcnt(0)
	s_waitcnt lgkmcnt(0)
	v_mfma_f32_32x32x16_bf16 v[80:95], v[184:187], v[220:223], v[80:95]
	v_mfma_f32_32x32x16_bf16 v[64:79], v[192:195], v[220:223], v[64:79]
	v_mfma_f32_32x32x16_bf16 v[80:95], v[196:199], v[224:227], v[80:95]
	v_mfma_f32_32x32x16_bf16 v[64:79], v[200:203], v[224:227], v[64:79]
	v_mfma_f32_32x32x16_bf16 v[80:95], v[204:207], v[228:231], v[80:95]
	v_mfma_f32_32x32x16_bf16 v[64:79], v[208:211], v[228:231], v[64:79]
	v_mfma_f32_32x32x16_bf16 v[80:95], v[212:215], v[232:235], v[80:95]
	v_mfma_f32_32x32x16_bf16 v[64:79], v[216:219], v[232:235], v[64:79]
	s_barrier
	v_readfirstlane_b32 s63, v161
	v_lshl_add_u64 v[238:239], v[188:189], 0, s[46:47]
	s_mov_b32 m0, s63
	v_readfirstlane_b32 s63, v162
	ds_read_b128 v[184:187], v154 offset:49152
	ds_read_b128 v[192:195], v154 offset:53248
	ds_read_b128 v[196:199], v153 offset:49152
	ds_read_b128 v[200:203], v153 offset:53248
	ds_read_b128 v[204:207], v152 offset:49152
	ds_read_b128 v[208:211], v152 offset:53248
	ds_read_b128 v[212:215], v131 offset:49152
	ds_read_b128 v[216:219], v131 offset:53248
	global_load_lds_dwordx4 v[238:239], off
	v_lshl_add_u64 v[188:189], v[188:189], 0, s[48:49]
	s_mov_b32 m0, s63
	s_nop 0
	global_load_lds_dwordx4 v[188:189], off
	s_barrier
	s_waitcnt lgkmcnt(0)
	s_waitcnt lgkmcnt(0)
	v_mfma_f32_32x32x16_bf16 v[48:63], v[184:187], v[168:171], v[48:63]
	v_mfma_f32_32x32x16_bf16 v[32:47], v[192:195], v[168:171], v[32:47]
	v_mfma_f32_32x32x16_bf16 v[48:63], v[196:199], v[172:175], v[48:63]
	v_mfma_f32_32x32x16_bf16 v[32:47], v[200:203], v[172:175], v[32:47]
	v_mfma_f32_32x32x16_bf16 v[48:63], v[204:207], v[176:179], v[48:63]
	v_mfma_f32_32x32x16_bf16 v[32:47], v[208:211], v[176:179], v[32:47]
	v_mfma_f32_32x32x16_bf16 v[48:63], v[212:215], v[180:183], v[48:63]
	v_mfma_f32_32x32x16_bf16 v[32:47], v[216:219], v[180:183], v[32:47]
	s_barrier
	v_readfirstlane_b32 s63, v163
	v_lshl_add_u64 v[168:169], v[236:237], 0, s[50:51]
	s_mov_b32 m0, s63
	v_readfirstlane_b32 s63, v164
	global_load_lds_dwordx4 v[168:169], off
	v_lshl_add_u64 v[168:169], v[236:237], 0, s[52:53]
	s_mov_b32 m0, s63
	s_nop 0
	global_load_lds_dwordx4 v[168:169], off
	s_waitcnt vmcnt(6)
	s_barrier
	v_mfma_f32_32x32x16_bf16 v[16:31], v[184:187], v[220:223], v[16:31]
	v_mfma_f32_32x32x16_bf16 v[0:15], v[192:195], v[220:223], v[0:15]
	v_mfma_f32_32x32x16_bf16 v[16:31], v[196:199], v[224:227], v[16:31]
	v_mfma_f32_32x32x16_bf16 v[0:15], v[200:203], v[224:227], v[0:15]
	v_mfma_f32_32x32x16_bf16 v[16:31], v[204:207], v[228:231], v[16:31]
	v_mfma_f32_32x32x16_bf16 v[0:15], v[208:211], v[228:231], v[0:15]
	v_mfma_f32_32x32x16_bf16 v[16:31], v[212:215], v[232:235], v[16:31]
	v_mfma_f32_32x32x16_bf16 v[0:15], v[216:219], v[232:235], v[0:15]
	s_barrier
	s_add_i32 s33, s33, 2
	v_lshl_add_u64 v[136:137], v[136:137], 0, s[54:55]
	s_cmp_lt_u32 s33, 60
	v_lshl_add_u64 v[138:139], v[138:139], 0, s[54:55]
	s_cbranch_scc1 .LBB0_2401
	v_readfirstlane_b32 s33, v166
	v_lshl_add_u64 v[188:189], v[134:135], 0, s[56:57]
	s_mov_b32 m0, s33
	v_readfirstlane_b32 s33, v165
	ds_read_b128 v[136:139], v155
	ds_read_b128 v[160:163], v156
	ds_read_b128 v[168:171], v157
	ds_read_b128 v[172:175], v158
	ds_read_b128 v[176:179], v154
	ds_read_b128 v[180:183], v154 offset:4096
	ds_read_b128 v[184:187], v153
	ds_read_b128 v[192:195], v153 offset:4096
	ds_read_b128 v[196:199], v152
	ds_read_b128 v[200:203], v152 offset:4096
	ds_read_b128 v[204:207], v131
	ds_read_b128 v[208:211], v131 offset:4096
	global_load_lds_dwordx4 v[188:189], off
	v_lshl_add_u64 v[134:135], v[134:135], 0, s[58:59]
	s_mov_b32 m0, s33
	s_nop 0
	global_load_lds_dwordx4 v[134:135], off
	s_barrier
	s_waitcnt lgkmcnt(0)
	s_waitcnt lgkmcnt(0)
	v_mfma_f32_32x32x16_bf16 v[112:127], v[176:179], v[136:139], v[112:127]
	v_mfma_f32_32x32x16_bf16 v[96:111], v[180:183], v[136:139], v[96:111]
	v_mfma_f32_32x32x16_bf16 v[112:127], v[184:187], v[160:163], v[112:127]
	v_mfma_f32_32x32x16_bf16 v[96:111], v[192:195], v[160:163], v[96:111]
	v_mfma_f32_32x32x16_bf16 v[112:127], v[196:199], v[168:171], v[112:127]
	v_mfma_f32_32x32x16_bf16 v[96:111], v[200:203], v[168:171], v[96:111]
	v_mfma_f32_32x32x16_bf16 v[112:127], v[204:207], v[172:175], v[112:127]
	v_mfma_f32_32x32x16_bf16 v[96:111], v[208:211], v[172:175], v[96:111]
	s_barrier
	ds_read_b128 v[164:167], v155 offset:16384
	ds_read_b128 v[212:215], v156 offset:16384
	ds_read_b128 v[216:219], v157 offset:16384
	ds_read_b128 v[220:223], v158 offset:16384
	s_barrier
; #define G8_LDA(b, h) do { _Pragma("unroll") for (int m_ = 0; m_ < 2; ++m_) _Pragma("unroll") for (int k_ = 0; k_ < 4; ++k_) \
;     At[m_][k_] = *reinterpret_cast<const LAS bf16x8*>(la + ((b) * 2 + (h)) * 16384 + m_ * 4096 + (((k_ * 2 + hi) ^ swz) << 4)); } while (0)
; #define G8_LDB(dst, b, h) do { _Pragma("unroll") for (int k_ = 0; k_ < 4; ++k_) \
;     dst[k_] = *reinterpret_cast<const LAS bf16x8*>(lb + ((b) * 2 + (h)) * 16384 + (((k_ * 2 + hi) ^ swz) << 4)); } while (0)
; #define G8_MMA(ai, bj, Bx) do { __builtin_amdgcn_s_setprio(1); _Pragma("unroll") for (int k_ = 0; k_ < 4; ++k_) _Pragma("unroll") for (int m_ = 0; m_ < 2; ++m_) \
;     acc[ai][bj][m_] = __builtin_amdgcn_mfma_f32_32x32x16_bf16(At[m_][k_], Bx[k_], acc[ai][bj][m_], 0, 0, 0); __builtin_amdgcn_s_setprio(0); } while (0)
; #define G8_WV(n) asm volatile("s_waitcnt vmcnt(" #n ")" ::: "memory")
; #define G8_WL(n) asm volatile("s_waitcnt lgkmcnt(" #n ")" ::: "memory")
; #define G8_BAR __builtin_amdgcn_s_barrier()
; #define G8_SCHED __builtin_amdgcn_sched_barrier(0)
; template <class Epi>
; __device__ __forceinline__ void gemm8p(const bf16_t* __restrict__ A, int lda, const bf16_t* __restrict__ Bt, int ldb, int K,
;                                        LP lds, const Epi& epi, bool pre = false, const bf16_t* An = nullptr, const bf16_t* Bn = nullptr) {
;     ...
;     G8_BAR; G8_WL(0); G8_MMA(0, 0, B0); G8_BAR; G8_SCHED;
;     G8_LDB(B1, 0, 1); G8_BAR; G8_WL(0); G8_MMA(0, 1, B1); G8_BAR; G8_SCHED;
;     G8_LDA(0, 1); G8_WV(4); G8_BAR; G8_WL(0); G8_MMA(1, 0, B0); G8_MMA(1, 1, B1); G8_BAR; G8_SCHED; }
;   { G8_LDB(B0, 1, 0); G8_LDA(1, 0); G8_WV(2); G8_BAR; G8_WL(0); G8_MMA(0, 0, B0); G8_BAR; G8_SCHED;
;     G8_LDB(B1, 1, 1); G8_WV(0); G8_BAR; G8_WL(0); G8_MMA(0, 1, B1); G8_BAR; G8_SCHED;
;     G8_LDA(1, 1); G8_BAR; G8_WL(0); G8_MMA(1, 0, B0); G8_MMA(1, 1, B1); G8_BAR; G8_SCHED; }
;   if (wr == 0) G8_BAR;
;   G8_SCHED;
;   if (An != nullptr) {
	s_waitcnt lgkmcnt(0)
	s_waitcnt lgkmcnt(0)
	v_mfma_f32_32x32x16_bf16 v[80:95], v[176:179], v[164:167], v[80:95]
	v_mfma_f32_32x32x16_bf16 v[64:79], v[180:183], v[164:167], v[64:79]
	v_mfma_f32_32x32x16_bf16 v[80:95], v[184:187], v[212:215], v[80:95]
	v_mfma_f32_32x32x16_bf16 v[64:79], v[192:195], v[212:215], v[64:79]
	v_mfma_f32_32x32x16_bf16 v[80:95], v[196:199], v[216:219], v[80:95]
	v_mfma_f32_32x32x16_bf16 v[64:79], v[200:203], v[216:219], v[64:79]
	v_mfma_f32_32x32x16_bf16 v[80:95], v[204:207], v[220:223], v[80:95]
	v_mfma_f32_32x32x16_bf16 v[64:79], v[208:211], v[220:223], v[64:79]
	s_barrier
	ds_read_b128 v[176:179], v154 offset:16384
	ds_read_b128 v[180:183], v154 offset:20480
	ds_read_b128 v[184:187], v153 offset:16384
	ds_read_b128 v[192:195], v153 offset:20480
	ds_read_b128 v[196:199], v152 offset:16384
	ds_read_b128 v[200:203], v152 offset:20480
	ds_read_b128 v[204:207], v131 offset:16384
	ds_read_b128 v[208:211], v131 offset:20480
	s_waitcnt vmcnt(4)
	s_barrier
	s_waitcnt lgkmcnt(0)
	s_waitcnt lgkmcnt(0)
	v_mfma_f32_32x32x16_bf16 v[48:63], v[176:179], v[136:139], v[48:63]
	v_mfma_f32_32x32x16_bf16 v[32:47], v[180:183], v[136:139], v[32:47]
	v_mfma_f32_32x32x16_bf16 v[48:63], v[184:187], v[160:163], v[48:63]
	v_mfma_f32_32x32x16_bf16 v[32:47], v[192:195], v[160:163], v[32:47]
	v_mfma_f32_32x32x16_bf16 v[48:63], v[196:199], v[168:171], v[48:63]
	v_mfma_f32_32x32x16_bf16 v[32:47], v[200:203], v[168:171], v[32:47]
	v_mfma_f32_32x32x16_bf16 v[48:63], v[204:207], v[172:175], v[48:63]
	v_mfma_f32_32x32x16_bf16 v[32:47], v[208:211], v[172:175], v[32:47]
	v_mfma_f32_32x32x16_bf16 v[16:31], v[176:179], v[164:167], v[16:31]
	v_mfma_f32_32x32x16_bf16 v[0:15], v[180:183], v[164:167], v[0:15]
	v_mfma_f32_32x32x16_bf16 v[16:31], v[184:187], v[212:215], v[16:31]
	v_mfma_f32_32x32x16_bf16 v[0:15], v[192:195], v[212:215], v[0:15]
	v_mfma_f32_32x32x16_bf16 v[16:31], v[196:199], v[216:219], v[16:31]
	v_mfma_f32_32x32x16_bf16 v[0:15], v[200:203], v[216:219], v[0:15]
	v_mfma_f32_32x32x16_bf16 v[16:31], v[204:207], v[220:223], v[16:31]
	v_mfma_f32_32x32x16_bf16 v[0:15], v[208:211], v[220:223], v[0:15]
	s_barrier
	ds_read_b128 v[134:137], v155 offset:32768
	ds_read_b128 v[160:163], v156 offset:32768
	ds_read_b128 v[164:167], v157 offset:32768
	ds_read_b128 v[168:171], v158 offset:32768
	ds_read_b128 v[172:175], v154 offset:32768
	ds_read_b128 v[176:179], v154 offset:36864
	ds_read_b128 v[180:183], v153 offset:32768
	ds_read_b128 v[184:187], v153 offset:36864
	ds_read_b128 v[192:195], v152 offset:32768
	ds_read_b128 v[196:199], v152 offset:36864
	ds_read_b128 v[200:203], v131 offset:32768
	ds_read_b128 v[204:207], v131 offset:36864
	s_waitcnt vmcnt(2)
	s_barrier
	s_waitcnt lgkmcnt(0)
	s_waitcnt lgkmcnt(0)
	v_mfma_f32_32x32x16_bf16 v[112:127], v[172:175], v[134:137], v[112:127]
	v_mfma_f32_32x32x16_bf16 v[96:111], v[176:179], v[134:137], v[96:111]
	v_mfma_f32_32x32x16_bf16 v[112:127], v[180:183], v[160:163], v[112:127]
	v_mfma_f32_32x32x16_bf16 v[96:111], v[184:187], v[160:163], v[96:111]
	v_mfma_f32_32x32x16_bf16 v[112:127], v[192:195], v[164:167], v[112:127]
	v_mfma_f32_32x32x16_bf16 v[96:111], v[196:199], v[164:167], v[96:111]
	v_mfma_f32_32x32x16_bf16 v[112:127], v[200:203], v[168:171], v[112:127]
	v_mfma_f32_32x32x16_bf16 v[96:111], v[204:207], v[168:171], v[96:111]
	s_barrier
	ds_read_b128 v[208:211], v155 offset:49152
	ds_read_b128 v[212:215], v156 offset:49152
	ds_read_b128 v[216:219], v157 offset:49152
	ds_read_b128 v[156:159], v158 offset:49152
	s_waitcnt vmcnt(0)
	s_barrier
	s_waitcnt lgkmcnt(0)
	s_waitcnt lgkmcnt(0)
	v_mfma_f32_32x32x16_bf16 v[80:95], v[172:175], v[208:211], v[80:95]
	v_mfma_f32_32x32x16_bf16 v[64:79], v[176:179], v[208:211], v[64:79]
	v_mfma_f32_32x32x16_bf16 v[80:95], v[180:183], v[212:215], v[80:95]
	v_mfma_f32_32x32x16_bf16 v[64:79], v[184:187], v[212:215], v[64:79]
	v_mfma_f32_32x32x16_bf16 v[80:95], v[192:195], v[216:219], v[80:95]
	v_mfma_f32_32x32x16_bf16 v[64:79], v[196:199], v[216:219], v[64:79]
	v_mfma_f32_32x32x16_bf16 v[80:95], v[200:203], v[156:159], v[80:95]
	v_mfma_f32_32x32x16_bf16 v[64:79], v[204:207], v[156:159], v[64:79]
	s_barrier
	ds_read_b128 v[172:175], v154 offset:49152
	ds_read_b128 v[176:179], v154 offset:53248
	ds_read_b128 v[180:183], v153 offset:49152
	ds_read_b128 v[184:187], v153 offset:53248
	ds_read_b128 v[192:195], v152 offset:49152
	ds_read_b128 v[152:155], v152 offset:53248
	ds_read_b128 v[196:199], v131 offset:49152
	ds_read_b128 v[200:203], v131 offset:53248
	s_barrier
	s_waitcnt lgkmcnt(0)
	s_waitcnt lgkmcnt(0)
	v_mfma_f32_32x32x16_bf16 v[48:63], v[172:175], v[134:137], v[48:63]
	v_mfma_f32_32x32x16_bf16 v[32:47], v[176:179], v[134:137], v[32:47]
	v_mfma_f32_32x32x16_bf16 v[48:63], v[180:183], v[160:163], v[48:63]
	v_mfma_f32_32x32x16_bf16 v[32:47], v[184:187], v[160:163], v[32:47]
	v_mfma_f32_32x32x16_bf16 v[48:63], v[192:195], v[164:167], v[48:63]
	v_mfma_f32_32x32x16_bf16 v[32:47], v[152:155], v[164:167], v[32:47]
	v_mfma_f32_32x32x16_bf16 v[48:63], v[196:199], v[168:171], v[48:63]
	v_mfma_f32_32x32x16_bf16 v[32:47], v[200:203], v[168:171], v[32:47]
	v_mfma_f32_32x32x16_bf16 v[16:31], v[172:175], v[208:211], v[16:31]
	v_mfma_f32_32x32x16_bf16 v[0:15], v[176:179], v[208:211], v[0:15]
	v_mfma_f32_32x32x16_bf16 v[16:31], v[180:183], v[212:215], v[16:31]
	v_mfma_f32_32x32x16_bf16 v[0:15], v[184:187], v[212:215], v[0:15]
	v_mfma_f32_32x32x16_bf16 v[16:31], v[192:195], v[216:219], v[16:31]
	v_mfma_f32_32x32x16_bf16 v[0:15], v[152:155], v[216:219], v[0:15]
	v_mfma_f32_32x32x16_bf16 v[16:31], v[196:199], v[156:159], v[16:31]
	v_mfma_f32_32x32x16_bf16 v[0:15], v[200:203], v[156:159], v[0:15]
	s_barrier
	v_cmp_gt_u32_e32 vcc, s35, v148
	s_and_saveexec_b64 s[70:71], vcc
	s_cbranch_execz .LBB0_2404
	s_barrier
